# GEMM K loops: loading half-workgroup runs at raised priority, MFMA half at priority 0 (inverted s_setprio)
# baseline (speedup 1.0000x reference)
; #define G_STAGE_A(bufoff, p0, p1, koff) do { \
;         __builtin_amdgcn_global_load_lds((const unsigned*)(gbase + (size_t)(unsigned)((p0) + (koff) + voffA[0])), (LAS unsigned*)(lds + (bufoff) + ldsw), 16, 0, 0); \
;         __builtin_amdgcn_global_load_lds((const unsigned*)(gbase + (size_t)(unsigned)((p1) + (koff) + voffA[1])), (LAS unsigned*)(lds + (bufoff) + ldsw + 8192), 16, 0, 0); } while (0)
; #define G_STAGE_B(bufoff, p, koff) do { \
;         __builtin_amdgcn_global_load_lds((const unsigned*)(gbase + (size_t)(unsigned)((p) + (koff) + voffB[0])), (LAS unsigned*)(lds + (bufoff) + ldsw), 16, 0, 0); \
;         __builtin_amdgcn_global_load_lds((const unsigned*)(gbase + (size_t)(unsigned)((p) + (koff) + voffB[1])), (LAS unsigned*)(lds + (bufoff) + ldsw + 8192), 16, 0, 0); } while (0)
; #define G_WAIT_V(n) asm volatile("s_waitcnt vmcnt(" #n ")" ::: "memory")
; template <class Epi>
; DI void gemm_phase(LAS unsigned char* lds, const Sched& S, const Epi& E, const int K) {
;     ...
;             const bool last = (t == nt - 2);
;             const unsigned k1 = (unsigned)(t + 1) * kstepA;
;             const unsigned k2 = last ? 0u : (unsigned)(t + 2) * kstepA, k3 = k2 + kstepA;
;             const unsigned kb2 = last ? 0u : (unsigned)(t + 2) * kstepB, kb3 = kb2 + kstepB;
;             const unsigned x0 = last ? n0 : cur.a0, x1 = last ? n1 : cur.a1, x2 = last ? n2 : cur.a2, x3 = last ? n3 : cur.a3;
;             const unsigned xb = last ? nB : cur.b;
;     ...
;             G_LDB(B0, 0, 0); G_LDB(B1, 0, 1); G_SCHED; G_LDA(At, 0, 0); G_STAGE_A(G_SA(1, 1), cur.a2, cur.a3, k1);
;             G_WAIT_V(8); G_WAIT_L(0); G_BAR; G_MMA(0, 0, At, B0); G_MMA(0, 1, At, B1); G_BAR; G_SCHED;
;             G_LDA(At, 0, 1); G_STAGE_B(G_SB(0, 0), xb, kb2); G_STAGE_B(G_SB(0, 1), xb + hstepB, kb2); G_STAGE_A(G_SA(0, 0), x0, x1, k2);
;             G_WAIT_V(8); G_WAIT_L(0); G_BAR; G_MMA(1, 0, At, B0); G_MMA(1, 1, At, B1); G_BAR; G_SCHED;
;             G_LDB(B0, 1, 0); G_LDB(B1, 1, 1); G_SCHED; G_LDA(At, 1, 0); G_STAGE_A(G_SA(0, 1), x2, x3, k2);
;             G_WAIT_V(8); G_WAIT_L(0); G_BAR; G_MMA(0, 0, At, B0); G_MMA(0, 1, At, B1); G_BAR; G_SCHED;
;             G_LDA(At, 1, 1); G_STAGE_B(G_SB(1, 0), xb, kb3); G_STAGE_B(G_SB(1, 1), xb + hstepB, kb3); G_STAGE_A(G_SA(1, 0), x0, x1, k3);
;             G_WAIT_V(8); G_WAIT_L(0); G_BAR; G_MMA(1, 0, At, B0); G_MMA(1, 1, At, B1); G_BAR; G_SCHED;
.LBB0_110:
	s_add_i32 s91, s90, 0x100
	s_cmp_eq_u32 s44, 28
	s_cselect_b32 s40, 0, s91
	s_cselect_b32 s46, s54, s41
	s_cselect_b32 s47, s56, s61
	s_cselect_b32 s88, s55, s27
	s_cselect_b32 s62, s45, s58
	s_cselect_b32 vcc_hi, s57, s60
	s_add_i32 s63, 0, 0x10000
	s_add_i32 s0, 0, 0x14000
	v_add_u32_e32 v142, s63, v207
	v_add_u32_e32 v158, s0, v207
	ds_read_b128 v[130:133], v142
	ds_read_b128 v[134:137], v142 offset:1024
	ds_read_b128 v[138:141], v142 offset:2048
	ds_read_b128 v[142:145], v142 offset:3072
	ds_read_b128 v[146:149], v158
	ds_read_b128 v[150:153], v158 offset:1024
	ds_read_b128 v[154:157], v158 offset:2048
	ds_read_b128 v[162:165], v158 offset:3072
	s_or_b32 vcc_lo, s40, 0x80
	v_add_u32_e32 v158, s90, v129
	s_add_i32 m0, s78, 0xc000
	ds_read_b128 v[166:169], v214
	ds_read_b128 v[170:173], v214 offset:1024
	ds_read_b128 v[174:177], v214 offset:2048
	ds_read_b128 v[178:181], v214 offset:3072
	ds_read_b128 v[194:197], v214 offset:4096
	ds_read_b128 v[198:201], v214 offset:5120
	ds_read_b128 v[216:219], v214 offset:6144
	ds_read_b128 v[220:223], v214 offset:7168
	global_load_lds_dwordx4 v158, s[82:83]
	v_add_u32_e32 v158, s90, v128
	s_add_i32 m0, s78, 0xe000
	s_nop 0
	global_load_lds_dwordx4 v158, s[82:83]
	s_waitcnt vmcnt(8)
	s_waitcnt lgkmcnt(0)
	s_barrier
	s_setprio 0
	s_waitcnt lgkmcnt(0)
	v_mfma_f32_16x16x32_bf16 v[124:127], v[130:133], v[166:169], v[124:127]
	v_mfma_f32_16x16x32_bf16 v[120:123], v[138:141], v[166:169], v[120:123]
	v_mfma_f32_16x16x32_bf16 v[116:119], v[130:133], v[174:177], v[116:119]
	v_mfma_f32_16x16x32_bf16 v[112:115], v[138:141], v[174:177], v[112:115]
	v_mfma_f32_16x16x32_bf16 v[108:111], v[130:133], v[194:197], v[108:111]
	v_mfma_f32_16x16x32_bf16 v[104:107], v[138:141], v[194:197], v[104:107]
	v_mfma_f32_16x16x32_bf16 v[100:103], v[130:133], v[216:219], v[100:103]
	v_mfma_f32_16x16x32_bf16 v[96:99], v[138:141], v[216:219], v[96:99]
	v_mfma_f32_16x16x32_bf16 v[124:127], v[134:137], v[170:173], v[124:127]
	v_mfma_f32_16x16x32_bf16 v[120:123], v[142:145], v[170:173], v[120:123]
	v_mfma_f32_16x16x32_bf16 v[116:119], v[134:137], v[178:181], v[116:119]
	v_mfma_f32_16x16x32_bf16 v[112:115], v[142:145], v[178:181], v[112:115]
	v_mfma_f32_16x16x32_bf16 v[108:111], v[134:137], v[198:201], v[108:111]
	v_mfma_f32_16x16x32_bf16 v[104:107], v[142:145], v[198:201], v[104:107]
	v_mfma_f32_16x16x32_bf16 v[100:103], v[134:137], v[220:223], v[100:103]
	v_mfma_f32_16x16x32_bf16 v[96:99], v[142:145], v[220:223], v[96:99]
	v_mfma_f32_16x16x32_bf16 v[92:95], v[146:149], v[166:169], v[92:95]
	v_mfma_f32_16x16x32_bf16 v[88:91], v[154:157], v[166:169], v[88:91]
	v_mfma_f32_16x16x32_bf16 v[84:87], v[146:149], v[174:177], v[84:87]
	v_mfma_f32_16x16x32_bf16 v[80:83], v[154:157], v[174:177], v[80:83]
	v_mfma_f32_16x16x32_bf16 v[76:79], v[146:149], v[194:197], v[76:79]
	v_mfma_f32_16x16x32_bf16 v[72:75], v[154:157], v[194:197], v[72:75]
	v_mfma_f32_16x16x32_bf16 v[68:71], v[146:149], v[216:219], v[68:71]
	v_mfma_f32_16x16x32_bf16 v[64:67], v[154:157], v[216:219], v[64:67]
	v_mfma_f32_16x16x32_bf16 v[92:95], v[150:153], v[170:173], v[92:95]
	v_mfma_f32_16x16x32_bf16 v[88:91], v[162:165], v[170:173], v[88:91]
	v_mfma_f32_16x16x32_bf16 v[84:87], v[150:153], v[178:181], v[84:87]
	v_mfma_f32_16x16x32_bf16 v[80:83], v[162:165], v[178:181], v[80:83]
	v_mfma_f32_16x16x32_bf16 v[76:79], v[150:153], v[198:201], v[76:79]
	v_mfma_f32_16x16x32_bf16 v[72:75], v[162:165], v[198:201], v[72:75]
	v_mfma_f32_16x16x32_bf16 v[68:71], v[150:153], v[220:223], v[68:71]
	v_mfma_f32_16x16x32_bf16 v[64:67], v[162:165], v[220:223], v[64:67]
	s_setprio 1
	s_barrier
	s_add_i32 s90, s40, vcc_hi
	s_add_i32 s63, s63, s50
	v_add_u32_e32 v158, s90, v204
	s_mov_b32 m0, s63
	ds_read_b128 v[166:169], v214 offset:16384
	ds_read_b128 v[170:173], v214 offset:17408
	ds_read_b128 v[174:177], v214 offset:18432
	ds_read_b128 v[178:181], v214 offset:19456
	ds_read_b128 v[194:197], v214 offset:20480
	ds_read_b128 v[198:201], v214 offset:21504
	ds_read_b128 v[216:219], v214 offset:22528
	ds_read_b128 v[220:223], v214 offset:23552
	global_load_lds_dwordx4 v158, s[82:83]
	s_add_i32 m0, s63, 0x2000
	s_add_i32 s63, vcc_hi, 0x80000
	v_add_u32_e32 v158, s90, v206
	s_add_i32 s90, s63, s40
	s_add_i32 s0, s0, s50
	global_load_lds_dwordx4 v158, s[82:83]
	v_add_u32_e32 v158, s90, v204
	s_mov_b32 m0, s0
	s_nop 0
	global_load_lds_dwordx4 v158, s[82:83]
	v_add_u32_e32 v158, s90, v206
	s_add_i32 m0, s0, 0x2000
	s_nop 0
	global_load_lds_dwordx4 v158, s[82:83]
	v_add_u32_e32 v158, s62, v161
	v_add_u32_e32 v159, s40, v158
	s_mov_b32 m0, s78
	s_nop 0
	global_load_lds_dwordx4 v159, s[82:83]
	v_add_u32_e32 v159, s46, v205
	v_add_u32_e32 v182, s40, v159
	s_mov_b32 m0, s79
	s_nop 0
	global_load_lds_dwordx4 v182, s[82:83]
	s_waitcnt vmcnt(8)
	s_waitcnt lgkmcnt(0)
	s_barrier
; #define G_STAGE_A(bufoff, p0, p1, koff) do { \
;         __builtin_amdgcn_global_load_lds((const unsigned*)(gbase + (size_t)(unsigned)((p0) + (koff) + voffA[0])), (LAS unsigned*)(lds + (bufoff) + ldsw), 16, 0, 0); \
;         __builtin_amdgcn_global_load_lds((const unsigned*)(gbase + (size_t)(unsigned)((p1) + (koff) + voffA[1])), (LAS unsigned*)(lds + (bufoff) + ldsw + 8192), 16, 0, 0); } while (0)
; #define G_STAGE_B(bufoff, p, koff) do { \
;         __builtin_amdgcn_global_load_lds((const unsigned*)(gbase + (size_t)(unsigned)((p) + (koff) + voffB[0])), (LAS unsigned*)(lds + (bufoff) + ldsw), 16, 0, 0); \
;         __builtin_amdgcn_global_load_lds((const unsigned*)(gbase + (size_t)(unsigned)((p) + (koff) + voffB[1])), (LAS unsigned*)(lds + (bufoff) + ldsw + 8192), 16, 0, 0); } while (0)
; #define G_LDA(dst, b, h) do { _Pragma("unroll") for (int m = 0; m < 4; ++m) _Pragma("unroll") for (int k = 0; k < 2; ++k) dst[m][k] = *(const LAS bf16x8*)(lds + G_SA(b, h) + aoff + m * 2048 + k * 1024); } while (0)
; #define G_LDB(dst, b, h) do { _Pragma("unroll") for (int n = 0; n < 2; ++n) _Pragma("unroll") for (int k = 0; k < 2; ++k) dst[n][k] = *(const LAS bf16x8*)(lds + G_SB(b, h) + boff + n * 2048 + k * 1024); } while (0)
; #define G_WAIT_V(n) asm volatile("s_waitcnt vmcnt(" #n ")" ::: "memory")
; #define G_BAR __builtin_amdgcn_s_barrier()
; template <class Epi>
; DI void gemm_phase(LAS unsigned char* lds, const Sched& S, const Epi& E, const int K) {
;     ...
;             G_LDB(B0, 0, 0); G_LDB(B1, 0, 1); G_SCHED; G_LDA(At, 0, 0); G_STAGE_A(G_SA(1, 1), cur.a2, cur.a3, k1);
;             G_WAIT_V(8); G_WAIT_L(0); G_BAR; G_MMA(0, 0, At, B0); G_MMA(0, 1, At, B1); G_BAR; G_SCHED;
;             G_LDA(At, 0, 1); G_STAGE_B(G_SB(0, 0), xb, kb2); G_STAGE_B(G_SB(0, 1), xb + hstepB, kb2); G_STAGE_A(G_SA(0, 0), x0, x1, k2);
;             G_WAIT_V(8); G_WAIT_L(0); G_BAR; G_MMA(1, 0, At, B0); G_MMA(1, 1, At, B1); G_BAR; G_SCHED;
;             G_LDB(B0, 1, 0); G_LDB(B1, 1, 1); G_SCHED; G_LDA(At, 1, 0); G_STAGE_A(G_SA(0, 1), x2, x3, k2);
;             G_WAIT_V(8); G_WAIT_L(0); G_BAR; G_MMA(0, 0, At, B0); G_MMA(0, 1, At, B1); G_BAR; G_SCHED;
;             G_LDA(At, 1, 1); G_STAGE_B(G_SB(1, 0), xb, kb3); G_STAGE_B(G_SB(1, 1), xb + hstepB, kb3); G_STAGE_A(G_SA(1, 0), x0, x1, k3);
;             G_WAIT_V(8); G_WAIT_L(0); G_BAR; G_MMA(1, 0, At, B0); G_MMA(1, 1, At, B1); G_BAR; G_SCHED;
	s_setprio 0
	s_waitcnt lgkmcnt(0)
	v_mfma_f32_16x16x32_bf16 v[60:63], v[130:133], v[166:169], v[60:63]
	v_mfma_f32_16x16x32_bf16 v[56:59], v[138:141], v[166:169], v[56:59]
	v_mfma_f32_16x16x32_bf16 v[52:55], v[130:133], v[174:177], v[52:55]
	v_mfma_f32_16x16x32_bf16 v[48:51], v[138:141], v[174:177], v[48:51]
	v_mfma_f32_16x16x32_bf16 v[44:47], v[130:133], v[194:197], v[44:47]
	v_mfma_f32_16x16x32_bf16 v[40:43], v[138:141], v[194:197], v[40:43]
	v_mfma_f32_16x16x32_bf16 v[36:39], v[130:133], v[216:219], v[36:39]
	v_mfma_f32_16x16x32_bf16 v[32:35], v[138:141], v[216:219], v[32:35]
	v_mfma_f32_16x16x32_bf16 v[60:63], v[134:137], v[170:173], v[60:63]
	v_mfma_f32_16x16x32_bf16 v[56:59], v[142:145], v[170:173], v[56:59]
	v_mfma_f32_16x16x32_bf16 v[52:55], v[134:137], v[178:181], v[52:55]
	v_mfma_f32_16x16x32_bf16 v[48:51], v[142:145], v[178:181], v[48:51]
	v_mfma_f32_16x16x32_bf16 v[44:47], v[134:137], v[198:201], v[44:47]
	v_mfma_f32_16x16x32_bf16 v[40:43], v[142:145], v[198:201], v[40:43]
	v_mfma_f32_16x16x32_bf16 v[36:39], v[134:137], v[220:223], v[36:39]
	v_mfma_f32_16x16x32_bf16 v[32:35], v[142:145], v[220:223], v[32:35]
	v_mfma_f32_16x16x32_bf16 v[28:31], v[146:149], v[166:169], v[28:31]
	v_mfma_f32_16x16x32_bf16 v[24:27], v[154:157], v[166:169], v[24:27]
	v_mfma_f32_16x16x32_bf16 v[20:23], v[146:149], v[174:177], v[20:23]
	v_mfma_f32_16x16x32_bf16 v[16:19], v[154:157], v[174:177], v[16:19]
	v_mfma_f32_16x16x32_bf16 v[12:15], v[146:149], v[194:197], v[12:15]
	v_mfma_f32_16x16x32_bf16 v[8:11], v[154:157], v[194:197], v[8:11]
	v_mfma_f32_16x16x32_bf16 v[4:7], v[146:149], v[216:219], v[4:7]
	v_mfma_f32_16x16x32_bf16 v[0:3], v[154:157], v[216:219], v[0:3]
	v_mfma_f32_16x16x32_bf16 v[28:31], v[150:153], v[170:173], v[28:31]
	v_mfma_f32_16x16x32_bf16 v[24:27], v[162:165], v[170:173], v[24:27]
	v_mfma_f32_16x16x32_bf16 v[20:23], v[150:153], v[178:181], v[20:23]
	v_mfma_f32_16x16x32_bf16 v[16:19], v[162:165], v[178:181], v[16:19]
	v_mfma_f32_16x16x32_bf16 v[12:15], v[150:153], v[198:201], v[12:15]
	v_mfma_f32_16x16x32_bf16 v[8:11], v[162:165], v[198:201], v[8:11]
	v_mfma_f32_16x16x32_bf16 v[4:7], v[150:153], v[220:223], v[4:7]
	v_mfma_f32_16x16x32_bf16 v[0:3], v[162:165], v[220:223], v[0:3]
	s_setprio 1
	s_barrier
	s_add_i32 s0, 0, 0x18000
	s_add_i32 s46, 0, 0x1c000
	v_add_u32_e32 v142, s0, v207
	v_add_u32_e32 v162, s46, v207
	ds_read_b128 v[130:133], v142
	ds_read_b128 v[134:137], v142 offset:1024
	ds_read_b128 v[138:141], v142 offset:2048
	ds_read_b128 v[142:145], v142 offset:3072
	ds_read_b128 v[146:149], v162
	ds_read_b128 v[150:153], v162 offset:1024
	ds_read_b128 v[154:157], v162 offset:2048
	ds_read_b128 v[162:165], v162 offset:3072
	s_add_i32 s88, s88, s40
	s_mov_b32 m0, s92
	v_add_u32_e32 v182, s88, v161
	s_add_i32 s47, s47, s40
	ds_read_b128 v[166:169], v214 offset:32768
	ds_read_b128 v[170:173], v214 offset:33792
	ds_read_b128 v[174:177], v214 offset:34816
	ds_read_b128 v[178:181], v214 offset:35840
	ds_read_b128 v[194:197], v214 offset:36864
	ds_read_b128 v[198:201], v214 offset:37888
	ds_read_b128 v[216:219], v214 offset:38912
	ds_read_b128 v[220:223], v214 offset:39936
	global_load_lds_dwordx4 v182, s[82:83]
	v_add_u32_e32 v182, s47, v205
	s_mov_b32 m0, s93
	s_nop 0
	global_load_lds_dwordx4 v182, s[82:83]
	s_waitcnt vmcnt(8)
	s_waitcnt lgkmcnt(0)
	s_barrier
	s_setprio 0
	s_waitcnt lgkmcnt(0)
	v_mfma_f32_16x16x32_bf16 v[124:127], v[130:133], v[166:169], v[124:127]
	v_mfma_f32_16x16x32_bf16 v[120:123], v[138:141], v[166:169], v[120:123]
	v_mfma_f32_16x16x32_bf16 v[116:119], v[130:133], v[174:177], v[116:119]
	v_mfma_f32_16x16x32_bf16 v[112:115], v[138:141], v[174:177], v[112:115]
	v_mfma_f32_16x16x32_bf16 v[108:111], v[130:133], v[194:197], v[108:111]
	v_mfma_f32_16x16x32_bf16 v[104:107], v[138:141], v[194:197], v[104:107]
	v_mfma_f32_16x16x32_bf16 v[100:103], v[130:133], v[216:219], v[100:103]
	v_mfma_f32_16x16x32_bf16 v[96:99], v[138:141], v[216:219], v[96:99]
	v_mfma_f32_16x16x32_bf16 v[124:127], v[134:137], v[170:173], v[124:127]
	v_mfma_f32_16x16x32_bf16 v[120:123], v[142:145], v[170:173], v[120:123]
	v_mfma_f32_16x16x32_bf16 v[116:119], v[134:137], v[178:181], v[116:119]
	v_mfma_f32_16x16x32_bf16 v[112:115], v[142:145], v[178:181], v[112:115]
	v_mfma_f32_16x16x32_bf16 v[108:111], v[134:137], v[198:201], v[108:111]
	v_mfma_f32_16x16x32_bf16 v[104:107], v[142:145], v[198:201], v[104:107]
	v_mfma_f32_16x16x32_bf16 v[100:103], v[134:137], v[220:223], v[100:103]
	v_mfma_f32_16x16x32_bf16 v[96:99], v[142:145], v[220:223], v[96:99]
	v_mfma_f32_16x16x32_bf16 v[92:95], v[146:149], v[166:169], v[92:95]
	v_mfma_f32_16x16x32_bf16 v[88:91], v[154:157], v[166:169], v[88:91]
	v_mfma_f32_16x16x32_bf16 v[84:87], v[146:149], v[174:177], v[84:87]
	v_mfma_f32_16x16x32_bf16 v[80:83], v[154:157], v[174:177], v[80:83]
	v_mfma_f32_16x16x32_bf16 v[76:79], v[146:149], v[194:197], v[76:79]
	v_mfma_f32_16x16x32_bf16 v[72:75], v[154:157], v[194:197], v[72:75]
	v_mfma_f32_16x16x32_bf16 v[68:71], v[146:149], v[216:219], v[68:71]
	v_mfma_f32_16x16x32_bf16 v[64:67], v[154:157], v[216:219], v[64:67]
	v_mfma_f32_16x16x32_bf16 v[92:95], v[150:153], v[170:173], v[92:95]
	v_mfma_f32_16x16x32_bf16 v[88:91], v[162:165], v[170:173], v[88:91]
	v_mfma_f32_16x16x32_bf16 v[84:87], v[150:153], v[178:181], v[84:87]
	v_mfma_f32_16x16x32_bf16 v[80:83], v[162:165], v[178:181], v[80:83]
	v_mfma_f32_16x16x32_bf16 v[76:79], v[150:153], v[198:201], v[76:79]
	v_mfma_f32_16x16x32_bf16 v[72:75], v[162:165], v[198:201], v[72:75]
	v_mfma_f32_16x16x32_bf16 v[68:71], v[150:153], v[220:223], v[68:71]
	v_mfma_f32_16x16x32_bf16 v[64:67], v[162:165], v[220:223], v[64:67]
	s_setprio 1
	s_barrier
; #define G_STAGE_A(bufoff, p0, p1, koff) do { \
;         __builtin_amdgcn_global_load_lds((const unsigned*)(gbase + (size_t)(unsigned)((p0) + (koff) + voffA[0])), (LAS unsigned*)(lds + (bufoff) + ldsw), 16, 0, 0); \
;         __builtin_amdgcn_global_load_lds((const unsigned*)(gbase + (size_t)(unsigned)((p1) + (koff) + voffA[1])), (LAS unsigned*)(lds + (bufoff) + ldsw + 8192), 16, 0, 0); } while (0)
; #define G_STAGE_B(bufoff, p, koff) do { \
;         __builtin_amdgcn_global_load_lds((const unsigned*)(gbase + (size_t)(unsigned)((p) + (koff) + voffB[0])), (LAS unsigned*)(lds + (bufoff) + ldsw), 16, 0, 0); \
;         __builtin_amdgcn_global_load_lds((const unsigned*)(gbase + (size_t)(unsigned)((p) + (koff) + voffB[1])), (LAS unsigned*)(lds + (bufoff) + ldsw + 8192), 16, 0, 0); } while (0)
; #define G_LDA(dst, b, h) do { _Pragma("unroll") for (int m = 0; m < 4; ++m) _Pragma("unroll") for (int k = 0; k < 2; ++k) dst[m][k] = *(const LAS bf16x8*)(lds + G_SA(b, h) + aoff + m * 2048 + k * 1024); } while (0)
; #define G_MMA(ai, bj, At, Bt) do { __builtin_amdgcn_s_setprio(1); _Pragma("unroll") for (int m = 0; m < 4; ++m) _Pragma("unroll") for (int n = 0; n < 2; ++n) _Pragma("unroll") for (int k = 0; k < 2; ++k) \
;         acc[ai][bj][m][n] = __builtin_amdgcn_mfma_f32_16x16x32_bf16(Bt[n][k], At[m][k], acc[ai][bj][m][n], 0, 0, 0); __builtin_amdgcn_s_setprio(0); } while (0)
; #define G_WAIT_V(n) asm volatile("s_waitcnt vmcnt(" #n ")" ::: "memory")
; #define G_WAIT_L(n) asm volatile("s_waitcnt lgkmcnt(" #n ")" ::: "memory")
; #define G_BAR __builtin_amdgcn_s_barrier()
; #define G_SCHED __builtin_amdgcn_sched_barrier(0)
; template <class Epi>
; DI void gemm_phase(LAS unsigned char* lds, const Sched& S, const Epi& E, const int K) {
;     ...
;             G_LDA(At, 1, 1); G_STAGE_B(G_SB(1, 0), xb, kb3); G_STAGE_B(G_SB(1, 1), xb + hstepB, kb3); G_STAGE_A(G_SA(1, 0), x0, x1, k3);
;             G_WAIT_V(8); G_WAIT_L(0); G_BAR; G_MMA(1, 0, At, B0); G_MMA(1, 1, At, B1); G_BAR; G_SCHED;
	s_add_i32 s40, vcc_lo, vcc_hi
	s_add_i32 s0, s0, s50
	v_add_u32_e32 v182, s40, v204
	s_mov_b32 m0, s0
	ds_read_b128 v[166:169], v214 offset:49152
	ds_read_b128 v[170:173], v214 offset:50176
	ds_read_b128 v[174:177], v214 offset:51200
	ds_read_b128 v[178:181], v214 offset:52224
	ds_read_b128 v[194:197], v214 offset:53248
	ds_read_b128 v[198:201], v214 offset:54272
	ds_read_b128 v[216:219], v214 offset:55296
	ds_read_b128 v[220:223], v214 offset:56320
	global_load_lds_dwordx4 v182, s[82:83]
	v_add_u32_e32 v182, s40, v206
	s_add_i32 m0, s0, 0x2000
	s_add_i32 s0, vcc_lo, s63
	s_add_i32 s40, s46, s50
	global_load_lds_dwordx4 v182, s[82:83]
	v_add_u32_e32 v182, s0, v204
	s_mov_b32 m0, s40
	v_add_u32_e32 v158, vcc_lo, v158
	global_load_lds_dwordx4 v182, s[82:83]
	v_add_u32_e32 v182, s0, v206
	s_add_i32 m0, s40, 0x2000
	s_nop 0
	global_load_lds_dwordx4 v182, s[82:83]
	s_mov_b32 m0, s39
	s_nop 0
	global_load_lds_dwordx4 v158, s[82:83]
	v_add_u32_e32 v158, vcc_lo, v159
	s_mov_b32 m0, s38
	s_nop 0
	global_load_lds_dwordx4 v158, s[82:83]
	s_waitcnt vmcnt(8)
	s_waitcnt lgkmcnt(0)
	s_barrier
	s_setprio 0
	s_waitcnt lgkmcnt(0)
	v_mfma_f32_16x16x32_bf16 v[60:63], v[130:133], v[166:169], v[60:63]
	v_mfma_f32_16x16x32_bf16 v[56:59], v[138:141], v[166:169], v[56:59]
	v_mfma_f32_16x16x32_bf16 v[52:55], v[130:133], v[174:177], v[52:55]
	v_mfma_f32_16x16x32_bf16 v[48:51], v[138:141], v[174:177], v[48:51]
	v_mfma_f32_16x16x32_bf16 v[44:47], v[130:133], v[194:197], v[44:47]
	v_mfma_f32_16x16x32_bf16 v[40:43], v[138:141], v[194:197], v[40:43]
	v_mfma_f32_16x16x32_bf16 v[36:39], v[130:133], v[216:219], v[36:39]
	v_mfma_f32_16x16x32_bf16 v[32:35], v[138:141], v[216:219], v[32:35]
	v_mfma_f32_16x16x32_bf16 v[60:63], v[134:137], v[170:173], v[60:63]
	v_mfma_f32_16x16x32_bf16 v[56:59], v[142:145], v[170:173], v[56:59]
	v_mfma_f32_16x16x32_bf16 v[52:55], v[134:137], v[178:181], v[52:55]
	v_mfma_f32_16x16x32_bf16 v[48:51], v[142:145], v[178:181], v[48:51]
	v_mfma_f32_16x16x32_bf16 v[44:47], v[134:137], v[198:201], v[44:47]
	v_mfma_f32_16x16x32_bf16 v[40:43], v[142:145], v[198:201], v[40:43]
	v_mfma_f32_16x16x32_bf16 v[36:39], v[134:137], v[220:223], v[36:39]
	v_mfma_f32_16x16x32_bf16 v[32:35], v[142:145], v[220:223], v[32:35]
	v_mfma_f32_16x16x32_bf16 v[28:31], v[146:149], v[166:169], v[28:31]
	v_mfma_f32_16x16x32_bf16 v[24:27], v[154:157], v[166:169], v[24:27]
	v_mfma_f32_16x16x32_bf16 v[20:23], v[146:149], v[174:177], v[20:23]
	v_mfma_f32_16x16x32_bf16 v[16:19], v[154:157], v[174:177], v[16:19]
	v_mfma_f32_16x16x32_bf16 v[12:15], v[146:149], v[194:197], v[12:15]
	v_mfma_f32_16x16x32_bf16 v[8:11], v[154:157], v[194:197], v[8:11]
	v_mfma_f32_16x16x32_bf16 v[4:7], v[146:149], v[216:219], v[4:7]
	v_mfma_f32_16x16x32_bf16 v[0:3], v[154:157], v[216:219], v[0:3]
	v_mfma_f32_16x16x32_bf16 v[28:31], v[150:153], v[170:173], v[28:31]
	v_mfma_f32_16x16x32_bf16 v[24:27], v[162:165], v[170:173], v[24:27]
	v_mfma_f32_16x16x32_bf16 v[20:23], v[150:153], v[178:181], v[20:23]
	v_mfma_f32_16x16x32_bf16 v[16:19], v[162:165], v[178:181], v[16:19]
	v_mfma_f32_16x16x32_bf16 v[12:15], v[150:153], v[198:201], v[12:15]
	v_mfma_f32_16x16x32_bf16 v[8:11], v[162:165], v[198:201], v[8:11]
	v_mfma_f32_16x16x32_bf16 v[4:7], v[150:153], v[220:223], v[4:7]
	v_mfma_f32_16x16x32_bf16 v[0:3], v[162:165], v[220:223], v[0:3]
	s_setprio 1
	s_barrier
	s_add_i32 s44, s44, 2
	s_cmp_gt_u32 s44, 29
	s_mov_b32 s90, s91
	s_cbranch_scc0 .LBB0_110
	v_readlane_b32 s44, v254, 63
	v_readlane_b32 s45, v255, 0
	s_and_b64 vcc, exec, s[44:45]
	s_cbranch_vccz .LBB0_113
	s_barrier

; #define G_STAGE_A(bufoff, p0, p1, koff) do { \
;         __builtin_amdgcn_global_load_lds((const unsigned*)(gbase + (size_t)(unsigned)((p0) + (koff) + voffA[0])), (LAS unsigned*)(lds + (bufoff) + ldsw), 16, 0, 0); \
;         __builtin_amdgcn_global_load_lds((const unsigned*)(gbase + (size_t)(unsigned)((p1) + (koff) + voffA[1])), (LAS unsigned*)(lds + (bufoff) + ldsw + 8192), 16, 0, 0); } while (0)
; #define G_STAGE_B(bufoff, p, koff) do { \
;         __builtin_amdgcn_global_load_lds((const unsigned*)(gbase + (size_t)(unsigned)((p) + (koff) + voffB[0])), (LAS unsigned*)(lds + (bufoff) + ldsw), 16, 0, 0); \
;         __builtin_amdgcn_global_load_lds((const unsigned*)(gbase + (size_t)(unsigned)((p) + (koff) + voffB[1])), (LAS unsigned*)(lds + (bufoff) + ldsw + 8192), 16, 0, 0); } while (0)
; #define G_WAIT_V(n) asm volatile("s_waitcnt vmcnt(" #n ")" ::: "memory")
; template <class Epi>
; DI void gemm_phase(LAS unsigned char* lds, const Sched& S, const Epi& E, const int K) {
;     ...
;             const bool last = (t == nt - 2);
;             const unsigned k1 = (unsigned)(t + 1) * kstepA;
;             const unsigned k2 = last ? 0u : (unsigned)(t + 2) * kstepA, k3 = k2 + kstepA;
;             const unsigned kb2 = last ? 0u : (unsigned)(t + 2) * kstepB, kb3 = kb2 + kstepB;
;             const unsigned x0 = last ? n0 : cur.a0, x1 = last ? n1 : cur.a1, x2 = last ? n2 : cur.a2, x3 = last ? n3 : cur.a3;
;             const unsigned xb = last ? nB : cur.b;
;     ...
;             G_LDB(B0, 0, 0); G_LDB(B1, 0, 1); G_SCHED; G_LDA(At, 0, 0); G_STAGE_A(G_SA(1, 1), cur.a2, cur.a3, k1);
;             G_WAIT_V(8); G_WAIT_L(0); G_BAR; G_MMA(0, 0, At, B0); G_MMA(0, 1, At, B1); G_BAR; G_SCHED;
;             G_LDA(At, 0, 1); G_STAGE_B(G_SB(0, 0), xb, kb2); G_STAGE_B(G_SB(0, 1), xb + hstepB, kb2); G_STAGE_A(G_SA(0, 0), x0, x1, k2);
;             G_WAIT_V(8); G_WAIT_L(0); G_BAR; G_MMA(1, 0, At, B0); G_MMA(1, 1, At, B1); G_BAR; G_SCHED;
;             G_LDB(B0, 1, 0); G_LDB(B1, 1, 1); G_SCHED; G_LDA(At, 1, 0); G_STAGE_A(G_SA(0, 1), x2, x3, k2);
;             G_WAIT_V(8); G_WAIT_L(0); G_BAR; G_MMA(0, 0, At, B0); G_MMA(0, 1, At, B1); G_BAR; G_SCHED;
;             G_LDA(At, 1, 1); G_STAGE_B(G_SB(1, 0), xb, kb3); G_STAGE_B(G_SB(1, 1), xb + hstepB, kb3); G_STAGE_A(G_SA(1, 0), x0, x1, k3);
;             G_WAIT_V(8); G_WAIT_L(0); G_BAR; G_MMA(1, 0, At, B0); G_MMA(1, 1, At, B1); G_BAR; G_SCHED;
.LBB0_196:
	s_add_i32 s72, s71, 2
	s_add_i32 s73, s14, 0x100
	s_cmp_eq_u32 s47, s71
	s_cselect_b32 s40, 0, s73
	s_cselect_b32 s78, s67, s37
	s_cselect_b32 s79, s69, s35
	s_cselect_b32 s80, s68, s36
	s_cselect_b32 s81, s15, s27
	s_cselect_b32 s75, s70, s26
	s_add_i32 s86, 0, 0x10000
	s_add_i32 s87, 0, 0x14000
	v_add_u32_e32 v152, s86, v133
	v_add_u32_e32 v168, s87, v133
	ds_read_b128 v[140:143], v152
	ds_read_b128 v[144:147], v152 offset:1024
	ds_read_b128 v[148:151], v152 offset:2048
	ds_read_b128 v[152:155], v152 offset:3072
	ds_read_b128 v[156:159], v168
	ds_read_b128 v[160:163], v168 offset:1024
	ds_read_b128 v[164:167], v168 offset:2048
	ds_read_b128 v[168:171], v168 offset:3072
	s_or_b32 s71, s40, 0x80
	v_add_u32_e32 v184, s14, v139
	s_add_i32 m0, s25, 0xc000
	ds_read_b128 v[172:175], v137
	ds_read_b128 v[176:179], v137 offset:1024
	ds_read_b128 v[180:183], v137 offset:2048
	ds_read_b128 v[194:197], v137 offset:3072
	ds_read_b128 v[198:201], v137 offset:4096
	ds_read_b128 v[202:205], v137 offset:5120
	ds_read_b128 v[206:209], v137 offset:6144
	ds_read_b128 v[210:213], v137 offset:7168
	global_load_lds_dwordx4 v184, s[82:83]
	v_add_u32_e32 v184, s14, v138
	s_add_i32 m0, s25, 0xe000
	s_nop 0
	global_load_lds_dwordx4 v184, s[82:83]
	s_waitcnt vmcnt(8)
	s_waitcnt lgkmcnt(0)
	s_barrier
	s_setprio 0
	s_waitcnt lgkmcnt(0)
	v_mfma_f32_16x16x32_bf16 v[124:127], v[140:143], v[172:175], v[124:127]
	v_mfma_f32_16x16x32_bf16 v[120:123], v[148:151], v[172:175], v[120:123]
	v_mfma_f32_16x16x32_bf16 v[116:119], v[140:143], v[180:183], v[116:119]
	v_mfma_f32_16x16x32_bf16 v[112:115], v[148:151], v[180:183], v[112:115]
	v_mfma_f32_16x16x32_bf16 v[108:111], v[140:143], v[198:201], v[108:111]
	v_mfma_f32_16x16x32_bf16 v[104:107], v[148:151], v[198:201], v[104:107]
	v_mfma_f32_16x16x32_bf16 v[100:103], v[140:143], v[206:209], v[100:103]
	v_mfma_f32_16x16x32_bf16 v[96:99], v[148:151], v[206:209], v[96:99]
	v_mfma_f32_16x16x32_bf16 v[124:127], v[144:147], v[176:179], v[124:127]
	v_mfma_f32_16x16x32_bf16 v[120:123], v[152:155], v[176:179], v[120:123]
	v_mfma_f32_16x16x32_bf16 v[116:119], v[144:147], v[194:197], v[116:119]
	v_mfma_f32_16x16x32_bf16 v[112:115], v[152:155], v[194:197], v[112:115]
	v_mfma_f32_16x16x32_bf16 v[108:111], v[144:147], v[202:205], v[108:111]
	v_mfma_f32_16x16x32_bf16 v[104:107], v[152:155], v[202:205], v[104:107]
	v_mfma_f32_16x16x32_bf16 v[100:103], v[144:147], v[210:213], v[100:103]
	v_mfma_f32_16x16x32_bf16 v[96:99], v[152:155], v[210:213], v[96:99]
	v_mfma_f32_16x16x32_bf16 v[92:95], v[156:159], v[172:175], v[92:95]
	v_mfma_f32_16x16x32_bf16 v[88:91], v[164:167], v[172:175], v[88:91]
	v_mfma_f32_16x16x32_bf16 v[84:87], v[156:159], v[180:183], v[84:87]
	v_mfma_f32_16x16x32_bf16 v[80:83], v[164:167], v[180:183], v[80:83]
	v_mfma_f32_16x16x32_bf16 v[76:79], v[156:159], v[198:201], v[76:79]
	v_mfma_f32_16x16x32_bf16 v[72:75], v[164:167], v[198:201], v[72:75]
	v_mfma_f32_16x16x32_bf16 v[68:71], v[156:159], v[206:209], v[68:71]
	v_mfma_f32_16x16x32_bf16 v[64:67], v[164:167], v[206:209], v[64:67]
	v_mfma_f32_16x16x32_bf16 v[92:95], v[160:163], v[176:179], v[92:95]
	v_mfma_f32_16x16x32_bf16 v[88:91], v[168:171], v[176:179], v[88:91]
	v_mfma_f32_16x16x32_bf16 v[84:87], v[160:163], v[194:197], v[84:87]
	v_mfma_f32_16x16x32_bf16 v[80:83], v[168:171], v[194:197], v[80:83]
	v_mfma_f32_16x16x32_bf16 v[76:79], v[160:163], v[202:205], v[76:79]
	v_mfma_f32_16x16x32_bf16 v[72:75], v[168:171], v[202:205], v[72:75]
	v_mfma_f32_16x16x32_bf16 v[68:71], v[160:163], v[210:213], v[68:71]
	v_mfma_f32_16x16x32_bf16 v[64:67], v[168:171], v[210:213], v[64:67]
	s_setprio 1
	s_barrier
	s_add_i32 s14, s40, s75
	s_add_i32 s86, s86, s20
	v_add_u32_e32 v184, s14, v128
	s_mov_b32 m0, s86
	ds_read_b128 v[172:175], v137 offset:16384
	ds_read_b128 v[176:179], v137 offset:17408
	ds_read_b128 v[180:183], v137 offset:18432
	ds_read_b128 v[194:197], v137 offset:19456
	ds_read_b128 v[198:201], v137 offset:20480
	ds_read_b128 v[202:205], v137 offset:21504
	ds_read_b128 v[206:209], v137 offset:22528
	ds_read_b128 v[210:213], v137 offset:23552
	global_load_lds_dwordx4 v184, s[82:83]
	v_add_u32_e32 v184, s14, v130
	s_add_i32 s14, s75, s16
	s_add_i32 m0, s86, 0x2000
	s_add_i32 s86, s14, s40
	s_add_i32 s87, s87, s20
	global_load_lds_dwordx4 v184, s[82:83]
	v_add_u32_e32 v184, s86, v128
	s_mov_b32 m0, s87
	s_nop 0
	global_load_lds_dwordx4 v184, s[82:83]
	v_add_u32_e32 v184, s86, v130
	s_add_i32 m0, s87, 0x2000
	s_nop 0
	global_load_lds_dwordx4 v184, s[82:83]
	v_add_u32_e32 v184, s81, v132
	v_add_u32_e32 v214, s40, v184
	s_mov_b32 m0, s25
	s_nop 0
	global_load_lds_dwordx4 v214, s[82:83]
	v_add_u32_e32 v214, s78, v129
	v_add_u32_e32 v215, s40, v214
	s_mov_b32 m0, s38
	s_nop 0
	global_load_lds_dwordx4 v215, s[82:83]
	s_waitcnt vmcnt(8)
	s_waitcnt lgkmcnt(0)
	s_barrier
; #define G_STAGE_A(bufoff, p0, p1, koff) do { \
;         __builtin_amdgcn_global_load_lds((const unsigned*)(gbase + (size_t)(unsigned)((p0) + (koff) + voffA[0])), (LAS unsigned*)(lds + (bufoff) + ldsw), 16, 0, 0); \
;         __builtin_amdgcn_global_load_lds((const unsigned*)(gbase + (size_t)(unsigned)((p1) + (koff) + voffA[1])), (LAS unsigned*)(lds + (bufoff) + ldsw + 8192), 16, 0, 0); } while (0)
; #define G_STAGE_B(bufoff, p, koff) do { \
;         __builtin_amdgcn_global_load_lds((const unsigned*)(gbase + (size_t)(unsigned)((p) + (koff) + voffB[0])), (LAS unsigned*)(lds + (bufoff) + ldsw), 16, 0, 0); \
;         __builtin_amdgcn_global_load_lds((const unsigned*)(gbase + (size_t)(unsigned)((p) + (koff) + voffB[1])), (LAS unsigned*)(lds + (bufoff) + ldsw + 8192), 16, 0, 0); } while (0)
; #define G_LDA(dst, b, h) do { _Pragma("unroll") for (int m = 0; m < 4; ++m) _Pragma("unroll") for (int k = 0; k < 2; ++k) dst[m][k] = *(const LAS bf16x8*)(lds + G_SA(b, h) + aoff + m * 2048 + k * 1024); } while (0)
; #define G_LDB(dst, b, h) do { _Pragma("unroll") for (int n = 0; n < 2; ++n) _Pragma("unroll") for (int k = 0; k < 2; ++k) dst[n][k] = *(const LAS bf16x8*)(lds + G_SB(b, h) + boff + n * 2048 + k * 1024); } while (0)
; #define G_WAIT_V(n) asm volatile("s_waitcnt vmcnt(" #n ")" ::: "memory")
; #define G_BAR __builtin_amdgcn_s_barrier()
; template <class Epi>
; DI void gemm_phase(LAS unsigned char* lds, const Sched& S, const Epi& E, const int K) {
;     ...
;             G_LDB(B0, 0, 0); G_LDB(B1, 0, 1); G_SCHED; G_LDA(At, 0, 0); G_STAGE_A(G_SA(1, 1), cur.a2, cur.a3, k1);
;             G_WAIT_V(8); G_WAIT_L(0); G_BAR; G_MMA(0, 0, At, B0); G_MMA(0, 1, At, B1); G_BAR; G_SCHED;
;             G_LDA(At, 0, 1); G_STAGE_B(G_SB(0, 0), xb, kb2); G_STAGE_B(G_SB(0, 1), xb + hstepB, kb2); G_STAGE_A(G_SA(0, 0), x0, x1, k2);
;             G_WAIT_V(8); G_WAIT_L(0); G_BAR; G_MMA(1, 0, At, B0); G_MMA(1, 1, At, B1); G_BAR; G_SCHED;
;             G_LDB(B0, 1, 0); G_LDB(B1, 1, 1); G_SCHED; G_LDA(At, 1, 0); G_STAGE_A(G_SA(0, 1), x2, x3, k2);
;             G_WAIT_V(8); G_WAIT_L(0); G_BAR; G_MMA(0, 0, At, B0); G_MMA(0, 1, At, B1); G_BAR; G_SCHED;
;             G_LDA(At, 1, 1); G_STAGE_B(G_SB(1, 0), xb, kb3); G_STAGE_B(G_SB(1, 1), xb + hstepB, kb3); G_STAGE_A(G_SA(1, 0), x0, x1, k3);
;             G_WAIT_V(8); G_WAIT_L(0); G_BAR; G_MMA(1, 0, At, B0); G_MMA(1, 1, At, B1); G_BAR; G_SCHED;
	s_setprio 0
	s_waitcnt lgkmcnt(0)
	v_mfma_f32_16x16x32_bf16 v[60:63], v[140:143], v[172:175], v[60:63]
	v_mfma_f32_16x16x32_bf16 v[56:59], v[148:151], v[172:175], v[56:59]
	v_mfma_f32_16x16x32_bf16 v[52:55], v[140:143], v[180:183], v[52:55]
	v_mfma_f32_16x16x32_bf16 v[48:51], v[148:151], v[180:183], v[48:51]
	v_mfma_f32_16x16x32_bf16 v[44:47], v[140:143], v[198:201], v[44:47]
	v_mfma_f32_16x16x32_bf16 v[40:43], v[148:151], v[198:201], v[40:43]
	v_mfma_f32_16x16x32_bf16 v[36:39], v[140:143], v[206:209], v[36:39]
	v_mfma_f32_16x16x32_bf16 v[32:35], v[148:151], v[206:209], v[32:35]
	v_mfma_f32_16x16x32_bf16 v[60:63], v[144:147], v[176:179], v[60:63]
	v_mfma_f32_16x16x32_bf16 v[56:59], v[152:155], v[176:179], v[56:59]
	v_mfma_f32_16x16x32_bf16 v[52:55], v[144:147], v[194:197], v[52:55]
	v_mfma_f32_16x16x32_bf16 v[48:51], v[152:155], v[194:197], v[48:51]
	v_mfma_f32_16x16x32_bf16 v[44:47], v[144:147], v[202:205], v[44:47]
	v_mfma_f32_16x16x32_bf16 v[40:43], v[152:155], v[202:205], v[40:43]
	v_mfma_f32_16x16x32_bf16 v[36:39], v[144:147], v[210:213], v[36:39]
	v_mfma_f32_16x16x32_bf16 v[32:35], v[152:155], v[210:213], v[32:35]
	v_mfma_f32_16x16x32_bf16 v[28:31], v[156:159], v[172:175], v[28:31]
	v_mfma_f32_16x16x32_bf16 v[24:27], v[164:167], v[172:175], v[24:27]
	v_mfma_f32_16x16x32_bf16 v[20:23], v[156:159], v[180:183], v[20:23]
	v_mfma_f32_16x16x32_bf16 v[16:19], v[164:167], v[180:183], v[16:19]
	v_mfma_f32_16x16x32_bf16 v[12:15], v[156:159], v[198:201], v[12:15]
	v_mfma_f32_16x16x32_bf16 v[8:11], v[164:167], v[198:201], v[8:11]
	v_mfma_f32_16x16x32_bf16 v[4:7], v[156:159], v[206:209], v[4:7]
	v_mfma_f32_16x16x32_bf16 v[0:3], v[164:167], v[206:209], v[0:3]
	v_mfma_f32_16x16x32_bf16 v[28:31], v[160:163], v[176:179], v[28:31]
	v_mfma_f32_16x16x32_bf16 v[24:27], v[168:171], v[176:179], v[24:27]
	v_mfma_f32_16x16x32_bf16 v[20:23], v[160:163], v[194:197], v[20:23]
	v_mfma_f32_16x16x32_bf16 v[16:19], v[168:171], v[194:197], v[16:19]
	v_mfma_f32_16x16x32_bf16 v[12:15], v[160:163], v[202:205], v[12:15]
	v_mfma_f32_16x16x32_bf16 v[8:11], v[168:171], v[202:205], v[8:11]
	v_mfma_f32_16x16x32_bf16 v[4:7], v[160:163], v[210:213], v[4:7]
	v_mfma_f32_16x16x32_bf16 v[0:3], v[168:171], v[210:213], v[0:3]
	s_setprio 1
	s_barrier
	s_add_i32 s78, 0, 0x18000
	s_add_i32 s81, 0, 0x1c000
	v_add_u32_e32 v152, s78, v133
	v_add_u32_e32 v168, s81, v133
	ds_read_b128 v[140:143], v152
	ds_read_b128 v[144:147], v152 offset:1024
	ds_read_b128 v[148:151], v152 offset:2048
	ds_read_b128 v[152:155], v152 offset:3072
	ds_read_b128 v[156:159], v168
	ds_read_b128 v[160:163], v168 offset:1024
	ds_read_b128 v[164:167], v168 offset:2048
	ds_read_b128 v[168:171], v168 offset:3072
	s_add_i32 s80, s80, s40
	s_mov_b32 m0, s39
	v_add_u32_e32 v215, s80, v132
	s_add_i32 s79, s79, s40
	ds_read_b128 v[172:175], v137 offset:32768
	ds_read_b128 v[176:179], v137 offset:33792
	ds_read_b128 v[180:183], v137 offset:34816
	ds_read_b128 v[194:197], v137 offset:35840
	ds_read_b128 v[198:201], v137 offset:36864
	ds_read_b128 v[202:205], v137 offset:37888
	ds_read_b128 v[206:209], v137 offset:38912
	ds_read_b128 v[210:213], v137 offset:39936
	global_load_lds_dwordx4 v215, s[82:83]
	v_add_u32_e32 v215, s79, v129
	s_mov_b32 m0, s41
	s_nop 0
	global_load_lds_dwordx4 v215, s[82:83]
	s_waitcnt vmcnt(8)
	s_waitcnt lgkmcnt(0)
	s_barrier
	s_setprio 0
	s_waitcnt lgkmcnt(0)
	v_mfma_f32_16x16x32_bf16 v[124:127], v[140:143], v[172:175], v[124:127]
	v_mfma_f32_16x16x32_bf16 v[120:123], v[148:151], v[172:175], v[120:123]
	v_mfma_f32_16x16x32_bf16 v[116:119], v[140:143], v[180:183], v[116:119]
	v_mfma_f32_16x16x32_bf16 v[112:115], v[148:151], v[180:183], v[112:115]
	v_mfma_f32_16x16x32_bf16 v[108:111], v[140:143], v[198:201], v[108:111]
	v_mfma_f32_16x16x32_bf16 v[104:107], v[148:151], v[198:201], v[104:107]
	v_mfma_f32_16x16x32_bf16 v[100:103], v[140:143], v[206:209], v[100:103]
	v_mfma_f32_16x16x32_bf16 v[96:99], v[148:151], v[206:209], v[96:99]
	v_mfma_f32_16x16x32_bf16 v[124:127], v[144:147], v[176:179], v[124:127]
	v_mfma_f32_16x16x32_bf16 v[120:123], v[152:155], v[176:179], v[120:123]
	v_mfma_f32_16x16x32_bf16 v[116:119], v[144:147], v[194:197], v[116:119]
	v_mfma_f32_16x16x32_bf16 v[112:115], v[152:155], v[194:197], v[112:115]
	v_mfma_f32_16x16x32_bf16 v[108:111], v[144:147], v[202:205], v[108:111]
	v_mfma_f32_16x16x32_bf16 v[104:107], v[152:155], v[202:205], v[104:107]
	v_mfma_f32_16x16x32_bf16 v[100:103], v[144:147], v[210:213], v[100:103]
	v_mfma_f32_16x16x32_bf16 v[96:99], v[152:155], v[210:213], v[96:99]
	v_mfma_f32_16x16x32_bf16 v[92:95], v[156:159], v[172:175], v[92:95]
	v_mfma_f32_16x16x32_bf16 v[88:91], v[164:167], v[172:175], v[88:91]
	v_mfma_f32_16x16x32_bf16 v[84:87], v[156:159], v[180:183], v[84:87]
	v_mfma_f32_16x16x32_bf16 v[80:83], v[164:167], v[180:183], v[80:83]
	v_mfma_f32_16x16x32_bf16 v[76:79], v[156:159], v[198:201], v[76:79]
	v_mfma_f32_16x16x32_bf16 v[72:75], v[164:167], v[198:201], v[72:75]
	v_mfma_f32_16x16x32_bf16 v[68:71], v[156:159], v[206:209], v[68:71]
	v_mfma_f32_16x16x32_bf16 v[64:67], v[164:167], v[206:209], v[64:67]
	v_mfma_f32_16x16x32_bf16 v[92:95], v[160:163], v[176:179], v[92:95]
	v_mfma_f32_16x16x32_bf16 v[88:91], v[168:171], v[176:179], v[88:91]
	v_mfma_f32_16x16x32_bf16 v[84:87], v[160:163], v[194:197], v[84:87]
	v_mfma_f32_16x16x32_bf16 v[80:83], v[168:171], v[194:197], v[80:83]
	v_mfma_f32_16x16x32_bf16 v[76:79], v[160:163], v[202:205], v[76:79]
	v_mfma_f32_16x16x32_bf16 v[72:75], v[168:171], v[202:205], v[72:75]
	v_mfma_f32_16x16x32_bf16 v[68:71], v[160:163], v[210:213], v[68:71]
	v_mfma_f32_16x16x32_bf16 v[64:67], v[168:171], v[210:213], v[64:67]
	s_setprio 1
	s_barrier
; #define G_STAGE_A(bufoff, p0, p1, koff) do { \
;         __builtin_amdgcn_global_load_lds((const unsigned*)(gbase + (size_t)(unsigned)((p0) + (koff) + voffA[0])), (LAS unsigned*)(lds + (bufoff) + ldsw), 16, 0, 0); \
;         __builtin_amdgcn_global_load_lds((const unsigned*)(gbase + (size_t)(unsigned)((p1) + (koff) + voffA[1])), (LAS unsigned*)(lds + (bufoff) + ldsw + 8192), 16, 0, 0); } while (0)
; #define G_STAGE_B(bufoff, p, koff) do { \
;         __builtin_amdgcn_global_load_lds((const unsigned*)(gbase + (size_t)(unsigned)((p) + (koff) + voffB[0])), (LAS unsigned*)(lds + (bufoff) + ldsw), 16, 0, 0); \
;         __builtin_amdgcn_global_load_lds((const unsigned*)(gbase + (size_t)(unsigned)((p) + (koff) + voffB[1])), (LAS unsigned*)(lds + (bufoff) + ldsw + 8192), 16, 0, 0); } while (0)
; #define G_LDA(dst, b, h) do { _Pragma("unroll") for (int m = 0; m < 4; ++m) _Pragma("unroll") for (int k = 0; k < 2; ++k) dst[m][k] = *(const LAS bf16x8*)(lds + G_SA(b, h) + aoff + m * 2048 + k * 1024); } while (0)
; #define G_MMA(ai, bj, At, Bt) do { __builtin_amdgcn_s_setprio(1); _Pragma("unroll") for (int m = 0; m < 4; ++m) _Pragma("unroll") for (int n = 0; n < 2; ++n) _Pragma("unroll") for (int k = 0; k < 2; ++k) \
;         acc[ai][bj][m][n] = __builtin_amdgcn_mfma_f32_16x16x32_bf16(Bt[n][k], At[m][k], acc[ai][bj][m][n], 0, 0, 0); __builtin_amdgcn_s_setprio(0); } while (0)
; #define G_WAIT_V(n) asm volatile("s_waitcnt vmcnt(" #n ")" ::: "memory")
; #define G_WAIT_L(n) asm volatile("s_waitcnt lgkmcnt(" #n ")" ::: "memory")
; #define G_BAR __builtin_amdgcn_s_barrier()
; #define G_SCHED __builtin_amdgcn_sched_barrier(0)
; template <class Epi>
; DI void gemm_phase(LAS unsigned char* lds, const Sched& S, const Epi& E, const int K) {
;     ...
;             G_LDA(At, 1, 1); G_STAGE_B(G_SB(1, 0), xb, kb3); G_STAGE_B(G_SB(1, 1), xb + hstepB, kb3); G_STAGE_A(G_SA(1, 0), x0, x1, k3);
;             G_WAIT_V(8); G_WAIT_L(0); G_BAR; G_MMA(1, 0, At, B0); G_MMA(1, 1, At, B1); G_BAR; G_SCHED;
	s_add_i32 s40, s71, s75
	s_add_i32 s75, s78, s20
	v_add_u32_e32 v215, s40, v128
	s_mov_b32 m0, s75
	ds_read_b128 v[172:175], v137 offset:49152
	ds_read_b128 v[176:179], v137 offset:50176
	ds_read_b128 v[180:183], v137 offset:51200
	ds_read_b128 v[194:197], v137 offset:52224
	ds_read_b128 v[198:201], v137 offset:53248
	ds_read_b128 v[202:205], v137 offset:54272
	ds_read_b128 v[206:209], v137 offset:55296
	ds_read_b128 v[210:213], v137 offset:56320
	global_load_lds_dwordx4 v215, s[82:83]
	v_add_u32_e32 v215, s40, v130
	s_add_i32 m0, s75, 0x2000
	s_add_i32 s14, s71, s14
	s_add_i32 s40, s81, s20
	global_load_lds_dwordx4 v215, s[82:83]
	v_add_u32_e32 v215, s14, v128
	s_mov_b32 m0, s40
	v_add_u32_e32 v184, s71, v184
	global_load_lds_dwordx4 v215, s[82:83]
	v_add_u32_e32 v215, s14, v130
	s_add_i32 m0, s40, 0x2000
	s_nop 0
	global_load_lds_dwordx4 v215, s[82:83]
	s_mov_b32 m0, s45
	s_nop 0
	global_load_lds_dwordx4 v184, s[82:83]
	v_add_u32_e32 v184, s71, v214
	s_mov_b32 m0, s46
	s_nop 0
	global_load_lds_dwordx4 v184, s[82:83]
	s_waitcnt vmcnt(8)
	s_waitcnt lgkmcnt(0)
	s_barrier
	s_setprio 0
	s_waitcnt lgkmcnt(0)
	v_mfma_f32_16x16x32_bf16 v[60:63], v[140:143], v[172:175], v[60:63]
	v_mfma_f32_16x16x32_bf16 v[56:59], v[148:151], v[172:175], v[56:59]
	v_mfma_f32_16x16x32_bf16 v[52:55], v[140:143], v[180:183], v[52:55]
	v_mfma_f32_16x16x32_bf16 v[48:51], v[148:151], v[180:183], v[48:51]
	v_mfma_f32_16x16x32_bf16 v[44:47], v[140:143], v[198:201], v[44:47]
	v_mfma_f32_16x16x32_bf16 v[40:43], v[148:151], v[198:201], v[40:43]
	v_mfma_f32_16x16x32_bf16 v[36:39], v[140:143], v[206:209], v[36:39]
	v_mfma_f32_16x16x32_bf16 v[32:35], v[148:151], v[206:209], v[32:35]
	v_mfma_f32_16x16x32_bf16 v[60:63], v[144:147], v[176:179], v[60:63]
	v_mfma_f32_16x16x32_bf16 v[56:59], v[152:155], v[176:179], v[56:59]
	v_mfma_f32_16x16x32_bf16 v[52:55], v[144:147], v[194:197], v[52:55]
	v_mfma_f32_16x16x32_bf16 v[48:51], v[152:155], v[194:197], v[48:51]
	v_mfma_f32_16x16x32_bf16 v[44:47], v[144:147], v[202:205], v[44:47]
	v_mfma_f32_16x16x32_bf16 v[40:43], v[152:155], v[202:205], v[40:43]
	v_mfma_f32_16x16x32_bf16 v[36:39], v[144:147], v[210:213], v[36:39]
	v_mfma_f32_16x16x32_bf16 v[32:35], v[152:155], v[210:213], v[32:35]
	v_mfma_f32_16x16x32_bf16 v[28:31], v[156:159], v[172:175], v[28:31]
	v_mfma_f32_16x16x32_bf16 v[24:27], v[164:167], v[172:175], v[24:27]
	v_mfma_f32_16x16x32_bf16 v[20:23], v[156:159], v[180:183], v[20:23]
	v_mfma_f32_16x16x32_bf16 v[16:19], v[164:167], v[180:183], v[16:19]
	v_mfma_f32_16x16x32_bf16 v[12:15], v[156:159], v[198:201], v[12:15]
	v_mfma_f32_16x16x32_bf16 v[8:11], v[164:167], v[198:201], v[8:11]
	v_mfma_f32_16x16x32_bf16 v[4:7], v[156:159], v[206:209], v[4:7]
	v_mfma_f32_16x16x32_bf16 v[0:3], v[164:167], v[206:209], v[0:3]
	v_mfma_f32_16x16x32_bf16 v[28:31], v[160:163], v[176:179], v[28:31]
	v_mfma_f32_16x16x32_bf16 v[24:27], v[168:171], v[176:179], v[24:27]
	v_mfma_f32_16x16x32_bf16 v[20:23], v[160:163], v[194:197], v[20:23]
	v_mfma_f32_16x16x32_bf16 v[16:19], v[168:171], v[194:197], v[16:19]
	v_mfma_f32_16x16x32_bf16 v[12:15], v[160:163], v[202:205], v[12:15]
	v_mfma_f32_16x16x32_bf16 v[8:11], v[168:171], v[202:205], v[8:11]
	v_mfma_f32_16x16x32_bf16 v[4:7], v[160:163], v[210:213], v[4:7]
	v_mfma_f32_16x16x32_bf16 v[0:3], v[168:171], v[210:213], v[0:3]
	s_setprio 1
	s_barrier
	s_cmp_ge_u32 s72, s44
	s_mov_b32 s14, s73
	s_mov_b32 s71, s72
	s_cbranch_scc0 .LBB0_196
	s_and_b64 vcc, exec, s[12:13]
	s_mov_b32 s71, 0xf800000
	s_cbranch_vccz .LBB0_199
	s_barrier

; #define G_STAGE_A(bufoff, p0, p1, koff) do { \
;         __builtin_amdgcn_global_load_lds((const unsigned*)(gbase + (size_t)(unsigned)((p0) + (koff) + voffA[0])), (LAS unsigned*)(lds + (bufoff) + ldsw), 16, 0, 0); \
;         __builtin_amdgcn_global_load_lds((const unsigned*)(gbase + (size_t)(unsigned)((p1) + (koff) + voffA[1])), (LAS unsigned*)(lds + (bufoff) + ldsw + 8192), 16, 0, 0); } while (0)
; #define G_STAGE_B(bufoff, p, koff) do { \
;         __builtin_amdgcn_global_load_lds((const unsigned*)(gbase + (size_t)(unsigned)((p) + (koff) + voffB[0])), (LAS unsigned*)(lds + (bufoff) + ldsw), 16, 0, 0); \
;         __builtin_amdgcn_global_load_lds((const unsigned*)(gbase + (size_t)(unsigned)((p) + (koff) + voffB[1])), (LAS unsigned*)(lds + (bufoff) + ldsw + 8192), 16, 0, 0); } while (0)
; #define G_WAIT_V(n) asm volatile("s_waitcnt vmcnt(" #n ")" ::: "memory")
; template <class Epi>
; DI void gemm_phase(LAS unsigned char* lds, const Sched& S, const Epi& E, const int K) {
;     ...
;             const bool last = (t == nt - 2);
;             const unsigned k1 = (unsigned)(t + 1) * kstepA;
;             const unsigned k2 = last ? 0u : (unsigned)(t + 2) * kstepA, k3 = k2 + kstepA;
;             const unsigned kb2 = last ? 0u : (unsigned)(t + 2) * kstepB, kb3 = kb2 + kstepB;
;             const unsigned x0 = last ? n0 : cur.a0, x1 = last ? n1 : cur.a1, x2 = last ? n2 : cur.a2, x3 = last ? n3 : cur.a3;
;             const unsigned xb = last ? nB : cur.b;
;     ...
;             G_LDB(B0, 0, 0); G_LDB(B1, 0, 1); G_SCHED; G_LDA(At, 0, 0); G_STAGE_A(G_SA(1, 1), cur.a2, cur.a3, k1);
;             G_WAIT_V(8); G_WAIT_L(0); G_BAR; G_MMA(0, 0, At, B0); G_MMA(0, 1, At, B1); G_BAR; G_SCHED;
;             G_LDA(At, 0, 1); G_STAGE_B(G_SB(0, 0), xb, kb2); G_STAGE_B(G_SB(0, 1), xb + hstepB, kb2); G_STAGE_A(G_SA(0, 0), x0, x1, k2);
;             G_WAIT_V(8); G_WAIT_L(0); G_BAR; G_MMA(1, 0, At, B0); G_MMA(1, 1, At, B1); G_BAR; G_SCHED;
;             G_LDB(B0, 1, 0); G_LDB(B1, 1, 1); G_SCHED; G_LDA(At, 1, 0); G_STAGE_A(G_SA(0, 1), x2, x3, k2);
;             G_WAIT_V(8); G_WAIT_L(0); G_BAR; G_MMA(0, 0, At, B0); G_MMA(0, 1, At, B1); G_BAR; G_SCHED;
;             G_LDA(At, 1, 1); G_STAGE_B(G_SB(1, 0), xb, kb3); G_STAGE_B(G_SB(1, 1), xb + hstepB, kb3); G_STAGE_A(G_SA(1, 0), x0, x1, k3);
;             G_WAIT_V(8); G_WAIT_L(0); G_BAR; G_MMA(1, 0, At, B0); G_MMA(1, 1, At, B1); G_BAR; G_SCHED;
.LBB0_217:
	s_add_i32 s71, s70, 2
	s_add_i32 s72, s14, 0x100
	s_cmp_eq_u32 s46, s70
	s_cselect_b32 s40, 0, s72
	s_cselect_b32 s75, s15, s38
	s_cselect_b32 s78, s68, s36
	s_cselect_b32 s79, s67, s37
	s_cselect_b32 s80, s13, s35
	s_cselect_b32 s73, s69, s27
	s_add_i32 s81, 0, 0x10000
	s_add_i32 s86, 0, 0x14000
	v_add_u32_e32 v152, s81, v133
	v_add_u32_e32 v168, s86, v133
	ds_read_b128 v[140:143], v152
	ds_read_b128 v[144:147], v152 offset:1024
	ds_read_b128 v[148:151], v152 offset:2048
	ds_read_b128 v[152:155], v152 offset:3072
	ds_read_b128 v[156:159], v168
	ds_read_b128 v[160:163], v168 offset:1024
	ds_read_b128 v[164:167], v168 offset:2048
	ds_read_b128 v[168:171], v168 offset:3072
	s_or_b32 s70, s40, 0x80
	v_add_u32_e32 v184, s14, v139
	s_add_i32 m0, s26, 0xc000
	ds_read_b128 v[172:175], v137
	ds_read_b128 v[176:179], v137 offset:1024
	ds_read_b128 v[180:183], v137 offset:2048
	ds_read_b128 v[194:197], v137 offset:3072
	ds_read_b128 v[198:201], v137 offset:4096
	ds_read_b128 v[202:205], v137 offset:5120
	ds_read_b128 v[206:209], v137 offset:6144
	ds_read_b128 v[210:213], v137 offset:7168
	global_load_lds_dwordx4 v184, s[82:83]
	v_add_u32_e32 v184, s14, v138
	s_add_i32 m0, s26, 0xe000
	s_nop 0
	global_load_lds_dwordx4 v184, s[82:83]
	s_waitcnt vmcnt(8)
	s_waitcnt lgkmcnt(0)
	s_barrier
	s_setprio 0
	s_waitcnt lgkmcnt(0)
	v_mfma_f32_16x16x32_bf16 v[124:127], v[140:143], v[172:175], v[124:127]
	v_mfma_f32_16x16x32_bf16 v[120:123], v[148:151], v[172:175], v[120:123]
	v_mfma_f32_16x16x32_bf16 v[116:119], v[140:143], v[180:183], v[116:119]
	v_mfma_f32_16x16x32_bf16 v[112:115], v[148:151], v[180:183], v[112:115]
	v_mfma_f32_16x16x32_bf16 v[108:111], v[140:143], v[198:201], v[108:111]
	v_mfma_f32_16x16x32_bf16 v[104:107], v[148:151], v[198:201], v[104:107]
	v_mfma_f32_16x16x32_bf16 v[100:103], v[140:143], v[206:209], v[100:103]
	v_mfma_f32_16x16x32_bf16 v[96:99], v[148:151], v[206:209], v[96:99]
	v_mfma_f32_16x16x32_bf16 v[124:127], v[144:147], v[176:179], v[124:127]
	v_mfma_f32_16x16x32_bf16 v[120:123], v[152:155], v[176:179], v[120:123]
	v_mfma_f32_16x16x32_bf16 v[116:119], v[144:147], v[194:197], v[116:119]
	v_mfma_f32_16x16x32_bf16 v[112:115], v[152:155], v[194:197], v[112:115]
	v_mfma_f32_16x16x32_bf16 v[108:111], v[144:147], v[202:205], v[108:111]
	v_mfma_f32_16x16x32_bf16 v[104:107], v[152:155], v[202:205], v[104:107]
	v_mfma_f32_16x16x32_bf16 v[100:103], v[144:147], v[210:213], v[100:103]
	v_mfma_f32_16x16x32_bf16 v[96:99], v[152:155], v[210:213], v[96:99]
	v_mfma_f32_16x16x32_bf16 v[92:95], v[156:159], v[172:175], v[92:95]
	v_mfma_f32_16x16x32_bf16 v[88:91], v[164:167], v[172:175], v[88:91]
	v_mfma_f32_16x16x32_bf16 v[84:87], v[156:159], v[180:183], v[84:87]
	v_mfma_f32_16x16x32_bf16 v[80:83], v[164:167], v[180:183], v[80:83]
	v_mfma_f32_16x16x32_bf16 v[76:79], v[156:159], v[198:201], v[76:79]
	v_mfma_f32_16x16x32_bf16 v[72:75], v[164:167], v[198:201], v[72:75]
	v_mfma_f32_16x16x32_bf16 v[68:71], v[156:159], v[206:209], v[68:71]
	v_mfma_f32_16x16x32_bf16 v[64:67], v[164:167], v[206:209], v[64:67]
	v_mfma_f32_16x16x32_bf16 v[92:95], v[160:163], v[176:179], v[92:95]
	v_mfma_f32_16x16x32_bf16 v[88:91], v[168:171], v[176:179], v[88:91]
	v_mfma_f32_16x16x32_bf16 v[84:87], v[160:163], v[194:197], v[84:87]
	v_mfma_f32_16x16x32_bf16 v[80:83], v[168:171], v[194:197], v[80:83]
	v_mfma_f32_16x16x32_bf16 v[76:79], v[160:163], v[202:205], v[76:79]
	v_mfma_f32_16x16x32_bf16 v[72:75], v[168:171], v[202:205], v[72:75]
	v_mfma_f32_16x16x32_bf16 v[68:71], v[160:163], v[210:213], v[68:71]
	v_mfma_f32_16x16x32_bf16 v[64:67], v[168:171], v[210:213], v[64:67]
	s_setprio 1
	s_barrier
	s_add_i32 s14, s40, s73
	s_add_i32 s81, s81, s21
	v_add_u32_e32 v184, s14, v128
	s_mov_b32 m0, s81
	ds_read_b128 v[172:175], v137 offset:16384
	ds_read_b128 v[176:179], v137 offset:17408
	ds_read_b128 v[180:183], v137 offset:18432
	ds_read_b128 v[194:197], v137 offset:19456
	ds_read_b128 v[198:201], v137 offset:20480
	ds_read_b128 v[202:205], v137 offset:21504
	ds_read_b128 v[206:209], v137 offset:22528
	ds_read_b128 v[210:213], v137 offset:23552
	global_load_lds_dwordx4 v184, s[82:83]
	v_add_u32_e32 v184, s14, v130
	s_add_i32 s14, s73, s16
	s_add_i32 m0, s81, 0x2000
	s_add_i32 s81, s14, s40
	s_add_i32 s86, s86, s21
	global_load_lds_dwordx4 v184, s[82:83]
	v_add_u32_e32 v184, s81, v128
	s_mov_b32 m0, s86
	s_nop 0
	global_load_lds_dwordx4 v184, s[82:83]
	v_add_u32_e32 v184, s81, v130
	s_add_i32 m0, s86, 0x2000
	s_nop 0
	global_load_lds_dwordx4 v184, s[82:83]
	v_add_u32_e32 v184, s80, v132
	v_add_u32_e32 v214, s40, v184
	s_mov_b32 m0, s26
	s_nop 0
	global_load_lds_dwordx4 v214, s[82:83]
	v_add_u32_e32 v214, s75, v129
	v_add_u32_e32 v215, s40, v214
	s_mov_b32 m0, s39
	s_nop 0
	global_load_lds_dwordx4 v215, s[82:83]
	s_waitcnt vmcnt(8)
	s_waitcnt lgkmcnt(0)
	s_barrier
; #define G_STAGE_A(bufoff, p0, p1, koff) do { \
;         __builtin_amdgcn_global_load_lds((const unsigned*)(gbase + (size_t)(unsigned)((p0) + (koff) + voffA[0])), (LAS unsigned*)(lds + (bufoff) + ldsw), 16, 0, 0); \
;         __builtin_amdgcn_global_load_lds((const unsigned*)(gbase + (size_t)(unsigned)((p1) + (koff) + voffA[1])), (LAS unsigned*)(lds + (bufoff) + ldsw + 8192), 16, 0, 0); } while (0)
; #define G_STAGE_B(bufoff, p, koff) do { \
;         __builtin_amdgcn_global_load_lds((const unsigned*)(gbase + (size_t)(unsigned)((p) + (koff) + voffB[0])), (LAS unsigned*)(lds + (bufoff) + ldsw), 16, 0, 0); \
;         __builtin_amdgcn_global_load_lds((const unsigned*)(gbase + (size_t)(unsigned)((p) + (koff) + voffB[1])), (LAS unsigned*)(lds + (bufoff) + ldsw + 8192), 16, 0, 0); } while (0)
; #define G_LDA(dst, b, h) do { _Pragma("unroll") for (int m = 0; m < 4; ++m) _Pragma("unroll") for (int k = 0; k < 2; ++k) dst[m][k] = *(const LAS bf16x8*)(lds + G_SA(b, h) + aoff + m * 2048 + k * 1024); } while (0)
; #define G_LDB(dst, b, h) do { _Pragma("unroll") for (int n = 0; n < 2; ++n) _Pragma("unroll") for (int k = 0; k < 2; ++k) dst[n][k] = *(const LAS bf16x8*)(lds + G_SB(b, h) + boff + n * 2048 + k * 1024); } while (0)
; #define G_WAIT_V(n) asm volatile("s_waitcnt vmcnt(" #n ")" ::: "memory")
; #define G_BAR __builtin_amdgcn_s_barrier()
; template <class Epi>
; DI void gemm_phase(LAS unsigned char* lds, const Sched& S, const Epi& E, const int K) {
;     ...
;             G_LDB(B0, 0, 0); G_LDB(B1, 0, 1); G_SCHED; G_LDA(At, 0, 0); G_STAGE_A(G_SA(1, 1), cur.a2, cur.a3, k1);
;             G_WAIT_V(8); G_WAIT_L(0); G_BAR; G_MMA(0, 0, At, B0); G_MMA(0, 1, At, B1); G_BAR; G_SCHED;
;             G_LDA(At, 0, 1); G_STAGE_B(G_SB(0, 0), xb, kb2); G_STAGE_B(G_SB(0, 1), xb + hstepB, kb2); G_STAGE_A(G_SA(0, 0), x0, x1, k2);
;             G_WAIT_V(8); G_WAIT_L(0); G_BAR; G_MMA(1, 0, At, B0); G_MMA(1, 1, At, B1); G_BAR; G_SCHED;
;             G_LDB(B0, 1, 0); G_LDB(B1, 1, 1); G_SCHED; G_LDA(At, 1, 0); G_STAGE_A(G_SA(0, 1), x2, x3, k2);
;             G_WAIT_V(8); G_WAIT_L(0); G_BAR; G_MMA(0, 0, At, B0); G_MMA(0, 1, At, B1); G_BAR; G_SCHED;
;             G_LDA(At, 1, 1); G_STAGE_B(G_SB(1, 0), xb, kb3); G_STAGE_B(G_SB(1, 1), xb + hstepB, kb3); G_STAGE_A(G_SA(1, 0), x0, x1, k3);
;             G_WAIT_V(8); G_WAIT_L(0); G_BAR; G_MMA(1, 0, At, B0); G_MMA(1, 1, At, B1); G_BAR; G_SCHED;
	s_setprio 0
	s_waitcnt lgkmcnt(0)
	v_mfma_f32_16x16x32_bf16 v[60:63], v[140:143], v[172:175], v[60:63]
	v_mfma_f32_16x16x32_bf16 v[56:59], v[148:151], v[172:175], v[56:59]
	v_mfma_f32_16x16x32_bf16 v[52:55], v[140:143], v[180:183], v[52:55]
	v_mfma_f32_16x16x32_bf16 v[48:51], v[148:151], v[180:183], v[48:51]
	v_mfma_f32_16x16x32_bf16 v[44:47], v[140:143], v[198:201], v[44:47]
	v_mfma_f32_16x16x32_bf16 v[40:43], v[148:151], v[198:201], v[40:43]
	v_mfma_f32_16x16x32_bf16 v[36:39], v[140:143], v[206:209], v[36:39]
	v_mfma_f32_16x16x32_bf16 v[32:35], v[148:151], v[206:209], v[32:35]
	v_mfma_f32_16x16x32_bf16 v[60:63], v[144:147], v[176:179], v[60:63]
	v_mfma_f32_16x16x32_bf16 v[56:59], v[152:155], v[176:179], v[56:59]
	v_mfma_f32_16x16x32_bf16 v[52:55], v[144:147], v[194:197], v[52:55]
	v_mfma_f32_16x16x32_bf16 v[48:51], v[152:155], v[194:197], v[48:51]
	v_mfma_f32_16x16x32_bf16 v[44:47], v[144:147], v[202:205], v[44:47]
	v_mfma_f32_16x16x32_bf16 v[40:43], v[152:155], v[202:205], v[40:43]
	v_mfma_f32_16x16x32_bf16 v[36:39], v[144:147], v[210:213], v[36:39]
	v_mfma_f32_16x16x32_bf16 v[32:35], v[152:155], v[210:213], v[32:35]
	v_mfma_f32_16x16x32_bf16 v[28:31], v[156:159], v[172:175], v[28:31]
	v_mfma_f32_16x16x32_bf16 v[24:27], v[164:167], v[172:175], v[24:27]
	v_mfma_f32_16x16x32_bf16 v[20:23], v[156:159], v[180:183], v[20:23]
	v_mfma_f32_16x16x32_bf16 v[16:19], v[164:167], v[180:183], v[16:19]
	v_mfma_f32_16x16x32_bf16 v[12:15], v[156:159], v[198:201], v[12:15]
	v_mfma_f32_16x16x32_bf16 v[8:11], v[164:167], v[198:201], v[8:11]
	v_mfma_f32_16x16x32_bf16 v[4:7], v[156:159], v[206:209], v[4:7]
	v_mfma_f32_16x16x32_bf16 v[0:3], v[164:167], v[206:209], v[0:3]
	v_mfma_f32_16x16x32_bf16 v[28:31], v[160:163], v[176:179], v[28:31]
	v_mfma_f32_16x16x32_bf16 v[24:27], v[168:171], v[176:179], v[24:27]
	v_mfma_f32_16x16x32_bf16 v[20:23], v[160:163], v[194:197], v[20:23]
	v_mfma_f32_16x16x32_bf16 v[16:19], v[168:171], v[194:197], v[16:19]
	v_mfma_f32_16x16x32_bf16 v[12:15], v[160:163], v[202:205], v[12:15]
	v_mfma_f32_16x16x32_bf16 v[8:11], v[168:171], v[202:205], v[8:11]
	v_mfma_f32_16x16x32_bf16 v[4:7], v[160:163], v[210:213], v[4:7]
	v_mfma_f32_16x16x32_bf16 v[0:3], v[168:171], v[210:213], v[0:3]
	s_setprio 1
	s_barrier
	s_add_i32 s75, 0, 0x18000
	s_add_i32 s80, 0, 0x1c000
	v_add_u32_e32 v152, s75, v133
	v_add_u32_e32 v168, s80, v133
	ds_read_b128 v[140:143], v152
	ds_read_b128 v[144:147], v152 offset:1024
	ds_read_b128 v[148:151], v152 offset:2048
	ds_read_b128 v[152:155], v152 offset:3072
	ds_read_b128 v[156:159], v168
	ds_read_b128 v[160:163], v168 offset:1024
	ds_read_b128 v[164:167], v168 offset:2048
	ds_read_b128 v[168:171], v168 offset:3072
	s_add_i32 s79, s79, s40
	s_mov_b32 m0, s41
	v_add_u32_e32 v215, s79, v132
	s_add_i32 s78, s78, s40
	ds_read_b128 v[172:175], v137 offset:32768
	ds_read_b128 v[176:179], v137 offset:33792
	ds_read_b128 v[180:183], v137 offset:34816
	ds_read_b128 v[194:197], v137 offset:35840
	ds_read_b128 v[198:201], v137 offset:36864
	ds_read_b128 v[202:205], v137 offset:37888
	ds_read_b128 v[206:209], v137 offset:38912
	ds_read_b128 v[210:213], v137 offset:39936
	global_load_lds_dwordx4 v215, s[82:83]
	v_add_u32_e32 v215, s78, v129
	s_mov_b32 m0, s44
	s_nop 0
	global_load_lds_dwordx4 v215, s[82:83]
	s_waitcnt vmcnt(8)
	s_waitcnt lgkmcnt(0)
	s_barrier
	s_setprio 0
	s_waitcnt lgkmcnt(0)
	v_mfma_f32_16x16x32_bf16 v[124:127], v[140:143], v[172:175], v[124:127]
	v_mfma_f32_16x16x32_bf16 v[120:123], v[148:151], v[172:175], v[120:123]
	v_mfma_f32_16x16x32_bf16 v[116:119], v[140:143], v[180:183], v[116:119]
	v_mfma_f32_16x16x32_bf16 v[112:115], v[148:151], v[180:183], v[112:115]
	v_mfma_f32_16x16x32_bf16 v[108:111], v[140:143], v[198:201], v[108:111]
	v_mfma_f32_16x16x32_bf16 v[104:107], v[148:151], v[198:201], v[104:107]
	v_mfma_f32_16x16x32_bf16 v[100:103], v[140:143], v[206:209], v[100:103]
	v_mfma_f32_16x16x32_bf16 v[96:99], v[148:151], v[206:209], v[96:99]
	v_mfma_f32_16x16x32_bf16 v[124:127], v[144:147], v[176:179], v[124:127]
	v_mfma_f32_16x16x32_bf16 v[120:123], v[152:155], v[176:179], v[120:123]
	v_mfma_f32_16x16x32_bf16 v[116:119], v[144:147], v[194:197], v[116:119]
	v_mfma_f32_16x16x32_bf16 v[112:115], v[152:155], v[194:197], v[112:115]
	v_mfma_f32_16x16x32_bf16 v[108:111], v[144:147], v[202:205], v[108:111]
	v_mfma_f32_16x16x32_bf16 v[104:107], v[152:155], v[202:205], v[104:107]
	v_mfma_f32_16x16x32_bf16 v[100:103], v[144:147], v[210:213], v[100:103]
	v_mfma_f32_16x16x32_bf16 v[96:99], v[152:155], v[210:213], v[96:99]
	v_mfma_f32_16x16x32_bf16 v[92:95], v[156:159], v[172:175], v[92:95]
	v_mfma_f32_16x16x32_bf16 v[88:91], v[164:167], v[172:175], v[88:91]
	v_mfma_f32_16x16x32_bf16 v[84:87], v[156:159], v[180:183], v[84:87]
	v_mfma_f32_16x16x32_bf16 v[80:83], v[164:167], v[180:183], v[80:83]
	v_mfma_f32_16x16x32_bf16 v[76:79], v[156:159], v[198:201], v[76:79]
	v_mfma_f32_16x16x32_bf16 v[72:75], v[164:167], v[198:201], v[72:75]
	v_mfma_f32_16x16x32_bf16 v[68:71], v[156:159], v[206:209], v[68:71]
	v_mfma_f32_16x16x32_bf16 v[64:67], v[164:167], v[206:209], v[64:67]
	v_mfma_f32_16x16x32_bf16 v[92:95], v[160:163], v[176:179], v[92:95]
	v_mfma_f32_16x16x32_bf16 v[88:91], v[168:171], v[176:179], v[88:91]
	v_mfma_f32_16x16x32_bf16 v[84:87], v[160:163], v[194:197], v[84:87]
	v_mfma_f32_16x16x32_bf16 v[80:83], v[168:171], v[194:197], v[80:83]
	v_mfma_f32_16x16x32_bf16 v[76:79], v[160:163], v[202:205], v[76:79]
	v_mfma_f32_16x16x32_bf16 v[72:75], v[168:171], v[202:205], v[72:75]
	v_mfma_f32_16x16x32_bf16 v[68:71], v[160:163], v[210:213], v[68:71]
	v_mfma_f32_16x16x32_bf16 v[64:67], v[168:171], v[210:213], v[64:67]
	s_setprio 1
	s_barrier
; #define G_STAGE_A(bufoff, p0, p1, koff) do { \
;         __builtin_amdgcn_global_load_lds((const unsigned*)(gbase + (size_t)(unsigned)((p0) + (koff) + voffA[0])), (LAS unsigned*)(lds + (bufoff) + ldsw), 16, 0, 0); \
;         __builtin_amdgcn_global_load_lds((const unsigned*)(gbase + (size_t)(unsigned)((p1) + (koff) + voffA[1])), (LAS unsigned*)(lds + (bufoff) + ldsw + 8192), 16, 0, 0); } while (0)
; #define G_STAGE_B(bufoff, p, koff) do { \
;         __builtin_amdgcn_global_load_lds((const unsigned*)(gbase + (size_t)(unsigned)((p) + (koff) + voffB[0])), (LAS unsigned*)(lds + (bufoff) + ldsw), 16, 0, 0); \
;         __builtin_amdgcn_global_load_lds((const unsigned*)(gbase + (size_t)(unsigned)((p) + (koff) + voffB[1])), (LAS unsigned*)(lds + (bufoff) + ldsw + 8192), 16, 0, 0); } while (0)
; #define G_LDA(dst, b, h) do { _Pragma("unroll") for (int m = 0; m < 4; ++m) _Pragma("unroll") for (int k = 0; k < 2; ++k) dst[m][k] = *(const LAS bf16x8*)(lds + G_SA(b, h) + aoff + m * 2048 + k * 1024); } while (0)
; #define G_MMA(ai, bj, At, Bt) do { __builtin_amdgcn_s_setprio(1); _Pragma("unroll") for (int m = 0; m < 4; ++m) _Pragma("unroll") for (int n = 0; n < 2; ++n) _Pragma("unroll") for (int k = 0; k < 2; ++k) \
;         acc[ai][bj][m][n] = __builtin_amdgcn_mfma_f32_16x16x32_bf16(Bt[n][k], At[m][k], acc[ai][bj][m][n], 0, 0, 0); __builtin_amdgcn_s_setprio(0); } while (0)
; #define G_WAIT_V(n) asm volatile("s_waitcnt vmcnt(" #n ")" ::: "memory")
; #define G_WAIT_L(n) asm volatile("s_waitcnt lgkmcnt(" #n ")" ::: "memory")
; #define G_BAR __builtin_amdgcn_s_barrier()
; #define G_SCHED __builtin_amdgcn_sched_barrier(0)
; template <class Epi>
; DI void gemm_phase(LAS unsigned char* lds, const Sched& S, const Epi& E, const int K) {
;     ...
;             G_LDA(At, 1, 1); G_STAGE_B(G_SB(1, 0), xb, kb3); G_STAGE_B(G_SB(1, 1), xb + hstepB, kb3); G_STAGE_A(G_SA(1, 0), x0, x1, k3);
;             G_WAIT_V(8); G_WAIT_L(0); G_BAR; G_MMA(1, 0, At, B0); G_MMA(1, 1, At, B1); G_BAR; G_SCHED;
	s_add_i32 s40, s70, s73
	s_add_i32 s73, s75, s21
	v_add_u32_e32 v215, s40, v128
	s_mov_b32 m0, s73
	ds_read_b128 v[172:175], v137 offset:49152
	ds_read_b128 v[176:179], v137 offset:50176
	ds_read_b128 v[180:183], v137 offset:51200
	ds_read_b128 v[194:197], v137 offset:52224
	ds_read_b128 v[198:201], v137 offset:53248
	ds_read_b128 v[202:205], v137 offset:54272
	ds_read_b128 v[206:209], v137 offset:55296
	ds_read_b128 v[210:213], v137 offset:56320
	global_load_lds_dwordx4 v215, s[82:83]
	v_add_u32_e32 v215, s40, v130
	s_add_i32 m0, s73, 0x2000
	s_add_i32 s14, s70, s14
	s_add_i32 s40, s80, s21
	global_load_lds_dwordx4 v215, s[82:83]
	v_add_u32_e32 v215, s14, v128
	s_mov_b32 m0, s40
	v_add_u32_e32 v184, s70, v184
	global_load_lds_dwordx4 v215, s[82:83]
	v_add_u32_e32 v215, s14, v130
	s_add_i32 m0, s40, 0x2000
	s_nop 0
	global_load_lds_dwordx4 v215, s[82:83]
	s_mov_b32 m0, s18
	s_nop 0
	global_load_lds_dwordx4 v184, s[82:83]
	v_add_u32_e32 v184, s70, v214
	s_mov_b32 m0, s45
	s_nop 0
	global_load_lds_dwordx4 v184, s[82:83]
	s_waitcnt vmcnt(8)
	s_waitcnt lgkmcnt(0)
	s_barrier
	s_setprio 0
	s_waitcnt lgkmcnt(0)
	v_mfma_f32_16x16x32_bf16 v[60:63], v[140:143], v[172:175], v[60:63]
	v_mfma_f32_16x16x32_bf16 v[56:59], v[148:151], v[172:175], v[56:59]
	v_mfma_f32_16x16x32_bf16 v[52:55], v[140:143], v[180:183], v[52:55]
	v_mfma_f32_16x16x32_bf16 v[48:51], v[148:151], v[180:183], v[48:51]
	v_mfma_f32_16x16x32_bf16 v[44:47], v[140:143], v[198:201], v[44:47]
	v_mfma_f32_16x16x32_bf16 v[40:43], v[148:151], v[198:201], v[40:43]
	v_mfma_f32_16x16x32_bf16 v[36:39], v[140:143], v[206:209], v[36:39]
	v_mfma_f32_16x16x32_bf16 v[32:35], v[148:151], v[206:209], v[32:35]
	v_mfma_f32_16x16x32_bf16 v[60:63], v[144:147], v[176:179], v[60:63]
	v_mfma_f32_16x16x32_bf16 v[56:59], v[152:155], v[176:179], v[56:59]
	v_mfma_f32_16x16x32_bf16 v[52:55], v[144:147], v[194:197], v[52:55]
	v_mfma_f32_16x16x32_bf16 v[48:51], v[152:155], v[194:197], v[48:51]
	v_mfma_f32_16x16x32_bf16 v[44:47], v[144:147], v[202:205], v[44:47]
	v_mfma_f32_16x16x32_bf16 v[40:43], v[152:155], v[202:205], v[40:43]
	v_mfma_f32_16x16x32_bf16 v[36:39], v[144:147], v[210:213], v[36:39]
	v_mfma_f32_16x16x32_bf16 v[32:35], v[152:155], v[210:213], v[32:35]
	v_mfma_f32_16x16x32_bf16 v[28:31], v[156:159], v[172:175], v[28:31]
	v_mfma_f32_16x16x32_bf16 v[24:27], v[164:167], v[172:175], v[24:27]
	v_mfma_f32_16x16x32_bf16 v[20:23], v[156:159], v[180:183], v[20:23]
	v_mfma_f32_16x16x32_bf16 v[16:19], v[164:167], v[180:183], v[16:19]
	v_mfma_f32_16x16x32_bf16 v[12:15], v[156:159], v[198:201], v[12:15]
	v_mfma_f32_16x16x32_bf16 v[8:11], v[164:167], v[198:201], v[8:11]
	v_mfma_f32_16x16x32_bf16 v[4:7], v[156:159], v[206:209], v[4:7]
	v_mfma_f32_16x16x32_bf16 v[0:3], v[164:167], v[206:209], v[0:3]
	v_mfma_f32_16x16x32_bf16 v[28:31], v[160:163], v[176:179], v[28:31]
	v_mfma_f32_16x16x32_bf16 v[24:27], v[168:171], v[176:179], v[24:27]
	v_mfma_f32_16x16x32_bf16 v[20:23], v[160:163], v[194:197], v[20:23]
	v_mfma_f32_16x16x32_bf16 v[16:19], v[168:171], v[194:197], v[16:19]
	v_mfma_f32_16x16x32_bf16 v[12:15], v[160:163], v[202:205], v[12:15]
	v_mfma_f32_16x16x32_bf16 v[8:11], v[168:171], v[202:205], v[8:11]
	v_mfma_f32_16x16x32_bf16 v[4:7], v[160:163], v[210:213], v[4:7]
	v_mfma_f32_16x16x32_bf16 v[0:3], v[168:171], v[210:213], v[0:3]
	s_setprio 1
	s_barrier
	s_cmp_ge_u32 s71, s17
	s_mov_b32 s14, s72
	s_mov_b32 s70, s71
	s_cbranch_scc0 .LBB0_217
	s_and_b64 vcc, exec, s[10:11]
	s_movk_i32 s70, 0x1000
	s_cbranch_vccz .LBB0_220
	s_barrier

; #define G_STAGE_A(bufoff, p0, p1, koff) do { \
;         __builtin_amdgcn_global_load_lds((const unsigned*)(gbase + (size_t)(unsigned)((p0) + (koff) + voffA[0])), (LAS unsigned*)(lds + (bufoff) + ldsw), 16, 0, 0); \
;         __builtin_amdgcn_global_load_lds((const unsigned*)(gbase + (size_t)(unsigned)((p1) + (koff) + voffA[1])), (LAS unsigned*)(lds + (bufoff) + ldsw + 8192), 16, 0, 0); } while (0)
; #define G_STAGE_B(bufoff, p, koff) do { \
;         __builtin_amdgcn_global_load_lds((const unsigned*)(gbase + (size_t)(unsigned)((p) + (koff) + voffB[0])), (LAS unsigned*)(lds + (bufoff) + ldsw), 16, 0, 0); \
;         __builtin_amdgcn_global_load_lds((const unsigned*)(gbase + (size_t)(unsigned)((p) + (koff) + voffB[1])), (LAS unsigned*)(lds + (bufoff) + ldsw + 8192), 16, 0, 0); } while (0)
; #define G_LDA(dst, b, h) do { _Pragma("unroll") for (int m = 0; m < 4; ++m) _Pragma("unroll") for (int k = 0; k < 2; ++k) dst[m][k] = *(const LAS bf16x8*)(lds + G_SA(b, h) + aoff + m * 2048 + k * 1024); } while (0)
; #define G_LDB(dst, b, h) do { _Pragma("unroll") for (int n = 0; n < 2; ++n) _Pragma("unroll") for (int k = 0; k < 2; ++k) dst[n][k] = *(const LAS bf16x8*)(lds + G_SB(b, h) + boff + n * 2048 + k * 1024); } while (0)
; #define G_WAIT_V(n) asm volatile("s_waitcnt vmcnt(" #n ")" ::: "memory")
; #define G_BAR __builtin_amdgcn_s_barrier()
; template <class Epi>
; DI void gemm_phase(LAS unsigned char* lds, const Sched& S, const Epi& E, const int K) {
;     ...
;             G_LDB(B0, 0, 0); G_LDB(B1, 0, 1); G_SCHED; G_LDA(At, 0, 0); G_STAGE_A(G_SA(1, 1), cur.a2, cur.a3, k1);
;             G_WAIT_V(8); G_WAIT_L(0); G_BAR; G_MMA(0, 0, At, B0); G_MMA(0, 1, At, B1); G_BAR; G_SCHED;
;             G_LDA(At, 0, 1); G_STAGE_B(G_SB(0, 0), xb, kb2); G_STAGE_B(G_SB(0, 1), xb + hstepB, kb2); G_STAGE_A(G_SA(0, 0), x0, x1, k2);
;             G_WAIT_V(8); G_WAIT_L(0); G_BAR; G_MMA(1, 0, At, B0); G_MMA(1, 1, At, B1); G_BAR; G_SCHED;
;             G_LDB(B0, 1, 0); G_LDB(B1, 1, 1); G_SCHED; G_LDA(At, 1, 0); G_STAGE_A(G_SA(0, 1), x2, x3, k2);
;             G_WAIT_V(8); G_WAIT_L(0); G_BAR; G_MMA(0, 0, At, B0); G_MMA(0, 1, At, B1); G_BAR; G_SCHED;
;             G_LDA(At, 1, 1); G_STAGE_B(G_SB(1, 0), xb, kb3); G_STAGE_B(G_SB(1, 1), xb + hstepB, kb3); G_STAGE_A(G_SA(1, 0), x0, x1, k3);
;             G_WAIT_V(8); G_WAIT_L(0); G_BAR; G_MMA(1, 0, At, B0); G_MMA(1, 1, At, B1); G_BAR; G_SCHED;
.LBB0_240:
	s_add_i32 s14, s15, 0x8000
	v_add_u32_e32 v151, s14, v80
	v_add_u32_e32 v152, s14, v81
	s_add_i32 s14, s15, 0x80
	v_add_u32_e32 v153, s14, v80
	v_add_u32_e32 v154, s14, v81
	s_add_i32 s14, s15, 0x8080
	v_add_u32_e32 v85, s15, v80
	v_add_u32_e32 v150, s15, v81
	v_add_u32_e32 v155, s14, v80
	v_add_u32_e32 v156, s14, v81
	s_add_i32 s14, 0, 0x10000
	s_add_i32 s15, 0, 0x14000
	v_add_u32_e32 v98, s14, v83
	v_add_u32_e32 v114, s15, v83
	ds_read_b128 v[86:89], v98
	ds_read_b128 v[90:93], v98 offset:1024
	ds_read_b128 v[94:97], v98 offset:2048
	ds_read_b128 v[98:101], v98 offset:3072
	ds_read_b128 v[102:105], v114
	ds_read_b128 v[106:109], v114 offset:1024
	ds_read_b128 v[110:113], v114 offset:2048
	ds_read_b128 v[114:117], v114 offset:3072
	s_add_i32 m0, s17, 0xc000
	s_waitcnt vmcnt(0)
	ds_read_b128 v[118:121], v84
	ds_read_b128 v[122:125], v84 offset:1024
	ds_read_b128 v[126:129], v84 offset:2048
	ds_read_b128 v[130:133], v84 offset:3072
	ds_read_b128 v[134:137], v84 offset:4096
	ds_read_b128 v[138:141], v84 offset:5120
	ds_read_b128 v[142:145], v84 offset:6144
	ds_read_b128 v[146:149], v84 offset:7168
	global_load_lds_dwordx4 v[76:77], off
	s_add_i32 m0, s17, 0xe000
	s_nop 0
	global_load_lds_dwordx4 v[78:79], off
	s_waitcnt vmcnt(8)
	s_waitcnt lgkmcnt(0)
	s_barrier
	s_setprio 0
	s_waitcnt lgkmcnt(0)
	v_mfma_f32_16x16x32_bf16 v[60:63], v[86:89], v[118:121], v[60:63]
	v_mfma_f32_16x16x32_bf16 v[56:59], v[94:97], v[118:121], v[56:59]
	v_mfma_f32_16x16x32_bf16 v[52:55], v[86:89], v[126:129], v[52:55]
	v_mfma_f32_16x16x32_bf16 v[48:51], v[94:97], v[126:129], v[48:51]
	v_mfma_f32_16x16x32_bf16 v[44:47], v[86:89], v[134:137], v[44:47]
	v_mfma_f32_16x16x32_bf16 v[40:43], v[94:97], v[134:137], v[40:43]
	v_mfma_f32_16x16x32_bf16 v[36:39], v[86:89], v[142:145], v[36:39]
	v_mfma_f32_16x16x32_bf16 v[32:35], v[94:97], v[142:145], v[32:35]
	v_mfma_f32_16x16x32_bf16 v[60:63], v[90:93], v[122:125], v[60:63]
	v_mfma_f32_16x16x32_bf16 v[56:59], v[98:101], v[122:125], v[56:59]
	v_mfma_f32_16x16x32_bf16 v[52:55], v[90:93], v[130:133], v[52:55]
	v_mfma_f32_16x16x32_bf16 v[48:51], v[98:101], v[130:133], v[48:51]
	v_mfma_f32_16x16x32_bf16 v[44:47], v[90:93], v[138:141], v[44:47]
	v_mfma_f32_16x16x32_bf16 v[40:43], v[98:101], v[138:141], v[40:43]
	v_mfma_f32_16x16x32_bf16 v[36:39], v[90:93], v[146:149], v[36:39]
	v_mfma_f32_16x16x32_bf16 v[32:35], v[98:101], v[146:149], v[32:35]
	v_mfma_f32_16x16x32_bf16 v[28:31], v[102:105], v[118:121], v[28:31]
	v_mfma_f32_16x16x32_bf16 v[24:27], v[110:113], v[118:121], v[24:27]
	v_mfma_f32_16x16x32_bf16 v[20:23], v[102:105], v[126:129], v[20:23]
	v_mfma_f32_16x16x32_bf16 v[16:19], v[110:113], v[126:129], v[16:19]
	v_mfma_f32_16x16x32_bf16 v[12:15], v[102:105], v[134:137], v[12:15]
	v_mfma_f32_16x16x32_bf16 v[8:11], v[110:113], v[134:137], v[8:11]
	v_mfma_f32_16x16x32_bf16 v[4:7], v[102:105], v[142:145], v[4:7]
	v_mfma_f32_16x16x32_bf16 v[0:3], v[110:113], v[142:145], v[0:3]
	v_mfma_f32_16x16x32_bf16 v[28:31], v[106:109], v[122:125], v[28:31]
	v_mfma_f32_16x16x32_bf16 v[24:27], v[114:117], v[122:125], v[24:27]
	v_mfma_f32_16x16x32_bf16 v[20:23], v[106:109], v[130:133], v[20:23]
	v_mfma_f32_16x16x32_bf16 v[16:19], v[114:117], v[130:133], v[16:19]
	v_mfma_f32_16x16x32_bf16 v[12:15], v[106:109], v[138:141], v[12:15]
	v_mfma_f32_16x16x32_bf16 v[8:11], v[114:117], v[138:141], v[8:11]
	v_mfma_f32_16x16x32_bf16 v[4:7], v[106:109], v[146:149], v[4:7]
	v_mfma_f32_16x16x32_bf16 v[0:3], v[114:117], v[146:149], v[0:3]
	s_setprio 1
	s_barrier
	s_add_i32 s14, s14, s16
	s_mov_b32 m0, s14
	s_nop 0
	global_load_lds_dwordx4 v85, s[82:83]
	s_add_i32 m0, s14, 0x2000
	s_add_i32 s14, s15, s16
	global_load_lds_dwordx4 v150, s[82:83]
	s_mov_b32 m0, s14
	s_nop 0
	global_load_lds_dwordx4 v151, s[82:83]
	s_add_i32 m0, s14, 0x2000
	s_nop 0
	global_load_lds_dwordx4 v152, s[82:83]
	s_mov_b32 m0, s17
	s_nop 0
	global_load_lds_dwordx4 v[64:65], off
	s_mov_b32 m0, s18
	s_nop 0
	global_load_lds_dwordx4 v[66:67], off
	s_waitcnt vmcnt(8)
	s_waitcnt lgkmcnt(0)
	s_barrier
	s_setprio 1
	s_setprio 0
	s_setprio 1
	s_setprio 0
	s_barrier
	s_add_i32 s14, 0, 0x18000
	v_add_u32_e32 v85, s14, v83
	s_add_i32 s15, 0, 0x1c000
	ds_read_b128 v[86:89], v85
	ds_read_b128 v[90:93], v85 offset:1024
	ds_read_b128 v[94:97], v85 offset:2048
	ds_read_b128 v[98:101], v85 offset:3072
	v_add_u32_e32 v85, s15, v83
	ds_read_b128 v[102:105], v85
	ds_read_b128 v[106:109], v85 offset:1024
	ds_read_b128 v[110:113], v85 offset:2048
	ds_read_b128 v[114:117], v85 offset:3072
	s_mov_b32 m0, s19
	ds_read_b128 v[118:121], v84 offset:32768
	ds_read_b128 v[122:125], v84 offset:33792
	ds_read_b128 v[126:129], v84 offset:34816
	ds_read_b128 v[130:133], v84 offset:35840
	ds_read_b128 v[134:137], v84 offset:36864
	ds_read_b128 v[138:141], v84 offset:37888
	ds_read_b128 v[142:145], v84 offset:38912
	ds_read_b128 v[146:149], v84 offset:39936
	global_load_lds_dwordx4 v[68:69], off
	s_mov_b32 m0, s20
	s_nop 0
	global_load_lds_dwordx4 v[70:71], off
	s_waitcnt vmcnt(8)
	s_waitcnt lgkmcnt(0)
	s_barrier
; #define G_STAGE_A(bufoff, p0, p1, koff) do { \
;         __builtin_amdgcn_global_load_lds((const unsigned*)(gbase + (size_t)(unsigned)((p0) + (koff) + voffA[0])), (LAS unsigned*)(lds + (bufoff) + ldsw), 16, 0, 0); \
;         __builtin_amdgcn_global_load_lds((const unsigned*)(gbase + (size_t)(unsigned)((p1) + (koff) + voffA[1])), (LAS unsigned*)(lds + (bufoff) + ldsw + 8192), 16, 0, 0); } while (0)
; #define G_STAGE_B(bufoff, p, koff) do { \
;         __builtin_amdgcn_global_load_lds((const unsigned*)(gbase + (size_t)(unsigned)((p) + (koff) + voffB[0])), (LAS unsigned*)(lds + (bufoff) + ldsw), 16, 0, 0); \
;         __builtin_amdgcn_global_load_lds((const unsigned*)(gbase + (size_t)(unsigned)((p) + (koff) + voffB[1])), (LAS unsigned*)(lds + (bufoff) + ldsw + 8192), 16, 0, 0); } while (0)
; #define G_LDA(dst, b, h) do { _Pragma("unroll") for (int m = 0; m < 4; ++m) _Pragma("unroll") for (int k = 0; k < 2; ++k) dst[m][k] = *(const LAS bf16x8*)(lds + G_SA(b, h) + aoff + m * 2048 + k * 1024); } while (0)
; #define G_LDB(dst, b, h) do { _Pragma("unroll") for (int n = 0; n < 2; ++n) _Pragma("unroll") for (int k = 0; k < 2; ++k) dst[n][k] = *(const LAS bf16x8*)(lds + G_SB(b, h) + boff + n * 2048 + k * 1024); } while (0)
; #define G_BAR __builtin_amdgcn_s_barrier()
; template <class Epi>
; DI void gemm_phase(LAS unsigned char* lds, const Sched& S, const Epi& E, const int K) {
;     ...
;             G_LDB(B0, 1, 0); G_LDB(B1, 1, 1); G_SCHED; G_LDA(At, 1, 0); G_STAGE_A(G_SA(0, 1), x2, x3, k2);
;             G_WAIT_V(8); G_WAIT_L(0); G_BAR; G_MMA(0, 0, At, B0); G_MMA(0, 1, At, B1); G_BAR; G_SCHED;
;             G_LDA(At, 1, 1); G_STAGE_B(G_SB(1, 0), xb, kb3); G_STAGE_B(G_SB(1, 1), xb + hstepB, kb3); G_STAGE_A(G_SA(1, 0), x0, x1, k3);
;             G_WAIT_V(8); G_WAIT_L(0); G_BAR; G_MMA(1, 0, At, B0); G_MMA(1, 1, At, B1); G_BAR; G_SCHED;
;     DI void operator()(const f32x4 (&acc)[2][2][4][2], const Unit& u, int wr, int wc, int fr, int fq) const {
;         if (wr != 0) return;
;         const int b = u.z >> 6, k1 = u.z & 63;
; #pragma unroll
;         for (int m = 0; m < 4; ++m) { const int k2 = 16 * m + fr; bf16_t* rowp = MIXCAT + (size_t)(b * 4096 + k1 + 64 * k2) * DM + 1024 + u.pn * 256 + wc * 32 + 8 * fq;
; #pragma unroll
;             for (int bj = 0; bj < 2; ++bj) *(u32x4*)(rowp + bj * 128) = pack8(acc[0][bj][m][0] * 0.015625f, acc[0][bj][m][1] * 0.015625f); }
	s_setprio 0
	s_waitcnt lgkmcnt(0)
	v_mfma_f32_16x16x32_bf16 v[60:63], v[86:89], v[118:121], v[60:63]
	v_mfma_f32_16x16x32_bf16 v[56:59], v[94:97], v[118:121], v[56:59]
	v_mfma_f32_16x16x32_bf16 v[52:55], v[86:89], v[126:129], v[52:55]
	v_mfma_f32_16x16x32_bf16 v[48:51], v[94:97], v[126:129], v[48:51]
	v_mfma_f32_16x16x32_bf16 v[44:47], v[86:89], v[134:137], v[44:47]
	v_mfma_f32_16x16x32_bf16 v[40:43], v[94:97], v[134:137], v[40:43]
	v_mfma_f32_16x16x32_bf16 v[36:39], v[86:89], v[142:145], v[36:39]
	v_mfma_f32_16x16x32_bf16 v[32:35], v[94:97], v[142:145], v[32:35]
	v_mfma_f32_16x16x32_bf16 v[60:63], v[90:93], v[122:125], v[60:63]
	v_mfma_f32_16x16x32_bf16 v[56:59], v[98:101], v[122:125], v[56:59]
	v_mfma_f32_16x16x32_bf16 v[52:55], v[90:93], v[130:133], v[52:55]
	v_mfma_f32_16x16x32_bf16 v[48:51], v[98:101], v[130:133], v[48:51]
	v_mfma_f32_16x16x32_bf16 v[44:47], v[90:93], v[138:141], v[44:47]
	v_mfma_f32_16x16x32_bf16 v[40:43], v[98:101], v[138:141], v[40:43]
	v_mfma_f32_16x16x32_bf16 v[36:39], v[90:93], v[146:149], v[36:39]
	v_mfma_f32_16x16x32_bf16 v[32:35], v[98:101], v[146:149], v[32:35]
	v_mfma_f32_16x16x32_bf16 v[28:31], v[102:105], v[118:121], v[28:31]
	v_mfma_f32_16x16x32_bf16 v[24:27], v[110:113], v[118:121], v[24:27]
	v_mfma_f32_16x16x32_bf16 v[20:23], v[102:105], v[126:129], v[20:23]
	v_mfma_f32_16x16x32_bf16 v[16:19], v[110:113], v[126:129], v[16:19]
	v_mfma_f32_16x16x32_bf16 v[12:15], v[102:105], v[134:137], v[12:15]
	v_mfma_f32_16x16x32_bf16 v[8:11], v[110:113], v[134:137], v[8:11]
	v_mfma_f32_16x16x32_bf16 v[4:7], v[102:105], v[142:145], v[4:7]
	v_mfma_f32_16x16x32_bf16 v[0:3], v[110:113], v[142:145], v[0:3]
	v_mfma_f32_16x16x32_bf16 v[28:31], v[106:109], v[122:125], v[28:31]
	v_mfma_f32_16x16x32_bf16 v[24:27], v[114:117], v[122:125], v[24:27]
	v_mfma_f32_16x16x32_bf16 v[20:23], v[106:109], v[130:133], v[20:23]
	v_mfma_f32_16x16x32_bf16 v[16:19], v[114:117], v[130:133], v[16:19]
	v_mfma_f32_16x16x32_bf16 v[12:15], v[106:109], v[138:141], v[12:15]
	v_mfma_f32_16x16x32_bf16 v[8:11], v[114:117], v[138:141], v[8:11]
	v_mfma_f32_16x16x32_bf16 v[4:7], v[106:109], v[146:149], v[4:7]
	v_mfma_f32_16x16x32_bf16 v[0:3], v[114:117], v[146:149], v[0:3]
	s_setprio 1
	s_barrier
	s_add_i32 s14, s14, s16
	s_mov_b32 m0, s14
	s_nop 0
	global_load_lds_dwordx4 v153, s[82:83]
	s_add_i32 m0, s14, 0x2000
	s_add_i32 s14, s15, s16
	global_load_lds_dwordx4 v154, s[82:83]
	s_mov_b32 m0, s14
	s_nop 0
	global_load_lds_dwordx4 v155, s[82:83]
	s_add_i32 m0, s14, 0x2000
	s_nop 0
	global_load_lds_dwordx4 v156, s[82:83]
	s_mov_b32 m0, s21
	s_nop 0
	global_load_lds_dwordx4 v[72:73], off
	s_mov_b32 m0, s24
	s_nop 0
	global_load_lds_dwordx4 v[74:75], off
	s_waitcnt vmcnt(8)
	s_waitcnt lgkmcnt(0)
	s_barrier
	s_setprio 1
	s_setprio 0
	s_setprio 1
	s_setprio 0
	s_barrier
	s_andn2_b64 vcc, exec, s[12:13]
	s_cbranch_vccnz .LBB0_242
	s_lshl_b32 s15, s25, 6
	s_and_b32 s14, s25, 63
	s_and_b32 s15, s15, 0xfffff000
	s_or_b32 s14, s14, s15
	v_or_b32_e32 v90, s14, v82
	s_lshl_b32 s14, s26, 8
	v_ashrrev_i32_e32 v91, 31, v90
	v_readlane_b32 s44, v254, 30
	s_ashr_i32 s15, s14, 31
	v_lshlrev_b64 v[86:87], 12, v[90:91]
	v_readlane_b32 s45, v254, 31
	s_lshl_b64 s[14:15], s[14:15], 1
	s_mov_b32 s40, 0x3c800000
	v_lshl_add_u64 v[86:87], s[44:45], 0, v[86:87]
	v_lshl_add_u64 v[86:87], v[86:87], 0, s[14:15]
	v_lshl_add_u64 v[86:87], v[86:87], 0, s[48:49]
	v_lshl_add_u64 v[92:93], v[86:87], 0, v[184:185]
	v_pk_mul_f32 v[88:89], v[62:63], s[40:41] op_sel_hi:[1,0]
	v_pk_mul_f32 v[86:87], v[60:61], s[40:41] op_sel_hi:[1,0]
	v_pk_mul_f32 v[94:95], v[58:59], s[40:41] op_sel_hi:[1,0]
	v_pk_mul_f32 v[96:97], v[56:57], s[40:41] op_sel_hi:[1,0]
	v_cvt_pk_bf16_f32 v86, v86, v87
	v_cvt_pk_bf16_f32 v87, v88, v89
	v_cvt_pk_bf16_f32 v88, v96, v97
	v_cvt_pk_bf16_f32 v89, v94, v95
	s_barrier
; DI u32x4 pack8(const f32x4& v0, const f32x4& v1) { u32x4 w; w.x = pk2(v0[0], v0[1]); w.y = pk2(v0[2], v0[3]); w.z = pk2(v1[0], v1[1]); w.w = pk2(v1[2], v1[3]); return w; }
;     DI void operator()(const f32x4 (&acc)[2][2][4][2], const Unit& u, int wr, int wc, int fr, int fq) const {
;     ...
; #pragma unroll
;         for (int m = 0; m < 4; ++m) { const int k2 = 16 * m + fr; bf16_t* rowp = MIXCAT + (size_t)(b * 4096 + k1 + 64 * k2) * DM + 1024 + u.pn * 256 + wc * 32 + 8 * fq;
; #pragma unroll
;             for (int bj = 0; bj < 2; ++bj) *(u32x4*)(rowp + bj * 128) = pack8(acc[0][bj][m][0] * 0.015625f, acc[0][bj][m][1] * 0.015625f); }
	global_store_dwordx4 v[92:93], v[86:89], off offset:2048
	v_pk_mul_f32 v[94:95], v[26:27], s[40:41] op_sel_hi:[1,0]
	v_pk_mul_f32 v[96:97], v[24:25], s[40:41] op_sel_hi:[1,0]
	v_pk_mul_f32 v[88:89], v[30:31], s[40:41] op_sel_hi:[1,0]
	v_pk_mul_f32 v[86:87], v[28:29], s[40:41] op_sel_hi:[1,0]
	s_nop 0
	v_cvt_pk_bf16_f32 v86, v86, v87
	v_cvt_pk_bf16_f32 v87, v88, v89
	v_cvt_pk_bf16_f32 v88, v96, v97
	v_cvt_pk_bf16_f32 v89, v94, v95
	global_store_dwordx4 v[92:93], v[86:89], off offset:2304
	v_pk_mul_f32 v[94:95], v[50:51], s[40:41] op_sel_hi:[1,0]
	v_pk_mul_f32 v[96:97], v[48:49], s[40:41] op_sel_hi:[1,0]
	v_or_b32_e32 v86, 0x400, v90
	v_ashrrev_i32_e32 v87, 31, v86
	v_lshlrev_b64 v[86:87], 12, v[86:87]
	v_lshl_add_u64 v[86:87], s[44:45], 0, v[86:87]
	v_lshl_add_u64 v[86:87], v[86:87], 0, s[14:15]
	v_lshl_add_u64 v[86:87], v[86:87], 0, s[48:49]
	v_lshl_add_u64 v[92:93], v[86:87], 0, v[184:185]
	v_pk_mul_f32 v[88:89], v[54:55], s[40:41] op_sel_hi:[1,0]
	v_pk_mul_f32 v[86:87], v[52:53], s[40:41] op_sel_hi:[1,0]
	s_nop 0
	v_cvt_pk_bf16_f32 v86, v86, v87
	v_cvt_pk_bf16_f32 v87, v88, v89
	v_cvt_pk_bf16_f32 v88, v96, v97
	v_cvt_pk_bf16_f32 v89, v94, v95
	global_store_dwordx4 v[92:93], v[86:89], off offset:2048
	v_pk_mul_f32 v[94:95], v[18:19], s[40:41] op_sel_hi:[1,0]
	v_pk_mul_f32 v[96:97], v[16:17], s[40:41] op_sel_hi:[1,0]
	v_pk_mul_f32 v[88:89], v[22:23], s[40:41] op_sel_hi:[1,0]
	v_pk_mul_f32 v[86:87], v[20:21], s[40:41] op_sel_hi:[1,0]
	s_nop 0
	v_cvt_pk_bf16_f32 v86, v86, v87
	v_cvt_pk_bf16_f32 v87, v88, v89
	v_cvt_pk_bf16_f32 v88, v96, v97
	v_cvt_pk_bf16_f32 v89, v94, v95
	global_store_dwordx4 v[92:93], v[86:89], off offset:2304
	v_pk_mul_f32 v[94:95], v[42:43], s[40:41] op_sel_hi:[1,0]
	v_pk_mul_f32 v[96:97], v[40:41], s[40:41] op_sel_hi:[1,0]
	v_or_b32_e32 v86, 0x800, v90
	v_ashrrev_i32_e32 v87, 31, v86
	v_lshlrev_b64 v[86:87], 12, v[86:87]
	v_lshl_add_u64 v[86:87], s[44:45], 0, v[86:87]
	v_lshl_add_u64 v[86:87], v[86:87], 0, s[14:15]
	v_lshl_add_u64 v[86:87], v[86:87], 0, s[48:49]
	v_lshl_add_u64 v[92:93], v[86:87], 0, v[184:185]
	v_pk_mul_f32 v[88:89], v[46:47], s[40:41] op_sel_hi:[1,0]
	v_pk_mul_f32 v[86:87], v[44:45], s[40:41] op_sel_hi:[1,0]
	s_nop 0
	v_cvt_pk_bf16_f32 v86, v86, v87
	v_cvt_pk_bf16_f32 v87, v88, v89
	v_cvt_pk_bf16_f32 v88, v96, v97
	v_cvt_pk_bf16_f32 v89, v94, v95
	global_store_dwordx4 v[92:93], v[86:89], off offset:2048
	v_pk_mul_f32 v[94:95], v[10:11], s[40:41] op_sel_hi:[1,0]
	v_pk_mul_f32 v[96:97], v[8:9], s[40:41] op_sel_hi:[1,0]
	v_pk_mul_f32 v[88:89], v[14:15], s[40:41] op_sel_hi:[1,0]
	v_pk_mul_f32 v[86:87], v[12:13], s[40:41] op_sel_hi:[1,0]
	s_nop 0
	v_cvt_pk_bf16_f32 v86, v86, v87
	v_cvt_pk_bf16_f32 v87, v88, v89
	v_cvt_pk_bf16_f32 v88, v96, v97
	v_cvt_pk_bf16_f32 v89, v94, v95
	global_store_dwordx4 v[92:93], v[86:89], off offset:2304
	v_pk_mul_f32 v[92:93], v[34:35], s[40:41] op_sel_hi:[1,0]
	v_pk_mul_f32 v[94:95], v[32:33], s[40:41] op_sel_hi:[1,0]
	v_or_b32_e32 v86, 0xc00, v90
	v_ashrrev_i32_e32 v87, 31, v86
	v_lshlrev_b64 v[86:87], 12, v[86:87]
	v_lshl_add_u64 v[86:87], s[44:45], 0, v[86:87]
	v_lshl_add_u64 v[86:87], v[86:87], 0, s[14:15]
	v_lshl_add_u64 v[86:87], v[86:87], 0, s[48:49]
	v_lshl_add_u64 v[90:91], v[86:87], 0, v[184:185]
	v_pk_mul_f32 v[88:89], v[38:39], s[40:41] op_sel_hi:[1,0]
	v_pk_mul_f32 v[86:87], v[36:37], s[40:41] op_sel_hi:[1,0]
	s_nop 0
	v_cvt_pk_bf16_f32 v86, v86, v87
	v_cvt_pk_bf16_f32 v87, v88, v89
	v_cvt_pk_bf16_f32 v88, v94, v95
	v_cvt_pk_bf16_f32 v89, v92, v93
	global_store_dwordx4 v[90:91], v[86:89], off offset:2048
	v_pk_mul_f32 v[92:93], v[2:3], s[40:41] op_sel_hi:[1,0]
	v_pk_mul_f32 v[94:95], v[0:1], s[40:41] op_sel_hi:[1,0]
	v_pk_mul_f32 v[88:89], v[6:7], s[40:41] op_sel_hi:[1,0]
	v_pk_mul_f32 v[86:87], v[4:5], s[40:41] op_sel_hi:[1,0]
	s_nop 0
	v_cvt_pk_bf16_f32 v86, v86, v87
	v_cvt_pk_bf16_f32 v87, v88, v89
	v_cvt_pk_bf16_f32 v88, v94, v95
	v_cvt_pk_bf16_f32 v89, v92, v93
	global_store_dwordx4 v[90:91], v[86:89], off offset:2304
	s_andn2_b64 vcc, exec, s[10:11]
	s_cbranch_vccnz .LBB0_233
	s_branch .LBB0_243

; #define G_STAGE_A(bufoff, p0, p1, koff) do { \
;         __builtin_amdgcn_global_load_lds((const unsigned*)(gbase + (size_t)(unsigned)((p0) + (koff) + voffA[0])), (LAS unsigned*)(lds + (bufoff) + ldsw), 16, 0, 0); \
;         __builtin_amdgcn_global_load_lds((const unsigned*)(gbase + (size_t)(unsigned)((p1) + (koff) + voffA[1])), (LAS unsigned*)(lds + (bufoff) + ldsw + 8192), 16, 0, 0); } while (0)
; #define G_STAGE_B(bufoff, p, koff) do { \
;         __builtin_amdgcn_global_load_lds((const unsigned*)(gbase + (size_t)(unsigned)((p) + (koff) + voffB[0])), (LAS unsigned*)(lds + (bufoff) + ldsw), 16, 0, 0); \
;         __builtin_amdgcn_global_load_lds((const unsigned*)(gbase + (size_t)(unsigned)((p) + (koff) + voffB[1])), (LAS unsigned*)(lds + (bufoff) + ldsw + 8192), 16, 0, 0); } while (0)
; #define G_LDA(dst, b, h) do { _Pragma("unroll") for (int m = 0; m < 4; ++m) _Pragma("unroll") for (int k = 0; k < 2; ++k) dst[m][k] = *(const LAS bf16x8*)(lds + G_SA(b, h) + aoff + m * 2048 + k * 1024); } while (0)
; #define G_LDB(dst, b, h) do { _Pragma("unroll") for (int n = 0; n < 2; ++n) _Pragma("unroll") for (int k = 0; k < 2; ++k) dst[n][k] = *(const LAS bf16x8*)(lds + G_SB(b, h) + boff + n * 2048 + k * 1024); } while (0)
; #define G_MMA(ai, bj, At, Bt) do { __builtin_amdgcn_s_setprio(1); _Pragma("unroll") for (int m = 0; m < 4; ++m) _Pragma("unroll") for (int n = 0; n < 2; ++n) _Pragma("unroll") for (int k = 0; k < 2; ++k) \
;         acc[ai][bj][m][n] = __builtin_amdgcn_mfma_f32_16x16x32_bf16(Bt[n][k], At[m][k], acc[ai][bj][m][n], 0, 0, 0); __builtin_amdgcn_s_setprio(0); } while (0)
; #define G_WAIT_V(n) asm volatile("s_waitcnt vmcnt(" #n ")" ::: "memory")
; #define G_WAIT_L(n) asm volatile("s_waitcnt lgkmcnt(" #n ")" ::: "memory")
; #define G_BAR __builtin_amdgcn_s_barrier()
; template <class Epi>
; DI void gemm_phase(LAS unsigned char* lds, const Sched& S, const Epi& E, const int K) {
;     ...
;             G_LDB(B0, 0, 0); G_LDB(B1, 0, 1); G_SCHED; G_LDA(At, 0, 0); G_STAGE_A(G_SA(1, 1), cur.a2, cur.a3, k1);
;             G_WAIT_V(8); G_WAIT_L(0); G_BAR; G_MMA(0, 0, At, B0); G_MMA(0, 1, At, B1); G_BAR; G_SCHED;
;             G_LDA(At, 0, 1); G_STAGE_B(G_SB(0, 0), xb, kb2); G_STAGE_B(G_SB(0, 1), xb + hstepB, kb2); G_STAGE_A(G_SA(0, 0), x0, x1, k2);
;             G_WAIT_V(8); G_WAIT_L(0); G_BAR; G_MMA(1, 0, At, B0); G_MMA(1, 1, At, B1); G_BAR; G_SCHED;
.LBB0_261:
	s_add_i32 s12, s13, 0x8000
	v_add_u32_e32 v182, s12, v170
	v_add_u32_e32 v183, s12, v171
	s_add_i32 s12, s13, 0x2000
	v_add_u32_e32 v226, s12, v170
	v_add_u32_e32 v229, s12, v171
	s_add_i32 s12, s13, 0xa000
	v_add_u32_e32 v168, s13, v170
	v_add_u32_e32 v169, s13, v171
	v_add_u32_e32 v233, s12, v170
	v_add_u32_e32 v250, s12, v171
	s_add_i32 s12, 0, 0x10000
	s_add_i32 s13, 0, 0x14000
	v_add_u32_e32 v164, s12, v173
	v_add_u32_e32 v202, s13, v173
	ds_read_b128 v[152:155], v164
	ds_read_b128 v[156:159], v164 offset:1024
	ds_read_b128 v[160:163], v164 offset:2048
	ds_read_b128 v[164:167], v164 offset:3072
	ds_read_b128 v[178:181], v202
	ds_read_b128 v[194:197], v202 offset:1024
	ds_read_b128 v[198:201], v202 offset:2048
	ds_read_b128 v[202:205], v202 offset:3072
	s_add_i32 m0, s17, 0xc000
	ds_read_b128 v[206:209], v177
	ds_read_b128 v[210:213], v177 offset:1024
	ds_read_b128 v[214:217], v177 offset:2048
	ds_read_b128 v[218:221], v177 offset:3072
	ds_read_b128 v[222:225], v177 offset:4096
	ds_read_b128 v[234:237], v177 offset:5120
	ds_read_b128 v[242:245], v177 offset:6144
	ds_read_b128 v[246:249], v177 offset:7168
	global_load_lds_dwordx4 v[148:149], off
	s_add_i32 m0, s17, 0xe000
	s_nop 0
	global_load_lds_dwordx4 v[150:151], off
	s_waitcnt vmcnt(8)
	s_waitcnt lgkmcnt(0)
	s_barrier
	s_setprio 0
	s_waitcnt lgkmcnt(0)
	v_mfma_f32_16x16x32_bf16 v[124:127], v[152:155], v[206:209], v[124:127]
	v_mfma_f32_16x16x32_bf16 v[120:123], v[160:163], v[206:209], v[120:123]
	v_mfma_f32_16x16x32_bf16 v[116:119], v[152:155], v[214:217], v[116:119]
	v_mfma_f32_16x16x32_bf16 v[112:115], v[160:163], v[214:217], v[112:115]
	v_mfma_f32_16x16x32_bf16 v[108:111], v[152:155], v[222:225], v[108:111]
	v_mfma_f32_16x16x32_bf16 v[104:107], v[160:163], v[222:225], v[104:107]
	v_mfma_f32_16x16x32_bf16 v[100:103], v[152:155], v[242:245], v[100:103]
	v_mfma_f32_16x16x32_bf16 v[96:99], v[160:163], v[242:245], v[96:99]
	v_mfma_f32_16x16x32_bf16 v[124:127], v[156:159], v[210:213], v[124:127]
	v_mfma_f32_16x16x32_bf16 v[120:123], v[164:167], v[210:213], v[120:123]
	v_mfma_f32_16x16x32_bf16 v[116:119], v[156:159], v[218:221], v[116:119]
	v_mfma_f32_16x16x32_bf16 v[112:115], v[164:167], v[218:221], v[112:115]
	v_mfma_f32_16x16x32_bf16 v[108:111], v[156:159], v[234:237], v[108:111]
	v_mfma_f32_16x16x32_bf16 v[104:107], v[164:167], v[234:237], v[104:107]
	v_mfma_f32_16x16x32_bf16 v[100:103], v[156:159], v[246:249], v[100:103]
	v_mfma_f32_16x16x32_bf16 v[96:99], v[164:167], v[246:249], v[96:99]
	v_mfma_f32_16x16x32_bf16 v[92:95], v[178:181], v[206:209], v[92:95]
	v_mfma_f32_16x16x32_bf16 v[88:91], v[198:201], v[206:209], v[88:91]
	v_mfma_f32_16x16x32_bf16 v[84:87], v[178:181], v[214:217], v[84:87]
	v_mfma_f32_16x16x32_bf16 v[80:83], v[198:201], v[214:217], v[80:83]
	v_mfma_f32_16x16x32_bf16 v[76:79], v[178:181], v[222:225], v[76:79]
	v_mfma_f32_16x16x32_bf16 v[72:75], v[198:201], v[222:225], v[72:75]
	v_mfma_f32_16x16x32_bf16 v[68:71], v[178:181], v[242:245], v[68:71]
	v_mfma_f32_16x16x32_bf16 v[64:67], v[198:201], v[242:245], v[64:67]
	v_mfma_f32_16x16x32_bf16 v[92:95], v[194:197], v[210:213], v[92:95]
	v_mfma_f32_16x16x32_bf16 v[88:91], v[202:205], v[210:213], v[88:91]
	v_mfma_f32_16x16x32_bf16 v[84:87], v[194:197], v[218:221], v[84:87]
	v_mfma_f32_16x16x32_bf16 v[80:83], v[202:205], v[218:221], v[80:83]
	v_mfma_f32_16x16x32_bf16 v[76:79], v[194:197], v[234:237], v[76:79]
	v_mfma_f32_16x16x32_bf16 v[72:75], v[202:205], v[234:237], v[72:75]
	v_mfma_f32_16x16x32_bf16 v[68:71], v[194:197], v[246:249], v[68:71]
	v_mfma_f32_16x16x32_bf16 v[64:67], v[202:205], v[246:249], v[64:67]
	s_setprio 1
	s_barrier
	s_add_i32 s12, s12, s16
	s_mov_b32 m0, s12
	ds_read_b128 v[206:209], v177 offset:16384
	ds_read_b128 v[210:213], v177 offset:17408
	ds_read_b128 v[214:217], v177 offset:18432
	ds_read_b128 v[218:221], v177 offset:19456
	ds_read_b128 v[222:225], v177 offset:20480
	ds_read_b128 v[234:237], v177 offset:21504
	ds_read_b128 v[242:245], v177 offset:22528
	ds_read_b128 v[246:249], v177 offset:23552
	global_load_lds_dwordx4 v168, s[82:83]
	s_add_i32 m0, s12, 0x2000
	s_add_i32 s12, s13, s16
	global_load_lds_dwordx4 v169, s[82:83]
	s_mov_b32 m0, s12
	s_nop 0
	global_load_lds_dwordx4 v182, s[82:83]
	s_add_i32 m0, s12, 0x2000
	s_nop 0
	global_load_lds_dwordx4 v183, s[82:83]
	s_mov_b32 m0, s17
	s_nop 0
	global_load_lds_dwordx4 v[128:129], off
	s_mov_b32 m0, s18
	s_nop 0
	global_load_lds_dwordx4 v[130:131], off
	s_waitcnt vmcnt(8)
	s_waitcnt lgkmcnt(0)
	s_barrier
	s_setprio 0
	s_waitcnt lgkmcnt(0)
	v_mfma_f32_16x16x32_bf16 v[60:63], v[152:155], v[206:209], v[60:63]
	v_mfma_f32_16x16x32_bf16 v[56:59], v[160:163], v[206:209], v[56:59]
	v_mfma_f32_16x16x32_bf16 v[52:55], v[152:155], v[214:217], v[52:55]
	v_mfma_f32_16x16x32_bf16 v[48:51], v[160:163], v[214:217], v[48:51]
	v_mfma_f32_16x16x32_bf16 v[44:47], v[152:155], v[222:225], v[44:47]
	v_mfma_f32_16x16x32_bf16 v[40:43], v[160:163], v[222:225], v[40:43]
	v_mfma_f32_16x16x32_bf16 v[36:39], v[152:155], v[242:245], v[36:39]
	v_mfma_f32_16x16x32_bf16 v[32:35], v[160:163], v[242:245], v[32:35]
	v_mfma_f32_16x16x32_bf16 v[60:63], v[156:159], v[210:213], v[60:63]
	v_mfma_f32_16x16x32_bf16 v[56:59], v[164:167], v[210:213], v[56:59]
	v_mfma_f32_16x16x32_bf16 v[52:55], v[156:159], v[218:221], v[52:55]
	v_mfma_f32_16x16x32_bf16 v[48:51], v[164:167], v[218:221], v[48:51]
	v_mfma_f32_16x16x32_bf16 v[44:47], v[156:159], v[234:237], v[44:47]
	v_mfma_f32_16x16x32_bf16 v[40:43], v[164:167], v[234:237], v[40:43]
	v_mfma_f32_16x16x32_bf16 v[36:39], v[156:159], v[246:249], v[36:39]
	v_mfma_f32_16x16x32_bf16 v[32:35], v[164:167], v[246:249], v[32:35]
	v_mfma_f32_16x16x32_bf16 v[28:31], v[178:181], v[206:209], v[28:31]
	v_mfma_f32_16x16x32_bf16 v[24:27], v[198:201], v[206:209], v[24:27]
	v_mfma_f32_16x16x32_bf16 v[20:23], v[178:181], v[214:217], v[20:23]
	v_mfma_f32_16x16x32_bf16 v[16:19], v[198:201], v[214:217], v[16:19]
	v_mfma_f32_16x16x32_bf16 v[12:15], v[178:181], v[222:225], v[12:15]
	v_mfma_f32_16x16x32_bf16 v[8:11], v[198:201], v[222:225], v[8:11]
	v_mfma_f32_16x16x32_bf16 v[4:7], v[178:181], v[242:245], v[4:7]
	v_mfma_f32_16x16x32_bf16 v[0:3], v[198:201], v[242:245], v[0:3]
	v_mfma_f32_16x16x32_bf16 v[28:31], v[194:197], v[210:213], v[28:31]
	v_mfma_f32_16x16x32_bf16 v[24:27], v[202:205], v[210:213], v[24:27]
	v_mfma_f32_16x16x32_bf16 v[20:23], v[194:197], v[218:221], v[20:23]
	v_mfma_f32_16x16x32_bf16 v[16:19], v[202:205], v[218:221], v[16:19]
	v_mfma_f32_16x16x32_bf16 v[12:15], v[194:197], v[234:237], v[12:15]
	v_mfma_f32_16x16x32_bf16 v[8:11], v[202:205], v[234:237], v[8:11]
	v_mfma_f32_16x16x32_bf16 v[4:7], v[194:197], v[246:249], v[4:7]
	v_mfma_f32_16x16x32_bf16 v[0:3], v[202:205], v[246:249], v[0:3]
	s_setprio 1
	s_barrier
; #define G_STAGE_A(bufoff, p0, p1, koff) do { \
;         __builtin_amdgcn_global_load_lds((const unsigned*)(gbase + (size_t)(unsigned)((p0) + (koff) + voffA[0])), (LAS unsigned*)(lds + (bufoff) + ldsw), 16, 0, 0); \
;         __builtin_amdgcn_global_load_lds((const unsigned*)(gbase + (size_t)(unsigned)((p1) + (koff) + voffA[1])), (LAS unsigned*)(lds + (bufoff) + ldsw + 8192), 16, 0, 0); } while (0)
; #define G_STAGE_B(bufoff, p, koff) do { \
;         __builtin_amdgcn_global_load_lds((const unsigned*)(gbase + (size_t)(unsigned)((p) + (koff) + voffB[0])), (LAS unsigned*)(lds + (bufoff) + ldsw), 16, 0, 0); \
;         __builtin_amdgcn_global_load_lds((const unsigned*)(gbase + (size_t)(unsigned)((p) + (koff) + voffB[1])), (LAS unsigned*)(lds + (bufoff) + ldsw + 8192), 16, 0, 0); } while (0)
; #define G_LDA(dst, b, h) do { _Pragma("unroll") for (int m = 0; m < 4; ++m) _Pragma("unroll") for (int k = 0; k < 2; ++k) dst[m][k] = *(const LAS bf16x8*)(lds + G_SA(b, h) + aoff + m * 2048 + k * 1024); } while (0)
; #define G_LDB(dst, b, h) do { _Pragma("unroll") for (int n = 0; n < 2; ++n) _Pragma("unroll") for (int k = 0; k < 2; ++k) dst[n][k] = *(const LAS bf16x8*)(lds + G_SB(b, h) + boff + n * 2048 + k * 1024); } while (0)
; #define G_MMA(ai, bj, At, Bt) do { __builtin_amdgcn_s_setprio(1); _Pragma("unroll") for (int m = 0; m < 4; ++m) _Pragma("unroll") for (int n = 0; n < 2; ++n) _Pragma("unroll") for (int k = 0; k < 2; ++k) \
;         acc[ai][bj][m][n] = __builtin_amdgcn_mfma_f32_16x16x32_bf16(Bt[n][k], At[m][k], acc[ai][bj][m][n], 0, 0, 0); __builtin_amdgcn_s_setprio(0); } while (0)
; #define G_WAIT_V(n) asm volatile("s_waitcnt vmcnt(" #n ")" ::: "memory")
; #define G_WAIT_L(n) asm volatile("s_waitcnt lgkmcnt(" #n ")" ::: "memory")
; #define G_BAR __builtin_amdgcn_s_barrier()
; template <class Epi>
; DI void gemm_phase(LAS unsigned char* lds, const Sched& S, const Epi& E, const int K) {
;     ...
;             G_LDB(B0, 1, 0); G_LDB(B1, 1, 1); G_SCHED; G_LDA(At, 1, 0); G_STAGE_A(G_SA(0, 1), x2, x3, k2);
;             G_WAIT_V(8); G_WAIT_L(0); G_BAR; G_MMA(0, 0, At, B0); G_MMA(0, 1, At, B1); G_BAR; G_SCHED;
;             G_LDA(At, 1, 1); G_STAGE_B(G_SB(1, 0), xb, kb3); G_STAGE_B(G_SB(1, 1), xb + hstepB, kb3); G_STAGE_A(G_SA(1, 0), x0, x1, k3);
;             G_WAIT_V(8); G_WAIT_L(0); G_BAR; G_MMA(1, 0, At, B0); G_MMA(1, 1, At, B1); G_BAR; G_SCHED;
	s_add_i32 s12, 0, 0x18000
	s_add_i32 s13, 0, 0x1c000
	v_add_u32_e32 v164, s12, v173
	v_add_u32_e32 v168, s13, v173
	ds_read_b128 v[152:155], v164
	ds_read_b128 v[156:159], v164 offset:1024
	ds_read_b128 v[160:163], v164 offset:2048
	ds_read_b128 v[164:167], v164 offset:3072
	ds_read_b128 v[178:181], v168
	ds_read_b128 v[194:197], v168 offset:1024
	ds_read_b128 v[198:201], v168 offset:2048
	ds_read_b128 v[202:205], v168 offset:3072
	s_mov_b32 m0, s19
	ds_read_b128 v[206:209], v177 offset:32768
	ds_read_b128 v[210:213], v177 offset:33792
	ds_read_b128 v[214:217], v177 offset:34816
	ds_read_b128 v[218:221], v177 offset:35840
	ds_read_b128 v[222:225], v177 offset:36864
	ds_read_b128 v[234:237], v177 offset:37888
	ds_read_b128 v[242:245], v177 offset:38912
	ds_read_b128 v[246:249], v177 offset:39936
	global_load_lds_dwordx4 v[132:133], off
	s_mov_b32 m0, s20
	s_nop 0
	global_load_lds_dwordx4 v[134:135], off
	s_waitcnt vmcnt(8)
	s_waitcnt lgkmcnt(0)
	s_barrier
	s_setprio 0
	s_waitcnt lgkmcnt(0)
	v_mfma_f32_16x16x32_bf16 v[124:127], v[152:155], v[206:209], v[124:127]
	v_mfma_f32_16x16x32_bf16 v[120:123], v[160:163], v[206:209], v[120:123]
	v_mfma_f32_16x16x32_bf16 v[116:119], v[152:155], v[214:217], v[116:119]
	v_mfma_f32_16x16x32_bf16 v[112:115], v[160:163], v[214:217], v[112:115]
	v_mfma_f32_16x16x32_bf16 v[108:111], v[152:155], v[222:225], v[108:111]
	v_mfma_f32_16x16x32_bf16 v[104:107], v[160:163], v[222:225], v[104:107]
	v_mfma_f32_16x16x32_bf16 v[100:103], v[152:155], v[242:245], v[100:103]
	v_mfma_f32_16x16x32_bf16 v[96:99], v[160:163], v[242:245], v[96:99]
	v_mfma_f32_16x16x32_bf16 v[124:127], v[156:159], v[210:213], v[124:127]
	v_mfma_f32_16x16x32_bf16 v[120:123], v[164:167], v[210:213], v[120:123]
	v_mfma_f32_16x16x32_bf16 v[116:119], v[156:159], v[218:221], v[116:119]
	v_mfma_f32_16x16x32_bf16 v[112:115], v[164:167], v[218:221], v[112:115]
	v_mfma_f32_16x16x32_bf16 v[108:111], v[156:159], v[234:237], v[108:111]
	v_mfma_f32_16x16x32_bf16 v[104:107], v[164:167], v[234:237], v[104:107]
	v_mfma_f32_16x16x32_bf16 v[100:103], v[156:159], v[246:249], v[100:103]
	v_mfma_f32_16x16x32_bf16 v[96:99], v[164:167], v[246:249], v[96:99]
	v_mfma_f32_16x16x32_bf16 v[92:95], v[178:181], v[206:209], v[92:95]
	v_mfma_f32_16x16x32_bf16 v[88:91], v[198:201], v[206:209], v[88:91]
	v_mfma_f32_16x16x32_bf16 v[84:87], v[178:181], v[214:217], v[84:87]
	v_mfma_f32_16x16x32_bf16 v[80:83], v[198:201], v[214:217], v[80:83]
	v_mfma_f32_16x16x32_bf16 v[76:79], v[178:181], v[222:225], v[76:79]
	v_mfma_f32_16x16x32_bf16 v[72:75], v[198:201], v[222:225], v[72:75]
	v_mfma_f32_16x16x32_bf16 v[68:71], v[178:181], v[242:245], v[68:71]
	v_mfma_f32_16x16x32_bf16 v[64:67], v[198:201], v[242:245], v[64:67]
	v_mfma_f32_16x16x32_bf16 v[92:95], v[194:197], v[210:213], v[92:95]
	v_mfma_f32_16x16x32_bf16 v[88:91], v[202:205], v[210:213], v[88:91]
	v_mfma_f32_16x16x32_bf16 v[84:87], v[194:197], v[218:221], v[84:87]
	v_mfma_f32_16x16x32_bf16 v[80:83], v[202:205], v[218:221], v[80:83]
	v_mfma_f32_16x16x32_bf16 v[76:79], v[194:197], v[234:237], v[76:79]
	v_mfma_f32_16x16x32_bf16 v[72:75], v[202:205], v[234:237], v[72:75]
	v_mfma_f32_16x16x32_bf16 v[68:71], v[194:197], v[246:249], v[68:71]
	v_mfma_f32_16x16x32_bf16 v[64:67], v[202:205], v[246:249], v[64:67]
	s_setprio 1
	s_barrier
	s_add_i32 s12, s12, s16
	s_mov_b32 m0, s12
	ds_read_b128 v[206:209], v177 offset:49152
	ds_read_b128 v[210:213], v177 offset:50176
	ds_read_b128 v[214:217], v177 offset:51200
	ds_read_b128 v[218:221], v177 offset:52224
	ds_read_b128 v[222:225], v177 offset:53248
	ds_read_b128 v[234:237], v177 offset:54272
	ds_read_b128 v[242:245], v177 offset:55296
	ds_read_b128 v[246:249], v177 offset:56320
	global_load_lds_dwordx4 v226, s[82:83]
	s_add_i32 m0, s12, 0x2000
	s_add_i32 s12, s13, s16
	global_load_lds_dwordx4 v229, s[82:83]
	s_mov_b32 m0, s12
	s_nop 0
	global_load_lds_dwordx4 v233, s[82:83]
	s_add_i32 m0, s12, 0x2000
	s_nop 0
	global_load_lds_dwordx4 v250, s[82:83]
	s_mov_b32 m0, s21
	s_nop 0
	global_load_lds_dwordx4 v[136:137], off
	s_mov_b32 m0, s24
	s_nop 0
	global_load_lds_dwordx4 v[138:139], off
	s_waitcnt vmcnt(8)
	s_waitcnt lgkmcnt(0)
	s_barrier
	s_setprio 0
	s_waitcnt lgkmcnt(0)
	v_mfma_f32_16x16x32_bf16 v[60:63], v[152:155], v[206:209], v[60:63]
	v_mfma_f32_16x16x32_bf16 v[56:59], v[160:163], v[206:209], v[56:59]
	v_mfma_f32_16x16x32_bf16 v[52:55], v[152:155], v[214:217], v[52:55]
	v_mfma_f32_16x16x32_bf16 v[48:51], v[160:163], v[214:217], v[48:51]
	v_mfma_f32_16x16x32_bf16 v[44:47], v[152:155], v[222:225], v[44:47]
	v_mfma_f32_16x16x32_bf16 v[40:43], v[160:163], v[222:225], v[40:43]
	v_mfma_f32_16x16x32_bf16 v[36:39], v[152:155], v[242:245], v[36:39]
	v_mfma_f32_16x16x32_bf16 v[32:35], v[160:163], v[242:245], v[32:35]
	v_mfma_f32_16x16x32_bf16 v[60:63], v[156:159], v[210:213], v[60:63]
	v_mfma_f32_16x16x32_bf16 v[56:59], v[164:167], v[210:213], v[56:59]
	v_mfma_f32_16x16x32_bf16 v[52:55], v[156:159], v[218:221], v[52:55]
	v_mfma_f32_16x16x32_bf16 v[48:51], v[164:167], v[218:221], v[48:51]
	v_mfma_f32_16x16x32_bf16 v[44:47], v[156:159], v[234:237], v[44:47]
	v_mfma_f32_16x16x32_bf16 v[40:43], v[164:167], v[234:237], v[40:43]
	v_mfma_f32_16x16x32_bf16 v[36:39], v[156:159], v[246:249], v[36:39]
	v_mfma_f32_16x16x32_bf16 v[32:35], v[164:167], v[246:249], v[32:35]
	v_mfma_f32_16x16x32_bf16 v[28:31], v[178:181], v[206:209], v[28:31]
	v_mfma_f32_16x16x32_bf16 v[24:27], v[198:201], v[206:209], v[24:27]
	v_mfma_f32_16x16x32_bf16 v[20:23], v[178:181], v[214:217], v[20:23]
	v_mfma_f32_16x16x32_bf16 v[16:19], v[198:201], v[214:217], v[16:19]
	v_mfma_f32_16x16x32_bf16 v[12:15], v[178:181], v[222:225], v[12:15]
	v_mfma_f32_16x16x32_bf16 v[8:11], v[198:201], v[222:225], v[8:11]
	v_mfma_f32_16x16x32_bf16 v[4:7], v[178:181], v[242:245], v[4:7]
	v_mfma_f32_16x16x32_bf16 v[0:3], v[198:201], v[242:245], v[0:3]
	v_mfma_f32_16x16x32_bf16 v[28:31], v[194:197], v[210:213], v[28:31]
	v_mfma_f32_16x16x32_bf16 v[24:27], v[202:205], v[210:213], v[24:27]
	v_mfma_f32_16x16x32_bf16 v[20:23], v[194:197], v[218:221], v[20:23]
	v_mfma_f32_16x16x32_bf16 v[16:19], v[202:205], v[218:221], v[16:19]
	v_mfma_f32_16x16x32_bf16 v[12:15], v[194:197], v[234:237], v[12:15]
	v_mfma_f32_16x16x32_bf16 v[8:11], v[202:205], v[234:237], v[8:11]
	v_mfma_f32_16x16x32_bf16 v[4:7], v[194:197], v[246:249], v[4:7]
	v_mfma_f32_16x16x32_bf16 v[0:3], v[202:205], v[246:249], v[0:3]
	s_setprio 1
	s_barrier
; DI u32x4 pack8(const f32x4& v0, const f32x4& v1) { u32x4 w; w.x = pk2(v0[0], v0[1]); w.y = pk2(v0[2], v0[3]); w.z = pk2(v1[0], v1[1]); w.w = pk2(v1[2], v1[3]); return w; }
;     DI void operator()(const f32x4 (&acc)[2][2][4][2], const Unit& u, int wr, int wc, int fr, int fq) const {
;         if (wr != 0) return;
; #pragma unroll
;         for (int m = 0; m < 4; ++m) {
;             const int k1 = 16 * m + fr;
; #pragma unroll
;             for (int bj = 0; bj < 2; ++bj) {
;                 const int j0 = 128 * bj + 32 * wc + 8 * fq, ge = 4 * u.pn + (j0 >> 6), nl0 = j0 & 63;
;                 const f32x4* tw = (const f32x4*)(TW + (size_t)(k1 * 64 + nl0) * 2);
;                 f32x4 yr[2], yi[2];
; #pragma unroll
;                 for (int n = 0; n < 2; ++n) {
;                     const f32x4 t0 = tw[2 * n], t1 = tw[2 * n + 1];
;                     const f32x4 c = {t0.x, t0.z, t1.x, t1.z}, s = {t0.y, t0.w, t1.y, t1.w};
;                     const f32x4 r = acc[0][bj][m][n], i = acc[1][bj][m][n];
;                     yr[n] = c * r + s * i; yi[n] = c * i - s * r;
;                 }
;                 bf16_t* dst = YP + ((((size_t)(u.z * 64 + k1)) * 1024 + ge) * 2) * 64 + nl0;
;                 *(u32x4*)dst = pack8(yr[0], yr[1]); *(u32x4*)(dst + 64) = pack8(yi[0], yi[1]);
	s_andn2_b64 vcc, exec, s[10:11]
	s_cbranch_vccnz .LBB0_263
	s_lshl_b32 s44, s26, 6
	v_or_b32_e32 v152, s44, v172
	v_ashrrev_i32_e32 v153, 31, v152
	s_barrier
	v_lshlrev_b64 v[182:183], 18, v[152:153]
	global_load_dwordx4 v[178:181], v[140:141], off offset:32
	global_load_dwordx4 v[162:165], v[140:141], off offset:48
	global_load_dwordx4 v[152:155], v[140:141], off
	global_load_dwordx4 v[156:159], v[140:141], off offset:16
	s_lshl_b32 s12, s27, 2
	s_or_b32 s14, s12, s25
	v_readlane_b32 s46, v254, 39
	s_ashr_i32 s15, s14, 31
	v_readlane_b32 s47, v254, 40
	s_lshl_b64 s[12:13], s[14:15], 8
	s_or_b32 s14, s14, 2
	s_ashr_i32 s15, s14, 31
	s_lshl_b64 s[14:15], s[14:15], 8
	s_waitcnt vmcnt(0)
	v_mov_b32_e32 v168, v153
	v_mov_b32_e32 v166, v157
	v_mov_b32_e32 v167, v159
	v_mov_b32_e32 v169, v155
	v_pk_mul_f32 v[160:161], v[62:63], v[166:167]
	v_pk_mul_f32 v[194:195], v[60:61], v[168:169]
	v_mov_b32_e32 v157, v158
	v_mov_b32_e32 v153, v154
	v_pk_mul_f32 v[154:155], v[126:127], v[166:167]
	v_pk_mul_f32 v[166:167], v[124:125], v[168:169]
	v_pk_fma_f32 v[158:159], v[126:127], v[156:157], v[160:161]
	v_pk_fma_f32 v[160:161], v[124:125], v[152:153], v[194:195]
	v_pk_fma_f32 v[154:155], v[62:63], v[156:157], v[154:155] neg_lo:[0,0,1] neg_hi:[0,0,1]
	v_pk_fma_f32 v[156:157], v[60:61], v[152:153], v[166:167] neg_lo:[0,0,1] neg_hi:[0,0,1]
	v_mov_b32_e32 v152, v163
	v_mov_b32_e32 v153, v165
	v_pk_mul_f32 v[166:167], v[58:59], v[152:153]
	v_mov_b32_e32 v194, v179
	v_mov_b32_e32 v195, v181
	v_mov_b32_e32 v163, v164
	v_pk_mul_f32 v[152:153], v[122:123], v[152:153]
	v_pk_mul_f32 v[168:169], v[56:57], v[194:195]
	v_pk_fma_f32 v[166:167], v[122:123], v[162:163], v[166:167]
	v_mov_b32_e32 v179, v180
	v_pk_mul_f32 v[164:165], v[120:121], v[194:195]
	v_pk_fma_f32 v[162:163], v[58:59], v[162:163], v[152:153] neg_lo:[0,0,1] neg_hi:[0,0,1]
	v_lshl_add_u64 v[152:153], s[46:47], 0, v[182:183]
	v_pk_fma_f32 v[168:169], v[120:121], v[178:179], v[168:169]
	v_pk_fma_f32 v[164:165], v[56:57], v[178:179], v[164:165] neg_lo:[0,0,1] neg_hi:[0,0,1]
	v_lshl_add_u64 v[178:179], v[152:153], 0, s[12:13]
	v_lshl_add_u64 v[182:183], v[178:179], 0, v[184:185]
	v_cvt_pk_bf16_f32 v178, v160, v161
	v_cvt_pk_bf16_f32 v179, v158, v159
	v_cvt_pk_bf16_f32 v180, v168, v169
	v_cvt_pk_bf16_f32 v181, v166, v167
	v_cvt_pk_bf16_f32 v156, v156, v157
	v_cvt_pk_bf16_f32 v157, v154, v155
	v_cvt_pk_bf16_f32 v158, v164, v165
	v_cvt_pk_bf16_f32 v159, v162, v163
	global_store_dwordx4 v[182:183], v[178:181], off
	global_store_dwordx4 v[182:183], v[156:159], off offset:128
	global_load_dwordx4 v[178:181], v[140:141], off offset:32
	s_nop 0
	global_load_dwordx4 v[162:165], v[140:141], off offset:48
	global_load_dwordx4 v[166:169], v[140:141], off
	global_load_dwordx4 v[154:157], v[140:141], off offset:16
	v_lshl_add_u64 v[152:153], v[152:153], 0, s[14:15]
	s_waitcnt vmcnt(1)
	v_mov_b32_e32 v194, v167
	s_waitcnt vmcnt(0)
	v_mov_b32_e32 v182, v155
	v_mov_b32_e32 v183, v157
	v_mov_b32_e32 v195, v169
	v_pk_mul_f32 v[158:159], v[30:31], v[182:183]
	v_pk_mul_f32 v[160:161], v[28:29], v[194:195]
	v_mov_b32_e32 v155, v156
	v_mov_b32_e32 v167, v168
	v_pk_mul_f32 v[156:157], v[94:95], v[182:183]
	v_pk_mul_f32 v[168:169], v[92:93], v[194:195]
	v_mov_b32_e32 v182, v163
	v_mov_b32_e32 v183, v165
	v_mov_b32_e32 v194, v179
	v_mov_b32_e32 v195, v181
	v_pk_fma_f32 v[158:159], v[94:95], v[154:155], v[158:159]
	v_pk_fma_f32 v[160:161], v[92:93], v[166:167], v[160:161]
	v_pk_fma_f32 v[154:155], v[30:31], v[154:155], v[156:157] neg_lo:[0,0,1] neg_hi:[0,0,1]
	v_pk_fma_f32 v[156:157], v[28:29], v[166:167], v[168:169] neg_lo:[0,0,1] neg_hi:[0,0,1]
	v_pk_mul_f32 v[166:167], v[26:27], v[182:183]
	v_mov_b32_e32 v163, v164
	v_mov_b32_e32 v179, v180
	v_pk_mul_f32 v[164:165], v[90:91], v[182:183]
	v_pk_mul_f32 v[180:181], v[88:89], v[194:195]
	v_pk_mul_f32 v[168:169], v[24:25], v[194:195]
	v_pk_fma_f32 v[166:167], v[90:91], v[162:163], v[166:167]
	v_pk_fma_f32 v[162:163], v[26:27], v[162:163], v[164:165] neg_lo:[0,0,1] neg_hi:[0,0,1]
	v_pk_fma_f32 v[164:165], v[24:25], v[178:179], v[180:181] neg_lo:[0,0,1] neg_hi:[0,0,1]
	v_pk_fma_f32 v[168:169], v[88:89], v[178:179], v[168:169]
	v_lshl_add_u64 v[182:183], v[152:153], 0, v[184:185]
	v_cvt_pk_bf16_f32 v152, v156, v157
	v_cvt_pk_bf16_f32 v153, v154, v155
	v_cvt_pk_bf16_f32 v154, v164, v165
	v_cvt_pk_bf16_f32 v155, v162, v163
	v_cvt_pk_bf16_f32 v178, v160, v161
	v_cvt_pk_bf16_f32 v179, v158, v159
	v_cvt_pk_bf16_f32 v180, v168, v169
	v_cvt_pk_bf16_f32 v181, v166, v167
	global_store_dwordx4 v[182:183], v[152:155], off offset:128
	global_store_dwordx4 v[182:183], v[178:181], off
	s_nop 0
	v_or_b32_e32 v152, s44, v174
	v_ashrrev_i32_e32 v153, 31, v152
	v_lshlrev_b64 v[182:183], 18, v[152:153]
	global_load_dwordx4 v[178:181], v[142:143], off offset:32
	global_load_dwordx4 v[162:165], v[142:143], off offset:48
	global_load_dwordx4 v[152:155], v[142:143], off
	global_load_dwordx4 v[156:159], v[142:143], off offset:16
	s_waitcnt vmcnt(1)
	v_mov_b32_e32 v168, v153
	s_waitcnt vmcnt(0)
; DI u32x4 pack8(const f32x4& v0, const f32x4& v1) { u32x4 w; w.x = pk2(v0[0], v0[1]); w.y = pk2(v0[2], v0[3]); w.z = pk2(v1[0], v1[1]); w.w = pk2(v1[2], v1[3]); return w; }
;     DI void operator()(const f32x4 (&acc)[2][2][4][2], const Unit& u, int wr, int wc, int fr, int fq) const {
;     ...
;         for (int m = 0; m < 4; ++m) {
;             const int k1 = 16 * m + fr;
; #pragma unroll
;             for (int bj = 0; bj < 2; ++bj) {
;                 const int j0 = 128 * bj + 32 * wc + 8 * fq, ge = 4 * u.pn + (j0 >> 6), nl0 = j0 & 63;
;                 const f32x4* tw = (const f32x4*)(TW + (size_t)(k1 * 64 + nl0) * 2);
;                 f32x4 yr[2], yi[2];
; #pragma unroll
;                 for (int n = 0; n < 2; ++n) {
;                     const f32x4 t0 = tw[2 * n], t1 = tw[2 * n + 1];
;                     const f32x4 c = {t0.x, t0.z, t1.x, t1.z}, s = {t0.y, t0.w, t1.y, t1.w};
;                     const f32x4 r = acc[0][bj][m][n], i = acc[1][bj][m][n];
;                     yr[n] = c * r + s * i; yi[n] = c * i - s * r;
;                 }
;                 bf16_t* dst = YP + ((((size_t)(u.z * 64 + k1)) * 1024 + ge) * 2) * 64 + nl0;
;                 *(u32x4*)dst = pack8(yr[0], yr[1]); *(u32x4*)(dst + 64) = pack8(yi[0], yi[1]);
	v_mov_b32_e32 v166, v157
	v_mov_b32_e32 v167, v159
	v_mov_b32_e32 v169, v155
	v_pk_mul_f32 v[160:161], v[54:55], v[166:167]
	v_pk_mul_f32 v[194:195], v[52:53], v[168:169]
	v_mov_b32_e32 v157, v158
	v_mov_b32_e32 v153, v154
	v_pk_mul_f32 v[154:155], v[118:119], v[166:167]
	v_pk_mul_f32 v[166:167], v[116:117], v[168:169]
	v_pk_fma_f32 v[158:159], v[118:119], v[156:157], v[160:161]
	v_pk_fma_f32 v[160:161], v[116:117], v[152:153], v[194:195]
	v_pk_fma_f32 v[154:155], v[54:55], v[156:157], v[154:155] neg_lo:[0,0,1] neg_hi:[0,0,1]
	v_pk_fma_f32 v[156:157], v[52:53], v[152:153], v[166:167] neg_lo:[0,0,1] neg_hi:[0,0,1]
	v_mov_b32_e32 v152, v163
	v_mov_b32_e32 v153, v165
	v_pk_mul_f32 v[166:167], v[50:51], v[152:153]
	v_mov_b32_e32 v194, v179
	v_mov_b32_e32 v195, v181
	v_mov_b32_e32 v163, v164
	v_pk_mul_f32 v[152:153], v[114:115], v[152:153]
	v_pk_mul_f32 v[168:169], v[48:49], v[194:195]
	v_pk_fma_f32 v[166:167], v[114:115], v[162:163], v[166:167]
	v_mov_b32_e32 v179, v180
	v_pk_mul_f32 v[164:165], v[112:113], v[194:195]
	v_pk_fma_f32 v[162:163], v[50:51], v[162:163], v[152:153] neg_lo:[0,0,1] neg_hi:[0,0,1]
	v_lshl_add_u64 v[152:153], s[46:47], 0, v[182:183]
	v_pk_fma_f32 v[168:169], v[112:113], v[178:179], v[168:169]
	v_pk_fma_f32 v[164:165], v[48:49], v[178:179], v[164:165] neg_lo:[0,0,1] neg_hi:[0,0,1]
	v_lshl_add_u64 v[178:179], v[152:153], 0, s[12:13]
	v_lshl_add_u64 v[182:183], v[178:179], 0, v[184:185]
	v_cvt_pk_bf16_f32 v178, v160, v161
	v_cvt_pk_bf16_f32 v179, v158, v159
	v_cvt_pk_bf16_f32 v180, v168, v169
	v_cvt_pk_bf16_f32 v181, v166, v167
	v_cvt_pk_bf16_f32 v156, v156, v157
	v_cvt_pk_bf16_f32 v157, v154, v155
	v_cvt_pk_bf16_f32 v158, v164, v165
	v_cvt_pk_bf16_f32 v159, v162, v163
	global_store_dwordx4 v[182:183], v[178:181], off
	global_store_dwordx4 v[182:183], v[156:159], off offset:128
	global_load_dwordx4 v[178:181], v[142:143], off offset:32
	s_nop 0
	global_load_dwordx4 v[162:165], v[142:143], off offset:48
	global_load_dwordx4 v[166:169], v[142:143], off
	global_load_dwordx4 v[154:157], v[142:143], off offset:16
	v_lshl_add_u64 v[152:153], v[152:153], 0, s[14:15]
	s_waitcnt vmcnt(1)
	v_mov_b32_e32 v194, v167
	s_waitcnt vmcnt(0)
	v_mov_b32_e32 v182, v155
	v_mov_b32_e32 v183, v157
	v_mov_b32_e32 v195, v169
	v_pk_mul_f32 v[158:159], v[22:23], v[182:183]
	v_pk_mul_f32 v[160:161], v[20:21], v[194:195]
	v_mov_b32_e32 v155, v156
	v_mov_b32_e32 v167, v168
	v_pk_mul_f32 v[156:157], v[86:87], v[182:183]
	v_pk_mul_f32 v[168:169], v[84:85], v[194:195]
	v_mov_b32_e32 v182, v163
	v_mov_b32_e32 v183, v165
	v_mov_b32_e32 v194, v179
	v_mov_b32_e32 v195, v181
	v_pk_fma_f32 v[158:159], v[86:87], v[154:155], v[158:159]
	v_pk_fma_f32 v[160:161], v[84:85], v[166:167], v[160:161]
	v_pk_fma_f32 v[154:155], v[22:23], v[154:155], v[156:157] neg_lo:[0,0,1] neg_hi:[0,0,1]
	v_pk_fma_f32 v[156:157], v[20:21], v[166:167], v[168:169] neg_lo:[0,0,1] neg_hi:[0,0,1]
	v_pk_mul_f32 v[166:167], v[18:19], v[182:183]
	v_mov_b32_e32 v163, v164
	v_mov_b32_e32 v179, v180
	v_pk_mul_f32 v[164:165], v[82:83], v[182:183]
	v_pk_mul_f32 v[180:181], v[80:81], v[194:195]
	v_pk_mul_f32 v[168:169], v[16:17], v[194:195]
	v_pk_fma_f32 v[166:167], v[82:83], v[162:163], v[166:167]
	v_pk_fma_f32 v[162:163], v[18:19], v[162:163], v[164:165] neg_lo:[0,0,1] neg_hi:[0,0,1]
	v_pk_fma_f32 v[164:165], v[16:17], v[178:179], v[180:181] neg_lo:[0,0,1] neg_hi:[0,0,1]
	v_pk_fma_f32 v[168:169], v[80:81], v[178:179], v[168:169]
	v_lshl_add_u64 v[182:183], v[152:153], 0, v[184:185]
	v_cvt_pk_bf16_f32 v152, v156, v157
	v_cvt_pk_bf16_f32 v153, v154, v155
	v_cvt_pk_bf16_f32 v154, v164, v165
	v_cvt_pk_bf16_f32 v155, v162, v163
	v_cvt_pk_bf16_f32 v178, v160, v161
	v_cvt_pk_bf16_f32 v179, v158, v159
	v_cvt_pk_bf16_f32 v180, v168, v169
	v_cvt_pk_bf16_f32 v181, v166, v167
	global_store_dwordx4 v[182:183], v[152:155], off offset:128
	global_store_dwordx4 v[182:183], v[178:181], off
	s_nop 0
	v_or_b32_e32 v152, s44, v175
	v_ashrrev_i32_e32 v153, 31, v152
	v_lshlrev_b64 v[182:183], 18, v[152:153]
	global_load_dwordx4 v[178:181], v[144:145], off offset:32
	global_load_dwordx4 v[162:165], v[144:145], off offset:48
	global_load_dwordx4 v[152:155], v[144:145], off
	global_load_dwordx4 v[156:159], v[144:145], off offset:16
	s_waitcnt vmcnt(1)
	v_mov_b32_e32 v168, v153
	s_waitcnt vmcnt(0)
	v_mov_b32_e32 v166, v157
	v_mov_b32_e32 v167, v159
	v_mov_b32_e32 v169, v155
	v_pk_mul_f32 v[160:161], v[46:47], v[166:167]
	v_pk_mul_f32 v[194:195], v[44:45], v[168:169]
	v_mov_b32_e32 v157, v158
	v_mov_b32_e32 v153, v154
	v_pk_mul_f32 v[154:155], v[110:111], v[166:167]
	v_pk_mul_f32 v[166:167], v[108:109], v[168:169]
	v_pk_fma_f32 v[158:159], v[110:111], v[156:157], v[160:161]
	v_pk_fma_f32 v[160:161], v[108:109], v[152:153], v[194:195]
	v_pk_fma_f32 v[154:155], v[46:47], v[156:157], v[154:155] neg_lo:[0,0,1] neg_hi:[0,0,1]
	v_pk_fma_f32 v[156:157], v[44:45], v[152:153], v[166:167] neg_lo:[0,0,1] neg_hi:[0,0,1]
	v_mov_b32_e32 v152, v163
	v_mov_b32_e32 v153, v165
	v_pk_mul_f32 v[166:167], v[42:43], v[152:153]
	v_mov_b32_e32 v194, v179
	v_mov_b32_e32 v195, v181
	v_mov_b32_e32 v163, v164
	v_pk_mul_f32 v[152:153], v[106:107], v[152:153]
	v_pk_mul_f32 v[168:169], v[40:41], v[194:195]
	v_pk_fma_f32 v[166:167], v[106:107], v[162:163], v[166:167]
	v_mov_b32_e32 v179, v180
	v_pk_mul_f32 v[164:165], v[104:105], v[194:195]
	v_pk_fma_f32 v[162:163], v[42:43], v[162:163], v[152:153] neg_lo:[0,0,1] neg_hi:[0,0,1]
	v_lshl_add_u64 v[152:153], s[46:47], 0, v[182:183]
	v_pk_fma_f32 v[168:169], v[104:105], v[178:179], v[168:169]
	v_pk_fma_f32 v[164:165], v[40:41], v[178:179], v[164:165] neg_lo:[0,0,1] neg_hi:[0,0,1]
	v_lshl_add_u64 v[178:179], v[152:153], 0, s[12:13]
	v_lshl_add_u64 v[182:183], v[178:179], 0, v[184:185]
	v_cvt_pk_bf16_f32 v178, v160, v161
	v_cvt_pk_bf16_f32 v179, v158, v159
	v_cvt_pk_bf16_f32 v180, v168, v169
	v_cvt_pk_bf16_f32 v181, v166, v167
	v_cvt_pk_bf16_f32 v156, v156, v157
	v_cvt_pk_bf16_f32 v157, v154, v155
	v_cvt_pk_bf16_f32 v158, v164, v165
	v_cvt_pk_bf16_f32 v159, v162, v163
	global_store_dwordx4 v[182:183], v[178:181], off
	global_store_dwordx4 v[182:183], v[156:159], off offset:128
	global_load_dwordx4 v[178:181], v[144:145], off offset:32
	s_nop 0
	global_load_dwordx4 v[162:165], v[144:145], off offset:48
	global_load_dwordx4 v[166:169], v[144:145], off
	global_load_dwordx4 v[154:157], v[144:145], off offset:16
	v_lshl_add_u64 v[152:153], v[152:153], 0, s[14:15]
	s_waitcnt vmcnt(1)
; DI u32x4 pack8(const f32x4& v0, const f32x4& v1) { u32x4 w; w.x = pk2(v0[0], v0[1]); w.y = pk2(v0[2], v0[3]); w.z = pk2(v1[0], v1[1]); w.w = pk2(v1[2], v1[3]); return w; }
;     DI void operator()(const f32x4 (&acc)[2][2][4][2], const Unit& u, int wr, int wc, int fr, int fq) const {
;     ...
;             const int k1 = 16 * m + fr;
; #pragma unroll
;             for (int bj = 0; bj < 2; ++bj) {
;                 const int j0 = 128 * bj + 32 * wc + 8 * fq, ge = 4 * u.pn + (j0 >> 6), nl0 = j0 & 63;
;                 const f32x4* tw = (const f32x4*)(TW + (size_t)(k1 * 64 + nl0) * 2);
;                 f32x4 yr[2], yi[2];
; #pragma unroll
;                 for (int n = 0; n < 2; ++n) {
;                     const f32x4 t0 = tw[2 * n], t1 = tw[2 * n + 1];
;                     const f32x4 c = {t0.x, t0.z, t1.x, t1.z}, s = {t0.y, t0.w, t1.y, t1.w};
;                     const f32x4 r = acc[0][bj][m][n], i = acc[1][bj][m][n];
;                     yr[n] = c * r + s * i; yi[n] = c * i - s * r;
;                 }
;                 bf16_t* dst = YP + ((((size_t)(u.z * 64 + k1)) * 1024 + ge) * 2) * 64 + nl0;
;                 *(u32x4*)dst = pack8(yr[0], yr[1]); *(u32x4*)(dst + 64) = pack8(yi[0], yi[1]);
	v_mov_b32_e32 v194, v167
	s_waitcnt vmcnt(0)
	v_mov_b32_e32 v182, v155
	v_mov_b32_e32 v183, v157
	v_mov_b32_e32 v195, v169
	v_pk_mul_f32 v[158:159], v[14:15], v[182:183]
	v_pk_mul_f32 v[160:161], v[12:13], v[194:195]
	v_mov_b32_e32 v155, v156
	v_mov_b32_e32 v167, v168
	v_pk_mul_f32 v[156:157], v[78:79], v[182:183]
	v_pk_mul_f32 v[168:169], v[76:77], v[194:195]
	v_mov_b32_e32 v182, v163
	v_mov_b32_e32 v183, v165
	v_mov_b32_e32 v194, v179
	v_mov_b32_e32 v195, v181
	v_pk_fma_f32 v[158:159], v[78:79], v[154:155], v[158:159]
	v_pk_fma_f32 v[160:161], v[76:77], v[166:167], v[160:161]
	v_pk_fma_f32 v[154:155], v[14:15], v[154:155], v[156:157] neg_lo:[0,0,1] neg_hi:[0,0,1]
	v_pk_fma_f32 v[156:157], v[12:13], v[166:167], v[168:169] neg_lo:[0,0,1] neg_hi:[0,0,1]
	v_pk_mul_f32 v[166:167], v[10:11], v[182:183]
	v_mov_b32_e32 v163, v164
	v_mov_b32_e32 v179, v180
	v_pk_mul_f32 v[164:165], v[74:75], v[182:183]
	v_pk_mul_f32 v[180:181], v[72:73], v[194:195]
	v_pk_mul_f32 v[168:169], v[8:9], v[194:195]
	v_pk_fma_f32 v[166:167], v[74:75], v[162:163], v[166:167]
	v_pk_fma_f32 v[162:163], v[10:11], v[162:163], v[164:165] neg_lo:[0,0,1] neg_hi:[0,0,1]
	v_pk_fma_f32 v[164:165], v[8:9], v[178:179], v[180:181] neg_lo:[0,0,1] neg_hi:[0,0,1]
	v_pk_fma_f32 v[168:169], v[72:73], v[178:179], v[168:169]
	v_lshl_add_u64 v[182:183], v[152:153], 0, v[184:185]
	v_cvt_pk_bf16_f32 v152, v156, v157
	v_cvt_pk_bf16_f32 v153, v154, v155
	v_cvt_pk_bf16_f32 v154, v164, v165
	v_cvt_pk_bf16_f32 v155, v162, v163
	v_cvt_pk_bf16_f32 v178, v160, v161
	v_cvt_pk_bf16_f32 v179, v158, v159
	v_cvt_pk_bf16_f32 v180, v168, v169
	v_cvt_pk_bf16_f32 v181, v166, v167
	global_store_dwordx4 v[182:183], v[152:155], off offset:128
	global_store_dwordx4 v[182:183], v[178:181], off
	s_nop 0
	v_or_b32_e32 v152, s44, v176
	v_ashrrev_i32_e32 v153, 31, v152
	v_lshlrev_b64 v[182:183], 18, v[152:153]
	global_load_dwordx4 v[178:181], v[146:147], off offset:32
	global_load_dwordx4 v[162:165], v[146:147], off offset:48
	global_load_dwordx4 v[152:155], v[146:147], off
	global_load_dwordx4 v[156:159], v[146:147], off offset:16
	s_waitcnt vmcnt(1)
	v_mov_b32_e32 v168, v153
	s_waitcnt vmcnt(0)
	v_mov_b32_e32 v166, v157
	v_mov_b32_e32 v167, v159
	v_mov_b32_e32 v169, v155
	v_pk_mul_f32 v[160:161], v[38:39], v[166:167]
	v_pk_mul_f32 v[194:195], v[36:37], v[168:169]
	v_mov_b32_e32 v157, v158
	v_mov_b32_e32 v153, v154
	v_pk_mul_f32 v[154:155], v[102:103], v[166:167]
	v_pk_mul_f32 v[166:167], v[100:101], v[168:169]
	v_pk_fma_f32 v[158:159], v[102:103], v[156:157], v[160:161]
	v_pk_fma_f32 v[160:161], v[100:101], v[152:153], v[194:195]
	v_pk_fma_f32 v[154:155], v[38:39], v[156:157], v[154:155] neg_lo:[0,0,1] neg_hi:[0,0,1]
	v_pk_fma_f32 v[156:157], v[36:37], v[152:153], v[166:167] neg_lo:[0,0,1] neg_hi:[0,0,1]
	v_mov_b32_e32 v152, v163
	v_mov_b32_e32 v153, v165
	v_pk_mul_f32 v[166:167], v[34:35], v[152:153]
	v_mov_b32_e32 v194, v179
	v_mov_b32_e32 v195, v181
	v_mov_b32_e32 v163, v164
	v_pk_mul_f32 v[152:153], v[98:99], v[152:153]
	v_pk_mul_f32 v[168:169], v[32:33], v[194:195]
	v_pk_fma_f32 v[166:167], v[98:99], v[162:163], v[166:167]
	v_mov_b32_e32 v179, v180
	v_pk_mul_f32 v[164:165], v[96:97], v[194:195]
	v_pk_fma_f32 v[162:163], v[34:35], v[162:163], v[152:153] neg_lo:[0,0,1] neg_hi:[0,0,1]
	v_lshl_add_u64 v[152:153], s[46:47], 0, v[182:183]
	v_pk_fma_f32 v[168:169], v[96:97], v[178:179], v[168:169]
	v_pk_fma_f32 v[164:165], v[32:33], v[178:179], v[164:165] neg_lo:[0,0,1] neg_hi:[0,0,1]
	v_lshl_add_u64 v[178:179], v[152:153], 0, s[12:13]
	v_lshl_add_u64 v[182:183], v[178:179], 0, v[184:185]
	v_cvt_pk_bf16_f32 v178, v160, v161
	v_cvt_pk_bf16_f32 v179, v158, v159
	v_cvt_pk_bf16_f32 v180, v168, v169
	v_cvt_pk_bf16_f32 v181, v166, v167
	v_cvt_pk_bf16_f32 v156, v156, v157
	v_cvt_pk_bf16_f32 v157, v154, v155
	v_cvt_pk_bf16_f32 v158, v164, v165
	v_cvt_pk_bf16_f32 v159, v162, v163
	global_store_dwordx4 v[182:183], v[178:181], off
	global_store_dwordx4 v[182:183], v[156:159], off offset:128
	global_load_dwordx4 v[178:181], v[146:147], off offset:32
	s_nop 0
	global_load_dwordx4 v[162:165], v[146:147], off offset:48
	global_load_dwordx4 v[166:169], v[146:147], off
	global_load_dwordx4 v[154:157], v[146:147], off offset:16
	v_lshl_add_u64 v[152:153], v[152:153], 0, s[14:15]
	s_waitcnt vmcnt(1)
	v_mov_b32_e32 v194, v167
	s_waitcnt vmcnt(0)
	v_mov_b32_e32 v182, v155
	v_mov_b32_e32 v183, v157
	v_mov_b32_e32 v195, v169
	v_pk_mul_f32 v[158:159], v[6:7], v[182:183]
	v_pk_mul_f32 v[160:161], v[4:5], v[194:195]
	v_mov_b32_e32 v155, v156
	v_mov_b32_e32 v167, v168
	v_pk_mul_f32 v[156:157], v[70:71], v[182:183]
	v_pk_mul_f32 v[168:169], v[68:69], v[194:195]
	v_mov_b32_e32 v182, v163
	v_mov_b32_e32 v183, v165
	v_mov_b32_e32 v194, v179
	v_mov_b32_e32 v195, v181
	v_pk_fma_f32 v[158:159], v[70:71], v[154:155], v[158:159]
	v_pk_fma_f32 v[160:161], v[68:69], v[166:167], v[160:161]
	v_pk_fma_f32 v[154:155], v[6:7], v[154:155], v[156:157] neg_lo:[0,0,1] neg_hi:[0,0,1]
	v_pk_fma_f32 v[156:157], v[4:5], v[166:167], v[168:169] neg_lo:[0,0,1] neg_hi:[0,0,1]
	v_pk_mul_f32 v[166:167], v[2:3], v[182:183]
	v_pk_mul_f32 v[168:169], v[0:1], v[194:195]
	v_mov_b32_e32 v163, v164
	v_mov_b32_e32 v179, v180
	v_pk_mul_f32 v[164:165], v[66:67], v[182:183]
	v_pk_mul_f32 v[180:181], v[64:65], v[194:195]
	v_pk_fma_f32 v[166:167], v[66:67], v[162:163], v[166:167]
	v_pk_fma_f32 v[168:169], v[64:65], v[178:179], v[168:169]
	v_pk_fma_f32 v[162:163], v[2:3], v[162:163], v[164:165] neg_lo:[0,0,1] neg_hi:[0,0,1]
	v_pk_fma_f32 v[164:165], v[0:1], v[178:179], v[180:181] neg_lo:[0,0,1] neg_hi:[0,0,1]
	v_lshl_add_u64 v[182:183], v[152:153], 0, v[184:185]
	v_cvt_pk_bf16_f32 v178, v160, v161
	v_cvt_pk_bf16_f32 v179, v158, v159
	v_cvt_pk_bf16_f32 v180, v168, v169
	v_cvt_pk_bf16_f32 v181, v166, v167
	v_cvt_pk_bf16_f32 v152, v156, v157
	v_cvt_pk_bf16_f32 v153, v154, v155
	v_cvt_pk_bf16_f32 v154, v164, v165
	v_cvt_pk_bf16_f32 v155, v162, v163
	global_store_dwordx4 v[182:183], v[178:181], off
	global_store_dwordx4 v[182:183], v[152:155], off offset:128
	s_andn2_b64 vcc, exec, s[8:9]
	s_cbranch_vccnz .LBB0_254
	s_branch .LBB0_264

; #define G_STAGE_A(bufoff, p0, p1, koff) do { \
;         __builtin_amdgcn_global_load_lds((const unsigned*)(gbase + (size_t)(unsigned)((p0) + (koff) + voffA[0])), (LAS unsigned*)(lds + (bufoff) + ldsw), 16, 0, 0); \
;         __builtin_amdgcn_global_load_lds((const unsigned*)(gbase + (size_t)(unsigned)((p1) + (koff) + voffA[1])), (LAS unsigned*)(lds + (bufoff) + ldsw + 8192), 16, 0, 0); } while (0)
; #define G_STAGE_B(bufoff, p, koff) do { \
;         __builtin_amdgcn_global_load_lds((const unsigned*)(gbase + (size_t)(unsigned)((p) + (koff) + voffB[0])), (LAS unsigned*)(lds + (bufoff) + ldsw), 16, 0, 0); \
;         __builtin_amdgcn_global_load_lds((const unsigned*)(gbase + (size_t)(unsigned)((p) + (koff) + voffB[1])), (LAS unsigned*)(lds + (bufoff) + ldsw + 8192), 16, 0, 0); } while (0)
; #define G_LDA(dst, b, h) do { _Pragma("unroll") for (int m = 0; m < 4; ++m) _Pragma("unroll") for (int k = 0; k < 2; ++k) dst[m][k] = *(const LAS bf16x8*)(lds + G_SA(b, h) + aoff + m * 2048 + k * 1024); } while (0)
; #define G_LDB(dst, b, h) do { _Pragma("unroll") for (int n = 0; n < 2; ++n) _Pragma("unroll") for (int k = 0; k < 2; ++k) dst[n][k] = *(const LAS bf16x8*)(lds + G_SB(b, h) + boff + n * 2048 + k * 1024); } while (0)
; #define G_WAIT_V(n) asm volatile("s_waitcnt vmcnt(" #n ")" ::: "memory")
; template <class Epi>
; DI void gemm_phase(LAS unsigned char* lds, const Sched& S, const Epi& E, const int K) {
;     ...
;             const bool last = (t == nt - 2);
;             const unsigned k1 = (unsigned)(t + 1) * kstepA;
;             const unsigned k2 = last ? 0u : (unsigned)(t + 2) * kstepA, k3 = k2 + kstepA;
;             const unsigned kb2 = last ? 0u : (unsigned)(t + 2) * kstepB, kb3 = kb2 + kstepB;
;             const unsigned x0 = last ? n0 : cur.a0, x1 = last ? n1 : cur.a1, x2 = last ? n2 : cur.a2, x3 = last ? n3 : cur.a3;
;             const unsigned xb = last ? nB : cur.b;
;     ...
;             G_LDB(B0, 0, 0); G_LDB(B1, 0, 1); G_SCHED; G_LDA(At, 0, 0); G_STAGE_A(G_SA(1, 1), cur.a2, cur.a3, k1);
;             G_WAIT_V(8); G_WAIT_L(0); G_BAR; G_MMA(0, 0, At, B0); G_MMA(0, 1, At, B1); G_BAR; G_SCHED;
;             G_LDA(At, 0, 1); G_STAGE_B(G_SB(0, 0), xb, kb2); G_STAGE_B(G_SB(0, 1), xb + hstepB, kb2); G_STAGE_A(G_SA(0, 0), x0, x1, k2);
;             G_WAIT_V(8); G_WAIT_L(0); G_BAR; G_MMA(1, 0, At, B0); G_MMA(1, 1, At, B1); G_BAR; G_SCHED;
.LBB0_281:
	s_add_u32 s14, s12, 0x100
	s_addc_u32 s15, s13, 0
	s_cmp_eq_u32 s44, 4
	s_cselect_b32 s40, 0, s14
	s_cselect_b32 s46, s41, s35
	s_add_i32 s47, 0, 0x10000
	v_add_u32_e32 v132, s47, v136
	s_add_i32 s48, 0, 0x14000
	ds_read_b128 v[144:147], v132
	ds_read_b128 v[148:151], v132 offset:1024
	ds_read_b128 v[152:155], v132 offset:2048
	ds_read_b128 v[156:159], v132 offset:3072
	v_add_u32_e32 v132, s48, v136
	ds_read_b128 v[160:163], v132
	ds_read_b128 v[164:167], v132 offset:1024
	ds_read_b128 v[168:171], v132 offset:2048
	ds_read_b128 v[172:175], v132 offset:3072
	s_or_b32 s45, s40, 0x80
	v_lshl_add_u64 v[132:133], v[130:131], 0, s[12:13]
	s_add_i32 m0, s17, 0xc000
	ds_read_b128 v[176:179], v143
	ds_read_b128 v[180:183], v143 offset:1024
	ds_read_b128 v[194:197], v143 offset:2048
	ds_read_b128 v[198:201], v143 offset:3072
	ds_read_b128 v[202:205], v143 offset:4096
	ds_read_b128 v[206:209], v143 offset:5120
	ds_read_b128 v[210:213], v143 offset:6144
	ds_read_b128 v[214:217], v143 offset:7168
	global_load_lds_dwordx4 v[132:133], off
	v_lshl_add_u64 v[132:133], v[128:129], 0, s[12:13]
	s_add_i32 m0, s17, 0xe000
	s_nop 0
	global_load_lds_dwordx4 v[132:133], off
	s_waitcnt vmcnt(8)
	s_waitcnt lgkmcnt(0)
	s_barrier
	s_setprio 0
	s_waitcnt lgkmcnt(0)
	v_mfma_f32_16x16x32_bf16 v[124:127], v[144:147], v[176:179], v[124:127]
	v_mfma_f32_16x16x32_bf16 v[120:123], v[152:155], v[176:179], v[120:123]
	v_mfma_f32_16x16x32_bf16 v[116:119], v[144:147], v[194:197], v[116:119]
	v_mfma_f32_16x16x32_bf16 v[112:115], v[152:155], v[194:197], v[112:115]
	v_mfma_f32_16x16x32_bf16 v[108:111], v[144:147], v[202:205], v[108:111]
	v_mfma_f32_16x16x32_bf16 v[104:107], v[152:155], v[202:205], v[104:107]
	v_mfma_f32_16x16x32_bf16 v[100:103], v[144:147], v[210:213], v[100:103]
	v_mfma_f32_16x16x32_bf16 v[96:99], v[152:155], v[210:213], v[96:99]
	v_mfma_f32_16x16x32_bf16 v[124:127], v[148:151], v[180:183], v[124:127]
	v_mfma_f32_16x16x32_bf16 v[120:123], v[156:159], v[180:183], v[120:123]
	v_mfma_f32_16x16x32_bf16 v[116:119], v[148:151], v[198:201], v[116:119]
	v_mfma_f32_16x16x32_bf16 v[112:115], v[156:159], v[198:201], v[112:115]
	v_mfma_f32_16x16x32_bf16 v[108:111], v[148:151], v[206:209], v[108:111]
	v_mfma_f32_16x16x32_bf16 v[104:107], v[156:159], v[206:209], v[104:107]
	v_mfma_f32_16x16x32_bf16 v[100:103], v[148:151], v[214:217], v[100:103]
	v_mfma_f32_16x16x32_bf16 v[96:99], v[156:159], v[214:217], v[96:99]
	v_mfma_f32_16x16x32_bf16 v[92:95], v[160:163], v[176:179], v[92:95]
	v_mfma_f32_16x16x32_bf16 v[88:91], v[168:171], v[176:179], v[88:91]
	v_mfma_f32_16x16x32_bf16 v[84:87], v[160:163], v[194:197], v[84:87]
	v_mfma_f32_16x16x32_bf16 v[80:83], v[168:171], v[194:197], v[80:83]
	v_mfma_f32_16x16x32_bf16 v[76:79], v[160:163], v[202:205], v[76:79]
	v_mfma_f32_16x16x32_bf16 v[72:75], v[168:171], v[202:205], v[72:75]
	v_mfma_f32_16x16x32_bf16 v[68:71], v[160:163], v[210:213], v[68:71]
	v_mfma_f32_16x16x32_bf16 v[64:67], v[168:171], v[210:213], v[64:67]
	v_mfma_f32_16x16x32_bf16 v[92:95], v[164:167], v[180:183], v[92:95]
	v_mfma_f32_16x16x32_bf16 v[88:91], v[172:175], v[180:183], v[88:91]
	v_mfma_f32_16x16x32_bf16 v[84:87], v[164:167], v[198:201], v[84:87]
	v_mfma_f32_16x16x32_bf16 v[80:83], v[172:175], v[198:201], v[80:83]
	v_mfma_f32_16x16x32_bf16 v[76:79], v[164:167], v[206:209], v[76:79]
	v_mfma_f32_16x16x32_bf16 v[72:75], v[172:175], v[206:209], v[72:75]
	v_mfma_f32_16x16x32_bf16 v[68:71], v[164:167], v[214:217], v[68:71]
	v_mfma_f32_16x16x32_bf16 v[64:67], v[172:175], v[214:217], v[64:67]
	s_setprio 1
	s_barrier
	s_add_i32 s12, s40, s46
	s_add_i32 s13, s47, s16
	v_add_u32_e32 v132, s12, v134
	s_mov_b32 m0, s13
	ds_read_b128 v[176:179], v143 offset:16384
	ds_read_b128 v[180:183], v143 offset:17408
	ds_read_b128 v[194:197], v143 offset:18432
	ds_read_b128 v[198:201], v143 offset:19456
	ds_read_b128 v[202:205], v143 offset:20480
	ds_read_b128 v[206:209], v143 offset:21504
	ds_read_b128 v[210:213], v143 offset:22528
	ds_read_b128 v[214:217], v143 offset:23552
	global_load_lds_dwordx4 v132, s[82:83]
	v_add_u32_e32 v132, s12, v135
	s_add_i32 s12, s46, 0x20000
	s_add_i32 m0, s13, 0x2000
	s_add_i32 s13, s12, s40
	s_add_i32 s47, s48, s16
	global_load_lds_dwordx4 v132, s[82:83]
	v_add_u32_e32 v132, s13, v134
	s_mov_b32 m0, s47
	s_nop 0
	global_load_lds_dwordx4 v132, s[82:83]
	v_add_u32_e32 v132, s13, v135
	s_add_i32 m0, s47, 0x2000
	s_nop 0
	global_load_lds_dwordx4 v132, s[82:83]
	v_add_u32_e32 v132, s40, v141
	s_mov_b32 m0, s17
	s_nop 0
	global_load_lds_dwordx4 v132, s[82:83]
	v_add_u32_e32 v132, s40, v142
	s_mov_b32 m0, s18
	s_nop 0
	global_load_lds_dwordx4 v132, s[82:83]
	s_waitcnt vmcnt(8)
	s_waitcnt lgkmcnt(0)
	s_barrier
; #define G_STAGE_A(bufoff, p0, p1, koff) do { \
;         __builtin_amdgcn_global_load_lds((const unsigned*)(gbase + (size_t)(unsigned)((p0) + (koff) + voffA[0])), (LAS unsigned*)(lds + (bufoff) + ldsw), 16, 0, 0); \
;         __builtin_amdgcn_global_load_lds((const unsigned*)(gbase + (size_t)(unsigned)((p1) + (koff) + voffA[1])), (LAS unsigned*)(lds + (bufoff) + ldsw + 8192), 16, 0, 0); } while (0)
; #define G_LDA(dst, b, h) do { _Pragma("unroll") for (int m = 0; m < 4; ++m) _Pragma("unroll") for (int k = 0; k < 2; ++k) dst[m][k] = *(const LAS bf16x8*)(lds + G_SA(b, h) + aoff + m * 2048 + k * 1024); } while (0)
; #define G_LDB(dst, b, h) do { _Pragma("unroll") for (int n = 0; n < 2; ++n) _Pragma("unroll") for (int k = 0; k < 2; ++k) dst[n][k] = *(const LAS bf16x8*)(lds + G_SB(b, h) + boff + n * 2048 + k * 1024); } while (0)
; #define G_MMA(ai, bj, At, Bt) do { __builtin_amdgcn_s_setprio(1); _Pragma("unroll") for (int m = 0; m < 4; ++m) _Pragma("unroll") for (int n = 0; n < 2; ++n) _Pragma("unroll") for (int k = 0; k < 2; ++k) \
;         acc[ai][bj][m][n] = __builtin_amdgcn_mfma_f32_16x16x32_bf16(Bt[n][k], At[m][k], acc[ai][bj][m][n], 0, 0, 0); __builtin_amdgcn_s_setprio(0); } while (0)
; #define G_WAIT_V(n) asm volatile("s_waitcnt vmcnt(" #n ")" ::: "memory")
; #define G_WAIT_L(n) asm volatile("s_waitcnt lgkmcnt(" #n ")" ::: "memory")
; #define G_BAR __builtin_amdgcn_s_barrier()
; #define G_SCHED __builtin_amdgcn_sched_barrier(0)
; template <class Epi>
; DI void gemm_phase(LAS unsigned char* lds, const Sched& S, const Epi& E, const int K) {
;     ...
;             G_WAIT_V(8); G_WAIT_L(0); G_BAR; G_MMA(1, 0, At, B0); G_MMA(1, 1, At, B1); G_BAR; G_SCHED;
;             G_LDB(B0, 1, 0); G_LDB(B1, 1, 1); G_SCHED; G_LDA(At, 1, 0); G_STAGE_A(G_SA(0, 1), x2, x3, k2);
;             G_WAIT_V(8); G_WAIT_L(0); G_BAR; G_MMA(0, 0, At, B0); G_MMA(0, 1, At, B1); G_BAR; G_SCHED;
	s_setprio 0
	s_waitcnt lgkmcnt(0)
	v_mfma_f32_16x16x32_bf16 v[60:63], v[144:147], v[176:179], v[60:63]
	v_mfma_f32_16x16x32_bf16 v[56:59], v[152:155], v[176:179], v[56:59]
	v_mfma_f32_16x16x32_bf16 v[52:55], v[144:147], v[194:197], v[52:55]
	v_mfma_f32_16x16x32_bf16 v[48:51], v[152:155], v[194:197], v[48:51]
	v_mfma_f32_16x16x32_bf16 v[44:47], v[144:147], v[202:205], v[44:47]
	v_mfma_f32_16x16x32_bf16 v[40:43], v[152:155], v[202:205], v[40:43]
	v_mfma_f32_16x16x32_bf16 v[36:39], v[144:147], v[210:213], v[36:39]
	v_mfma_f32_16x16x32_bf16 v[32:35], v[152:155], v[210:213], v[32:35]
	v_mfma_f32_16x16x32_bf16 v[60:63], v[148:151], v[180:183], v[60:63]
	v_mfma_f32_16x16x32_bf16 v[56:59], v[156:159], v[180:183], v[56:59]
	v_mfma_f32_16x16x32_bf16 v[52:55], v[148:151], v[198:201], v[52:55]
	v_mfma_f32_16x16x32_bf16 v[48:51], v[156:159], v[198:201], v[48:51]
	v_mfma_f32_16x16x32_bf16 v[44:47], v[148:151], v[206:209], v[44:47]
	v_mfma_f32_16x16x32_bf16 v[40:43], v[156:159], v[206:209], v[40:43]
	v_mfma_f32_16x16x32_bf16 v[36:39], v[148:151], v[214:217], v[36:39]
	v_mfma_f32_16x16x32_bf16 v[32:35], v[156:159], v[214:217], v[32:35]
	v_mfma_f32_16x16x32_bf16 v[28:31], v[160:163], v[176:179], v[28:31]
	v_mfma_f32_16x16x32_bf16 v[24:27], v[168:171], v[176:179], v[24:27]
	v_mfma_f32_16x16x32_bf16 v[20:23], v[160:163], v[194:197], v[20:23]
	v_mfma_f32_16x16x32_bf16 v[16:19], v[168:171], v[194:197], v[16:19]
	v_mfma_f32_16x16x32_bf16 v[12:15], v[160:163], v[202:205], v[12:15]
	v_mfma_f32_16x16x32_bf16 v[8:11], v[168:171], v[202:205], v[8:11]
	v_mfma_f32_16x16x32_bf16 v[4:7], v[160:163], v[210:213], v[4:7]
	v_mfma_f32_16x16x32_bf16 v[0:3], v[168:171], v[210:213], v[0:3]
	v_mfma_f32_16x16x32_bf16 v[28:31], v[164:167], v[180:183], v[28:31]
	v_mfma_f32_16x16x32_bf16 v[24:27], v[172:175], v[180:183], v[24:27]
	v_mfma_f32_16x16x32_bf16 v[20:23], v[164:167], v[198:201], v[20:23]
	v_mfma_f32_16x16x32_bf16 v[16:19], v[172:175], v[198:201], v[16:19]
	v_mfma_f32_16x16x32_bf16 v[12:15], v[164:167], v[206:209], v[12:15]
	v_mfma_f32_16x16x32_bf16 v[8:11], v[172:175], v[206:209], v[8:11]
	v_mfma_f32_16x16x32_bf16 v[4:7], v[164:167], v[214:217], v[4:7]
	v_mfma_f32_16x16x32_bf16 v[0:3], v[172:175], v[214:217], v[0:3]
	s_setprio 1
	s_barrier
	s_add_i32 s13, 0, 0x18000
	v_add_u32_e32 v132, s13, v136
	s_add_i32 s47, 0, 0x1c000
	ds_read_b128 v[144:147], v132
	ds_read_b128 v[148:151], v132 offset:1024
	ds_read_b128 v[152:155], v132 offset:2048
	ds_read_b128 v[156:159], v132 offset:3072
	v_add_u32_e32 v132, s47, v136
	ds_read_b128 v[160:163], v132
	ds_read_b128 v[164:167], v132 offset:1024
	ds_read_b128 v[168:171], v132 offset:2048
	ds_read_b128 v[172:175], v132 offset:3072
	s_mov_b32 m0, s19
	v_add_u32_e32 v132, s40, v139
	ds_read_b128 v[176:179], v143 offset:32768
	ds_read_b128 v[180:183], v143 offset:33792
	ds_read_b128 v[194:197], v143 offset:34816
	ds_read_b128 v[198:201], v143 offset:35840
	ds_read_b128 v[202:205], v143 offset:36864
	ds_read_b128 v[206:209], v143 offset:37888
	ds_read_b128 v[210:213], v143 offset:38912
	ds_read_b128 v[214:217], v143 offset:39936
	global_load_lds_dwordx4 v132, s[82:83]
	v_add_u32_e32 v132, s40, v140
	s_mov_b32 m0, s20
	s_nop 0
	global_load_lds_dwordx4 v132, s[82:83]
	s_waitcnt vmcnt(8)
	s_waitcnt lgkmcnt(0)
	s_barrier
	s_setprio 0
	s_waitcnt lgkmcnt(0)
	v_mfma_f32_16x16x32_bf16 v[124:127], v[144:147], v[176:179], v[124:127]
	v_mfma_f32_16x16x32_bf16 v[120:123], v[152:155], v[176:179], v[120:123]
	v_mfma_f32_16x16x32_bf16 v[116:119], v[144:147], v[194:197], v[116:119]
	v_mfma_f32_16x16x32_bf16 v[112:115], v[152:155], v[194:197], v[112:115]
	v_mfma_f32_16x16x32_bf16 v[108:111], v[144:147], v[202:205], v[108:111]
	v_mfma_f32_16x16x32_bf16 v[104:107], v[152:155], v[202:205], v[104:107]
	v_mfma_f32_16x16x32_bf16 v[100:103], v[144:147], v[210:213], v[100:103]
	v_mfma_f32_16x16x32_bf16 v[96:99], v[152:155], v[210:213], v[96:99]
	v_mfma_f32_16x16x32_bf16 v[124:127], v[148:151], v[180:183], v[124:127]
	v_mfma_f32_16x16x32_bf16 v[120:123], v[156:159], v[180:183], v[120:123]
	v_mfma_f32_16x16x32_bf16 v[116:119], v[148:151], v[198:201], v[116:119]
	v_mfma_f32_16x16x32_bf16 v[112:115], v[156:159], v[198:201], v[112:115]
	v_mfma_f32_16x16x32_bf16 v[108:111], v[148:151], v[206:209], v[108:111]
	v_mfma_f32_16x16x32_bf16 v[104:107], v[156:159], v[206:209], v[104:107]
	v_mfma_f32_16x16x32_bf16 v[100:103], v[148:151], v[214:217], v[100:103]
	v_mfma_f32_16x16x32_bf16 v[96:99], v[156:159], v[214:217], v[96:99]
	v_mfma_f32_16x16x32_bf16 v[92:95], v[160:163], v[176:179], v[92:95]
	v_mfma_f32_16x16x32_bf16 v[88:91], v[168:171], v[176:179], v[88:91]
	v_mfma_f32_16x16x32_bf16 v[84:87], v[160:163], v[194:197], v[84:87]
	v_mfma_f32_16x16x32_bf16 v[80:83], v[168:171], v[194:197], v[80:83]
	v_mfma_f32_16x16x32_bf16 v[76:79], v[160:163], v[202:205], v[76:79]
	v_mfma_f32_16x16x32_bf16 v[72:75], v[168:171], v[202:205], v[72:75]
	v_mfma_f32_16x16x32_bf16 v[68:71], v[160:163], v[210:213], v[68:71]
	v_mfma_f32_16x16x32_bf16 v[64:67], v[168:171], v[210:213], v[64:67]
	v_mfma_f32_16x16x32_bf16 v[92:95], v[164:167], v[180:183], v[92:95]
	v_mfma_f32_16x16x32_bf16 v[88:91], v[172:175], v[180:183], v[88:91]
	v_mfma_f32_16x16x32_bf16 v[84:87], v[164:167], v[198:201], v[84:87]
	v_mfma_f32_16x16x32_bf16 v[80:83], v[172:175], v[198:201], v[80:83]
	v_mfma_f32_16x16x32_bf16 v[76:79], v[164:167], v[206:209], v[76:79]
	v_mfma_f32_16x16x32_bf16 v[72:75], v[172:175], v[206:209], v[72:75]
	v_mfma_f32_16x16x32_bf16 v[68:71], v[164:167], v[214:217], v[68:71]
	v_mfma_f32_16x16x32_bf16 v[64:67], v[172:175], v[214:217], v[64:67]
	s_setprio 1
	s_barrier
; #define G_STAGE_A(bufoff, p0, p1, koff) do { \
;         __builtin_amdgcn_global_load_lds((const unsigned*)(gbase + (size_t)(unsigned)((p0) + (koff) + voffA[0])), (LAS unsigned*)(lds + (bufoff) + ldsw), 16, 0, 0); \
;         __builtin_amdgcn_global_load_lds((const unsigned*)(gbase + (size_t)(unsigned)((p1) + (koff) + voffA[1])), (LAS unsigned*)(lds + (bufoff) + ldsw + 8192), 16, 0, 0); } while (0)
; #define G_STAGE_B(bufoff, p, koff) do { \
;         __builtin_amdgcn_global_load_lds((const unsigned*)(gbase + (size_t)(unsigned)((p) + (koff) + voffB[0])), (LAS unsigned*)(lds + (bufoff) + ldsw), 16, 0, 0); \
;         __builtin_amdgcn_global_load_lds((const unsigned*)(gbase + (size_t)(unsigned)((p) + (koff) + voffB[1])), (LAS unsigned*)(lds + (bufoff) + ldsw + 8192), 16, 0, 0); } while (0)
; #define G_LDA(dst, b, h) do { _Pragma("unroll") for (int m = 0; m < 4; ++m) _Pragma("unroll") for (int k = 0; k < 2; ++k) dst[m][k] = *(const LAS bf16x8*)(lds + G_SA(b, h) + aoff + m * 2048 + k * 1024); } while (0)
; #define G_MMA(ai, bj, At, Bt) do { __builtin_amdgcn_s_setprio(1); _Pragma("unroll") for (int m = 0; m < 4; ++m) _Pragma("unroll") for (int n = 0; n < 2; ++n) _Pragma("unroll") for (int k = 0; k < 2; ++k) \
;         acc[ai][bj][m][n] = __builtin_amdgcn_mfma_f32_16x16x32_bf16(Bt[n][k], At[m][k], acc[ai][bj][m][n], 0, 0, 0); __builtin_amdgcn_s_setprio(0); } while (0)
; #define G_WAIT_V(n) asm volatile("s_waitcnt vmcnt(" #n ")" ::: "memory")
; #define G_WAIT_L(n) asm volatile("s_waitcnt lgkmcnt(" #n ")" ::: "memory")
; #define G_BAR __builtin_amdgcn_s_barrier()
; #define G_SCHED __builtin_amdgcn_sched_barrier(0)
; template <class Epi>
; DI void gemm_phase(LAS unsigned char* lds, const Sched& S, const Epi& E, const int K) {
;     ...
;             G_WAIT_V(8); G_WAIT_L(0); G_BAR; G_MMA(0, 0, At, B0); G_MMA(0, 1, At, B1); G_BAR; G_SCHED;
;             G_LDA(At, 1, 1); G_STAGE_B(G_SB(1, 0), xb, kb3); G_STAGE_B(G_SB(1, 1), xb + hstepB, kb3); G_STAGE_A(G_SA(1, 0), x0, x1, k3);
;             G_WAIT_V(8); G_WAIT_L(0); G_BAR; G_MMA(1, 0, At, B0); G_MMA(1, 1, At, B1); G_BAR; G_SCHED;
;     ...
;         }
;     ...
;         if (wr == 0) G_BAR;
	s_add_i32 s40, s45, s46
	s_add_i32 s13, s13, s16
	v_add_u32_e32 v132, s40, v134
	s_mov_b32 m0, s13
	ds_read_b128 v[176:179], v143 offset:49152
	ds_read_b128 v[180:183], v143 offset:50176
	ds_read_b128 v[194:197], v143 offset:51200
	ds_read_b128 v[198:201], v143 offset:52224
	ds_read_b128 v[202:205], v143 offset:53248
	ds_read_b128 v[206:209], v143 offset:54272
	ds_read_b128 v[210:213], v143 offset:55296
	ds_read_b128 v[214:217], v143 offset:56320
	global_load_lds_dwordx4 v132, s[82:83]
	v_add_u32_e32 v132, s40, v135
	s_add_i32 m0, s13, 0x2000
	s_add_i32 s12, s45, s12
	s_add_i32 s13, s47, s16
	global_load_lds_dwordx4 v132, s[82:83]
	v_add_u32_e32 v132, s12, v134
	s_mov_b32 m0, s13
	s_nop 0
	global_load_lds_dwordx4 v132, s[82:83]
	v_add_u32_e32 v132, s12, v135
	s_add_i32 m0, s13, 0x2000
	s_nop 0
	global_load_lds_dwordx4 v132, s[82:83]
	v_add_u32_e32 v132, s45, v141
	s_mov_b32 m0, s21
	s_nop 0
	global_load_lds_dwordx4 v132, s[82:83]
	v_add_u32_e32 v132, s45, v142
	s_mov_b32 m0, s24
	s_nop 0
	global_load_lds_dwordx4 v132, s[82:83]
	s_waitcnt vmcnt(8)
	s_waitcnt lgkmcnt(0)
	s_barrier
	s_setprio 0
	s_waitcnt lgkmcnt(0)
	v_mfma_f32_16x16x32_bf16 v[60:63], v[144:147], v[176:179], v[60:63]
	v_mfma_f32_16x16x32_bf16 v[56:59], v[152:155], v[176:179], v[56:59]
	v_mfma_f32_16x16x32_bf16 v[52:55], v[144:147], v[194:197], v[52:55]
	v_mfma_f32_16x16x32_bf16 v[48:51], v[152:155], v[194:197], v[48:51]
	v_mfma_f32_16x16x32_bf16 v[44:47], v[144:147], v[202:205], v[44:47]
	v_mfma_f32_16x16x32_bf16 v[40:43], v[152:155], v[202:205], v[40:43]
	v_mfma_f32_16x16x32_bf16 v[36:39], v[144:147], v[210:213], v[36:39]
	v_mfma_f32_16x16x32_bf16 v[32:35], v[152:155], v[210:213], v[32:35]
	v_mfma_f32_16x16x32_bf16 v[60:63], v[148:151], v[180:183], v[60:63]
	v_mfma_f32_16x16x32_bf16 v[56:59], v[156:159], v[180:183], v[56:59]
	v_mfma_f32_16x16x32_bf16 v[52:55], v[148:151], v[198:201], v[52:55]
	v_mfma_f32_16x16x32_bf16 v[48:51], v[156:159], v[198:201], v[48:51]
	v_mfma_f32_16x16x32_bf16 v[44:47], v[148:151], v[206:209], v[44:47]
	v_mfma_f32_16x16x32_bf16 v[40:43], v[156:159], v[206:209], v[40:43]
	v_mfma_f32_16x16x32_bf16 v[36:39], v[148:151], v[214:217], v[36:39]
	v_mfma_f32_16x16x32_bf16 v[32:35], v[156:159], v[214:217], v[32:35]
	v_mfma_f32_16x16x32_bf16 v[28:31], v[160:163], v[176:179], v[28:31]
	v_mfma_f32_16x16x32_bf16 v[24:27], v[168:171], v[176:179], v[24:27]
	v_mfma_f32_16x16x32_bf16 v[20:23], v[160:163], v[194:197], v[20:23]
	v_mfma_f32_16x16x32_bf16 v[16:19], v[168:171], v[194:197], v[16:19]
	v_mfma_f32_16x16x32_bf16 v[12:15], v[160:163], v[202:205], v[12:15]
	v_mfma_f32_16x16x32_bf16 v[8:11], v[168:171], v[202:205], v[8:11]
	v_mfma_f32_16x16x32_bf16 v[4:7], v[160:163], v[210:213], v[4:7]
	v_mfma_f32_16x16x32_bf16 v[0:3], v[168:171], v[210:213], v[0:3]
	v_mfma_f32_16x16x32_bf16 v[28:31], v[164:167], v[180:183], v[28:31]
	v_mfma_f32_16x16x32_bf16 v[24:27], v[172:175], v[180:183], v[24:27]
	v_mfma_f32_16x16x32_bf16 v[20:23], v[164:167], v[198:201], v[20:23]
	v_mfma_f32_16x16x32_bf16 v[16:19], v[172:175], v[198:201], v[16:19]
	v_mfma_f32_16x16x32_bf16 v[12:15], v[164:167], v[206:209], v[12:15]
	v_mfma_f32_16x16x32_bf16 v[8:11], v[172:175], v[206:209], v[8:11]
	v_mfma_f32_16x16x32_bf16 v[4:7], v[164:167], v[214:217], v[4:7]
	v_mfma_f32_16x16x32_bf16 v[0:3], v[172:175], v[214:217], v[0:3]
	s_setprio 1
	s_barrier
	s_add_i32 s44, s44, 2
	s_cmp_gt_u32 s44, 5
	s_mov_b64 s[12:13], s[14:15]
	s_cbranch_scc0 .LBB0_281
	s_and_b64 vcc, exec, s[6:7]
	s_cbranch_vccz .LBB0_284
	s_barrier

; #define G_STAGE_A(bufoff, p0, p1, koff) do { \
;         __builtin_amdgcn_global_load_lds((const unsigned*)(gbase + (size_t)(unsigned)((p0) + (koff) + voffA[0])), (LAS unsigned*)(lds + (bufoff) + ldsw), 16, 0, 0); \
;         __builtin_amdgcn_global_load_lds((const unsigned*)(gbase + (size_t)(unsigned)((p1) + (koff) + voffA[1])), (LAS unsigned*)(lds + (bufoff) + ldsw + 8192), 16, 0, 0); } while (0)
; #define G_STAGE_B(bufoff, p, koff) do { \
;         __builtin_amdgcn_global_load_lds((const unsigned*)(gbase + (size_t)(unsigned)((p) + (koff) + voffB[0])), (LAS unsigned*)(lds + (bufoff) + ldsw), 16, 0, 0); \
;         __builtin_amdgcn_global_load_lds((const unsigned*)(gbase + (size_t)(unsigned)((p) + (koff) + voffB[1])), (LAS unsigned*)(lds + (bufoff) + ldsw + 8192), 16, 0, 0); } while (0)
; #define G_LDA(dst, b, h) do { _Pragma("unroll") for (int m = 0; m < 4; ++m) _Pragma("unroll") for (int k = 0; k < 2; ++k) dst[m][k] = *(const LAS bf16x8*)(lds + G_SA(b, h) + aoff + m * 2048 + k * 1024); } while (0)
; #define G_LDB(dst, b, h) do { _Pragma("unroll") for (int n = 0; n < 2; ++n) _Pragma("unroll") for (int k = 0; k < 2; ++k) dst[n][k] = *(const LAS bf16x8*)(lds + G_SB(b, h) + boff + n * 2048 + k * 1024); } while (0)
; #define G_BAR __builtin_amdgcn_s_barrier()
; template <class Epi>
; DI void gemm_phase(LAS unsigned char* lds, const Sched& S, const Epi& E, const int K) {
;     ...
;         for (int t = 0; t < nt; t += 2) {
;             const bool last = (t == nt - 2);
;             const unsigned k1 = (unsigned)(t + 1) * kstepA;
;             const unsigned k2 = last ? 0u : (unsigned)(t + 2) * kstepA, k3 = k2 + kstepA;
;             const unsigned kb2 = last ? 0u : (unsigned)(t + 2) * kstepB, kb3 = kb2 + kstepB;
;             const unsigned x0 = last ? n0 : cur.a0, x1 = last ? n1 : cur.a1, x2 = last ? n2 : cur.a2, x3 = last ? n3 : cur.a3;
;             const unsigned xb = last ? nB : cur.b;
;     ...
;             G_LDB(B0, 0, 0); G_LDB(B1, 0, 1); G_SCHED; G_LDA(At, 0, 0); G_STAGE_A(G_SA(1, 1), cur.a2, cur.a3, k1);
;             G_WAIT_V(8); G_WAIT_L(0); G_BAR; G_MMA(0, 0, At, B0); G_MMA(0, 1, At, B1); G_BAR; G_SCHED;
;             G_LDA(At, 0, 1); G_STAGE_B(G_SB(0, 0), xb, kb2); G_STAGE_B(G_SB(0, 1), xb + hstepB, kb2); G_STAGE_A(G_SA(0, 0), x0, x1, k2);
;             G_WAIT_V(8); G_WAIT_L(0); G_BAR; G_MMA(1, 0, At, B0); G_MMA(1, 1, At, B1); G_BAR; G_SCHED;
.LBB0_318:
	s_add_i32 s40, s86, 0x80
	v_add_u32_e32 v222, s80, v128
	v_add_u32_e32 v224, s40, v129
	v_add_u32_e32 v225, s40, v131
	s_add_i32 s40, 0, 0x10000
	s_add_i32 s80, 0, 0x14000
	v_add_u32_e32 v154, s40, v133
	v_add_u32_e32 v170, s80, v133
	ds_read_b128 v[142:145], v154
	ds_read_b128 v[146:149], v154 offset:1024
	ds_read_b128 v[150:153], v154 offset:2048
	ds_read_b128 v[154:157], v154 offset:3072
	ds_read_b128 v[158:161], v170
	ds_read_b128 v[162:165], v170 offset:1024
	ds_read_b128 v[166:169], v170 offset:2048
	ds_read_b128 v[170:173], v170 offset:3072
	s_add_i32 s36, s86, s44
	v_add_u32_e32 v218, s36, v129
	v_add_u32_e32 v219, s36, v131
	s_addk_i32 s36, 0x80
	v_add_u32_e32 v141, s50, v134
	v_add_u32_e32 v182, s47, v139
	v_add_u32_e32 v183, s86, v129
	v_add_u32_e32 v184, s86, v131
	v_add_u32_e32 v220, s37, v128
	v_add_u32_e32 v221, s79, v130
	v_add_u32_e32 v223, s81, v130
	v_add_u32_e32 v226, s36, v129
	v_add_u32_e32 v229, s36, v131
	v_add_u32_e32 v233, s37, v134
	v_add_u32_e32 v234, s79, v139
	s_add_i32 m0, s46, 0xc000
	ds_read_b128 v[174:177], v140
	ds_read_b128 v[178:181], v140 offset:1024
	ds_read_b128 v[194:197], v140 offset:2048
	ds_read_b128 v[198:201], v140 offset:3072
	ds_read_b128 v[202:205], v140 offset:4096
	ds_read_b128 v[206:209], v140 offset:5120
	ds_read_b128 v[210:213], v140 offset:6144
	ds_read_b128 v[214:217], v140 offset:7168
	global_load_lds_dwordx4 v141, s[82:83]
	s_add_i32 m0, s46, 0xe000
	s_nop 0
	global_load_lds_dwordx4 v182, s[82:83]
	s_waitcnt vmcnt(8)
	s_waitcnt lgkmcnt(0)
	s_barrier
	s_setprio 0
	s_waitcnt lgkmcnt(0)
	v_mfma_f32_16x16x32_bf16 v[124:127], v[142:145], v[174:177], v[124:127]
	v_mfma_f32_16x16x32_bf16 v[120:123], v[150:153], v[174:177], v[120:123]
	v_mfma_f32_16x16x32_bf16 v[116:119], v[142:145], v[194:197], v[116:119]
	v_mfma_f32_16x16x32_bf16 v[112:115], v[150:153], v[194:197], v[112:115]
	v_mfma_f32_16x16x32_bf16 v[108:111], v[142:145], v[202:205], v[108:111]
	v_mfma_f32_16x16x32_bf16 v[104:107], v[150:153], v[202:205], v[104:107]
	v_mfma_f32_16x16x32_bf16 v[100:103], v[142:145], v[210:213], v[100:103]
	v_mfma_f32_16x16x32_bf16 v[96:99], v[150:153], v[210:213], v[96:99]
	v_mfma_f32_16x16x32_bf16 v[124:127], v[146:149], v[178:181], v[124:127]
	v_mfma_f32_16x16x32_bf16 v[120:123], v[154:157], v[178:181], v[120:123]
	v_mfma_f32_16x16x32_bf16 v[116:119], v[146:149], v[198:201], v[116:119]
	v_mfma_f32_16x16x32_bf16 v[112:115], v[154:157], v[198:201], v[112:115]
	v_mfma_f32_16x16x32_bf16 v[108:111], v[146:149], v[206:209], v[108:111]
	v_mfma_f32_16x16x32_bf16 v[104:107], v[154:157], v[206:209], v[104:107]
	v_mfma_f32_16x16x32_bf16 v[100:103], v[146:149], v[214:217], v[100:103]
	v_mfma_f32_16x16x32_bf16 v[96:99], v[154:157], v[214:217], v[96:99]
	v_mfma_f32_16x16x32_bf16 v[92:95], v[158:161], v[174:177], v[92:95]
	v_mfma_f32_16x16x32_bf16 v[88:91], v[166:169], v[174:177], v[88:91]
	v_mfma_f32_16x16x32_bf16 v[84:87], v[158:161], v[194:197], v[84:87]
	v_mfma_f32_16x16x32_bf16 v[80:83], v[166:169], v[194:197], v[80:83]
	v_mfma_f32_16x16x32_bf16 v[76:79], v[158:161], v[202:205], v[76:79]
	v_mfma_f32_16x16x32_bf16 v[72:75], v[166:169], v[202:205], v[72:75]
	v_mfma_f32_16x16x32_bf16 v[68:71], v[158:161], v[210:213], v[68:71]
	v_mfma_f32_16x16x32_bf16 v[64:67], v[166:169], v[210:213], v[64:67]
	v_mfma_f32_16x16x32_bf16 v[92:95], v[162:165], v[178:181], v[92:95]
	v_mfma_f32_16x16x32_bf16 v[88:91], v[170:173], v[178:181], v[88:91]
	v_mfma_f32_16x16x32_bf16 v[84:87], v[162:165], v[198:201], v[84:87]
	v_mfma_f32_16x16x32_bf16 v[80:83], v[170:173], v[198:201], v[80:83]
	v_mfma_f32_16x16x32_bf16 v[76:79], v[162:165], v[206:209], v[76:79]
	v_mfma_f32_16x16x32_bf16 v[72:75], v[170:173], v[206:209], v[72:75]
	v_mfma_f32_16x16x32_bf16 v[68:71], v[162:165], v[214:217], v[68:71]
	v_mfma_f32_16x16x32_bf16 v[64:67], v[170:173], v[214:217], v[64:67]
	s_setprio 1
	s_barrier
	s_add_i32 s36, s40, s45
	s_mov_b32 m0, s36
	ds_read_b128 v[174:177], v140 offset:16384
	ds_read_b128 v[178:181], v140 offset:17408
	ds_read_b128 v[194:197], v140 offset:18432
	ds_read_b128 v[198:201], v140 offset:19456
	ds_read_b128 v[202:205], v140 offset:20480
	ds_read_b128 v[206:209], v140 offset:21504
	ds_read_b128 v[210:213], v140 offset:22528
	ds_read_b128 v[214:217], v140 offset:23552
	global_load_lds_dwordx4 v183, s[82:83]
	s_add_i32 m0, s36, 0x2000
	s_add_i32 s36, s80, s45
	global_load_lds_dwordx4 v184, s[82:83]
	s_mov_b32 m0, s36
	s_nop 0
	global_load_lds_dwordx4 v218, s[82:83]
	s_add_i32 m0, s36, 0x2000
	s_nop 0
	global_load_lds_dwordx4 v219, s[82:83]
	s_mov_b32 m0, s46
	s_nop 0
	global_load_lds_dwordx4 v220, s[82:83]
	s_mov_b32 m0, s56
	s_nop 0
	global_load_lds_dwordx4 v221, s[82:83]
	s_waitcnt vmcnt(8)
	s_waitcnt lgkmcnt(0)
	s_barrier
; #define G_STAGE_A(bufoff, p0, p1, koff) do { \
;         __builtin_amdgcn_global_load_lds((const unsigned*)(gbase + (size_t)(unsigned)((p0) + (koff) + voffA[0])), (LAS unsigned*)(lds + (bufoff) + ldsw), 16, 0, 0); \
;         __builtin_amdgcn_global_load_lds((const unsigned*)(gbase + (size_t)(unsigned)((p1) + (koff) + voffA[1])), (LAS unsigned*)(lds + (bufoff) + ldsw + 8192), 16, 0, 0); } while (0)
; #define G_LDA(dst, b, h) do { _Pragma("unroll") for (int m = 0; m < 4; ++m) _Pragma("unroll") for (int k = 0; k < 2; ++k) dst[m][k] = *(const LAS bf16x8*)(lds + G_SA(b, h) + aoff + m * 2048 + k * 1024); } while (0)
; #define G_LDB(dst, b, h) do { _Pragma("unroll") for (int n = 0; n < 2; ++n) _Pragma("unroll") for (int k = 0; k < 2; ++k) dst[n][k] = *(const LAS bf16x8*)(lds + G_SB(b, h) + boff + n * 2048 + k * 1024); } while (0)
; #define G_MMA(ai, bj, At, Bt) do { __builtin_amdgcn_s_setprio(1); _Pragma("unroll") for (int m = 0; m < 4; ++m) _Pragma("unroll") for (int n = 0; n < 2; ++n) _Pragma("unroll") for (int k = 0; k < 2; ++k) \
;         acc[ai][bj][m][n] = __builtin_amdgcn_mfma_f32_16x16x32_bf16(Bt[n][k], At[m][k], acc[ai][bj][m][n], 0, 0, 0); __builtin_amdgcn_s_setprio(0); } while (0)
; #define G_WAIT_V(n) asm volatile("s_waitcnt vmcnt(" #n ")" ::: "memory")
; #define G_WAIT_L(n) asm volatile("s_waitcnt lgkmcnt(" #n ")" ::: "memory")
; #define G_BAR __builtin_amdgcn_s_barrier()
; #define G_SCHED __builtin_amdgcn_sched_barrier(0)
; template <class Epi>
; DI void gemm_phase(LAS unsigned char* lds, const Sched& S, const Epi& E, const int K) {
;     ...
;             G_WAIT_V(8); G_WAIT_L(0); G_BAR; G_MMA(1, 0, At, B0); G_MMA(1, 1, At, B1); G_BAR; G_SCHED;
;             G_LDB(B0, 1, 0); G_LDB(B1, 1, 1); G_SCHED; G_LDA(At, 1, 0); G_STAGE_A(G_SA(0, 1), x2, x3, k2);
;             G_WAIT_V(8); G_WAIT_L(0); G_BAR; G_MMA(0, 0, At, B0); G_MMA(0, 1, At, B1); G_BAR; G_SCHED;
	s_setprio 0
	s_waitcnt lgkmcnt(0)
	v_mfma_f32_16x16x32_bf16 v[60:63], v[142:145], v[174:177], v[60:63]
	v_mfma_f32_16x16x32_bf16 v[56:59], v[150:153], v[174:177], v[56:59]
	v_mfma_f32_16x16x32_bf16 v[52:55], v[142:145], v[194:197], v[52:55]
	v_mfma_f32_16x16x32_bf16 v[48:51], v[150:153], v[194:197], v[48:51]
	v_mfma_f32_16x16x32_bf16 v[44:47], v[142:145], v[202:205], v[44:47]
	v_mfma_f32_16x16x32_bf16 v[40:43], v[150:153], v[202:205], v[40:43]
	v_mfma_f32_16x16x32_bf16 v[36:39], v[142:145], v[210:213], v[36:39]
	v_mfma_f32_16x16x32_bf16 v[32:35], v[150:153], v[210:213], v[32:35]
	v_mfma_f32_16x16x32_bf16 v[60:63], v[146:149], v[178:181], v[60:63]
	v_mfma_f32_16x16x32_bf16 v[56:59], v[154:157], v[178:181], v[56:59]
	v_mfma_f32_16x16x32_bf16 v[52:55], v[146:149], v[198:201], v[52:55]
	v_mfma_f32_16x16x32_bf16 v[48:51], v[154:157], v[198:201], v[48:51]
	v_mfma_f32_16x16x32_bf16 v[44:47], v[146:149], v[206:209], v[44:47]
	v_mfma_f32_16x16x32_bf16 v[40:43], v[154:157], v[206:209], v[40:43]
	v_mfma_f32_16x16x32_bf16 v[36:39], v[146:149], v[214:217], v[36:39]
	v_mfma_f32_16x16x32_bf16 v[32:35], v[154:157], v[214:217], v[32:35]
	v_mfma_f32_16x16x32_bf16 v[28:31], v[158:161], v[174:177], v[28:31]
	v_mfma_f32_16x16x32_bf16 v[24:27], v[166:169], v[174:177], v[24:27]
	v_mfma_f32_16x16x32_bf16 v[20:23], v[158:161], v[194:197], v[20:23]
	v_mfma_f32_16x16x32_bf16 v[16:19], v[166:169], v[194:197], v[16:19]
	v_mfma_f32_16x16x32_bf16 v[12:15], v[158:161], v[202:205], v[12:15]
	v_mfma_f32_16x16x32_bf16 v[8:11], v[166:169], v[202:205], v[8:11]
	v_mfma_f32_16x16x32_bf16 v[4:7], v[158:161], v[210:213], v[4:7]
	v_mfma_f32_16x16x32_bf16 v[0:3], v[166:169], v[210:213], v[0:3]
	v_mfma_f32_16x16x32_bf16 v[28:31], v[162:165], v[178:181], v[28:31]
	v_mfma_f32_16x16x32_bf16 v[24:27], v[170:173], v[178:181], v[24:27]
	v_mfma_f32_16x16x32_bf16 v[20:23], v[162:165], v[198:201], v[20:23]
	v_mfma_f32_16x16x32_bf16 v[16:19], v[170:173], v[198:201], v[16:19]
	v_mfma_f32_16x16x32_bf16 v[12:15], v[162:165], v[206:209], v[12:15]
	v_mfma_f32_16x16x32_bf16 v[8:11], v[170:173], v[206:209], v[8:11]
	v_mfma_f32_16x16x32_bf16 v[4:7], v[162:165], v[214:217], v[4:7]
	v_mfma_f32_16x16x32_bf16 v[0:3], v[170:173], v[214:217], v[0:3]
	s_setprio 1
	s_barrier
	s_add_i32 s36, 0, 0x18000
	v_add_u32_e32 v141, s36, v133
	s_add_i32 s37, 0, 0x1c000
	ds_read_b128 v[142:145], v141
	ds_read_b128 v[146:149], v141 offset:1024
	ds_read_b128 v[150:153], v141 offset:2048
	ds_read_b128 v[154:157], v141 offset:3072
	v_add_u32_e32 v141, s37, v133
	ds_read_b128 v[158:161], v141
	ds_read_b128 v[162:165], v141 offset:1024
	ds_read_b128 v[166:169], v141 offset:2048
	ds_read_b128 v[170:173], v141 offset:3072
	s_mov_b32 m0, s57
	ds_read_b128 v[174:177], v140 offset:32768
	ds_read_b128 v[178:181], v140 offset:33792
	ds_read_b128 v[194:197], v140 offset:34816
	ds_read_b128 v[198:201], v140 offset:35840
	ds_read_b128 v[202:205], v140 offset:36864
	ds_read_b128 v[206:209], v140 offset:37888
	ds_read_b128 v[210:213], v140 offset:38912
	ds_read_b128 v[214:217], v140 offset:39936
	global_load_lds_dwordx4 v222, s[82:83]
	s_mov_b32 m0, s58
	s_nop 0
	global_load_lds_dwordx4 v223, s[82:83]
	s_waitcnt vmcnt(8)
	s_waitcnt lgkmcnt(0)
	s_barrier
; #define G_STAGE_A(bufoff, p0, p1, koff) do { \
;         __builtin_amdgcn_global_load_lds((const unsigned*)(gbase + (size_t)(unsigned)((p0) + (koff) + voffA[0])), (LAS unsigned*)(lds + (bufoff) + ldsw), 16, 0, 0); \
;         __builtin_amdgcn_global_load_lds((const unsigned*)(gbase + (size_t)(unsigned)((p1) + (koff) + voffA[1])), (LAS unsigned*)(lds + (bufoff) + ldsw + 8192), 16, 0, 0); } while (0)
; #define G_STAGE_B(bufoff, p, koff) do { \
;         __builtin_amdgcn_global_load_lds((const unsigned*)(gbase + (size_t)(unsigned)((p) + (koff) + voffB[0])), (LAS unsigned*)(lds + (bufoff) + ldsw), 16, 0, 0); \
;         __builtin_amdgcn_global_load_lds((const unsigned*)(gbase + (size_t)(unsigned)((p) + (koff) + voffB[1])), (LAS unsigned*)(lds + (bufoff) + ldsw + 8192), 16, 0, 0); } while (0)
; #define G_LDA(dst, b, h) do { _Pragma("unroll") for (int m = 0; m < 4; ++m) _Pragma("unroll") for (int k = 0; k < 2; ++k) dst[m][k] = *(const LAS bf16x8*)(lds + G_SA(b, h) + aoff + m * 2048 + k * 1024); } while (0)
; #define G_MMA(ai, bj, At, Bt) do { __builtin_amdgcn_s_setprio(1); _Pragma("unroll") for (int m = 0; m < 4; ++m) _Pragma("unroll") for (int n = 0; n < 2; ++n) _Pragma("unroll") for (int k = 0; k < 2; ++k) \
;         acc[ai][bj][m][n] = __builtin_amdgcn_mfma_f32_16x16x32_bf16(Bt[n][k], At[m][k], acc[ai][bj][m][n], 0, 0, 0); __builtin_amdgcn_s_setprio(0); } while (0)
; #define G_WAIT_V(n) asm volatile("s_waitcnt vmcnt(" #n ")" ::: "memory")
; #define G_WAIT_L(n) asm volatile("s_waitcnt lgkmcnt(" #n ")" ::: "memory")
; #define G_BAR __builtin_amdgcn_s_barrier()
; #define G_SCHED __builtin_amdgcn_sched_barrier(0)
; template <class Epi>
; DI void gemm_phase(LAS unsigned char* lds, const Sched& S, const Epi& E, const int K) {
;     ...
;             G_WAIT_V(8); G_WAIT_L(0); G_BAR; G_MMA(0, 0, At, B0); G_MMA(0, 1, At, B1); G_BAR; G_SCHED;
;             G_LDA(At, 1, 1); G_STAGE_B(G_SB(1, 0), xb, kb3); G_STAGE_B(G_SB(1, 1), xb + hstepB, kb3); G_STAGE_A(G_SA(1, 0), x0, x1, k3);
;             G_WAIT_V(8); G_WAIT_L(0); G_BAR; G_MMA(1, 0, At, B0); G_MMA(1, 1, At, B1); G_BAR; G_SCHED;
;     ...
;         }
;     ...
;         if (wr == 0) G_BAR;
	s_setprio 0
	s_waitcnt lgkmcnt(0)
	v_mfma_f32_16x16x32_bf16 v[124:127], v[142:145], v[174:177], v[124:127]
	v_mfma_f32_16x16x32_bf16 v[120:123], v[150:153], v[174:177], v[120:123]
	v_mfma_f32_16x16x32_bf16 v[116:119], v[142:145], v[194:197], v[116:119]
	v_mfma_f32_16x16x32_bf16 v[112:115], v[150:153], v[194:197], v[112:115]
	v_mfma_f32_16x16x32_bf16 v[108:111], v[142:145], v[202:205], v[108:111]
	v_mfma_f32_16x16x32_bf16 v[104:107], v[150:153], v[202:205], v[104:107]
	v_mfma_f32_16x16x32_bf16 v[100:103], v[142:145], v[210:213], v[100:103]
	v_mfma_f32_16x16x32_bf16 v[96:99], v[150:153], v[210:213], v[96:99]
	v_mfma_f32_16x16x32_bf16 v[124:127], v[146:149], v[178:181], v[124:127]
	v_mfma_f32_16x16x32_bf16 v[120:123], v[154:157], v[178:181], v[120:123]
	v_mfma_f32_16x16x32_bf16 v[116:119], v[146:149], v[198:201], v[116:119]
	v_mfma_f32_16x16x32_bf16 v[112:115], v[154:157], v[198:201], v[112:115]
	v_mfma_f32_16x16x32_bf16 v[108:111], v[146:149], v[206:209], v[108:111]
	v_mfma_f32_16x16x32_bf16 v[104:107], v[154:157], v[206:209], v[104:107]
	v_mfma_f32_16x16x32_bf16 v[100:103], v[146:149], v[214:217], v[100:103]
	v_mfma_f32_16x16x32_bf16 v[96:99], v[154:157], v[214:217], v[96:99]
	v_mfma_f32_16x16x32_bf16 v[92:95], v[158:161], v[174:177], v[92:95]
	v_mfma_f32_16x16x32_bf16 v[88:91], v[166:169], v[174:177], v[88:91]
	v_mfma_f32_16x16x32_bf16 v[84:87], v[158:161], v[194:197], v[84:87]
	v_mfma_f32_16x16x32_bf16 v[80:83], v[166:169], v[194:197], v[80:83]
	v_mfma_f32_16x16x32_bf16 v[76:79], v[158:161], v[202:205], v[76:79]
	v_mfma_f32_16x16x32_bf16 v[72:75], v[166:169], v[202:205], v[72:75]
	v_mfma_f32_16x16x32_bf16 v[68:71], v[158:161], v[210:213], v[68:71]
	v_mfma_f32_16x16x32_bf16 v[64:67], v[166:169], v[210:213], v[64:67]
	v_mfma_f32_16x16x32_bf16 v[92:95], v[162:165], v[178:181], v[92:95]
	v_mfma_f32_16x16x32_bf16 v[88:91], v[170:173], v[178:181], v[88:91]
	v_mfma_f32_16x16x32_bf16 v[84:87], v[162:165], v[198:201], v[84:87]
	v_mfma_f32_16x16x32_bf16 v[80:83], v[170:173], v[198:201], v[80:83]
	v_mfma_f32_16x16x32_bf16 v[76:79], v[162:165], v[206:209], v[76:79]
	v_mfma_f32_16x16x32_bf16 v[72:75], v[170:173], v[206:209], v[72:75]
	v_mfma_f32_16x16x32_bf16 v[68:71], v[162:165], v[214:217], v[68:71]
	v_mfma_f32_16x16x32_bf16 v[64:67], v[170:173], v[214:217], v[64:67]
	s_setprio 1
	s_barrier
	s_add_i32 s36, s36, s45
	s_mov_b32 m0, s36
	ds_read_b128 v[174:177], v140 offset:49152
	ds_read_b128 v[178:181], v140 offset:50176
	ds_read_b128 v[194:197], v140 offset:51200
	ds_read_b128 v[198:201], v140 offset:52224
	ds_read_b128 v[202:205], v140 offset:53248
	ds_read_b128 v[206:209], v140 offset:54272
	ds_read_b128 v[210:213], v140 offset:55296
	ds_read_b128 v[214:217], v140 offset:56320
	global_load_lds_dwordx4 v224, s[82:83]
	s_add_i32 m0, s36, 0x2000
	s_add_i32 s36, s37, s45
	global_load_lds_dwordx4 v225, s[82:83]
	s_mov_b32 m0, s36
	s_nop 0
	global_load_lds_dwordx4 v226, s[82:83]
	s_add_i32 m0, s36, 0x2000
	s_nop 0
	global_load_lds_dwordx4 v229, s[82:83]
	s_mov_b32 m0, s59
	s_nop 0
	global_load_lds_dwordx4 v233, s[82:83]
	s_mov_b32 m0, s60
	s_nop 0
	global_load_lds_dwordx4 v234, s[82:83]
	s_waitcnt vmcnt(8)
	s_waitcnt lgkmcnt(0)
	s_barrier
	s_setprio 0
	s_waitcnt lgkmcnt(0)
	v_mfma_f32_16x16x32_bf16 v[60:63], v[142:145], v[174:177], v[60:63]
	v_mfma_f32_16x16x32_bf16 v[56:59], v[150:153], v[174:177], v[56:59]
	v_mfma_f32_16x16x32_bf16 v[52:55], v[142:145], v[194:197], v[52:55]
	v_mfma_f32_16x16x32_bf16 v[48:51], v[150:153], v[194:197], v[48:51]
	v_mfma_f32_16x16x32_bf16 v[44:47], v[142:145], v[202:205], v[44:47]
	v_mfma_f32_16x16x32_bf16 v[40:43], v[150:153], v[202:205], v[40:43]
	v_mfma_f32_16x16x32_bf16 v[36:39], v[142:145], v[210:213], v[36:39]
	v_mfma_f32_16x16x32_bf16 v[32:35], v[150:153], v[210:213], v[32:35]
	v_mfma_f32_16x16x32_bf16 v[60:63], v[146:149], v[178:181], v[60:63]
	v_mfma_f32_16x16x32_bf16 v[56:59], v[154:157], v[178:181], v[56:59]
	v_mfma_f32_16x16x32_bf16 v[52:55], v[146:149], v[198:201], v[52:55]
	v_mfma_f32_16x16x32_bf16 v[48:51], v[154:157], v[198:201], v[48:51]
	v_mfma_f32_16x16x32_bf16 v[44:47], v[146:149], v[206:209], v[44:47]
	v_mfma_f32_16x16x32_bf16 v[40:43], v[154:157], v[206:209], v[40:43]
	v_mfma_f32_16x16x32_bf16 v[36:39], v[146:149], v[214:217], v[36:39]
	v_mfma_f32_16x16x32_bf16 v[32:35], v[154:157], v[214:217], v[32:35]
	v_mfma_f32_16x16x32_bf16 v[28:31], v[158:161], v[174:177], v[28:31]
	v_mfma_f32_16x16x32_bf16 v[24:27], v[166:169], v[174:177], v[24:27]
	v_mfma_f32_16x16x32_bf16 v[20:23], v[158:161], v[194:197], v[20:23]
	v_mfma_f32_16x16x32_bf16 v[16:19], v[166:169], v[194:197], v[16:19]
	v_mfma_f32_16x16x32_bf16 v[12:15], v[158:161], v[202:205], v[12:15]
	v_mfma_f32_16x16x32_bf16 v[8:11], v[166:169], v[202:205], v[8:11]
	v_mfma_f32_16x16x32_bf16 v[4:7], v[158:161], v[210:213], v[4:7]
	v_mfma_f32_16x16x32_bf16 v[0:3], v[166:169], v[210:213], v[0:3]
	v_mfma_f32_16x16x32_bf16 v[28:31], v[162:165], v[178:181], v[28:31]
	v_mfma_f32_16x16x32_bf16 v[24:27], v[170:173], v[178:181], v[24:27]
	v_mfma_f32_16x16x32_bf16 v[20:23], v[162:165], v[198:201], v[20:23]
	v_mfma_f32_16x16x32_bf16 v[16:19], v[170:173], v[198:201], v[16:19]
	v_mfma_f32_16x16x32_bf16 v[12:15], v[162:165], v[206:209], v[12:15]
	v_mfma_f32_16x16x32_bf16 v[8:11], v[170:173], v[206:209], v[8:11]
	v_mfma_f32_16x16x32_bf16 v[4:7], v[162:165], v[214:217], v[4:7]
	v_mfma_f32_16x16x32_bf16 v[0:3], v[170:173], v[214:217], v[0:3]
	s_setprio 1
	s_barrier
	s_andn2_b64 vcc, exec, s[24:25]
	s_cbranch_vccnz .LBB0_320
	s_barrier

; #define G_STAGE_A(bufoff, p0, p1, koff) do { \
;         __builtin_amdgcn_global_load_lds((const unsigned*)(gbase + (size_t)(unsigned)((p0) + (koff) + voffA[0])), (LAS unsigned*)(lds + (bufoff) + ldsw), 16, 0, 0); \
;         __builtin_amdgcn_global_load_lds((const unsigned*)(gbase + (size_t)(unsigned)((p1) + (koff) + voffA[1])), (LAS unsigned*)(lds + (bufoff) + ldsw + 8192), 16, 0, 0); } while (0)
; #define G_STAGE_B(bufoff, p, koff) do { \
;         __builtin_amdgcn_global_load_lds((const unsigned*)(gbase + (size_t)(unsigned)((p) + (koff) + voffB[0])), (LAS unsigned*)(lds + (bufoff) + ldsw), 16, 0, 0); \
;         __builtin_amdgcn_global_load_lds((const unsigned*)(gbase + (size_t)(unsigned)((p) + (koff) + voffB[1])), (LAS unsigned*)(lds + (bufoff) + ldsw + 8192), 16, 0, 0); } while (0)
; #define G_LDA(dst, b, h) do { _Pragma("unroll") for (int m = 0; m < 4; ++m) _Pragma("unroll") for (int k = 0; k < 2; ++k) dst[m][k] = *(const LAS bf16x8*)(lds + G_SA(b, h) + aoff + m * 2048 + k * 1024); } while (0)
; #define G_LDB(dst, b, h) do { _Pragma("unroll") for (int n = 0; n < 2; ++n) _Pragma("unroll") for (int k = 0; k < 2; ++k) dst[n][k] = *(const LAS bf16x8*)(lds + G_SB(b, h) + boff + n * 2048 + k * 1024); } while (0)
; #define G_WAIT_V(n) asm volatile("s_waitcnt vmcnt(" #n ")" ::: "memory")
; template <class Epi>
; DI void gemm_phase(LAS unsigned char* lds, const Sched& S, const Epi& E, const int K) {
;     ...
;             const bool last = (t == nt - 2);
;             const unsigned k1 = (unsigned)(t + 1) * kstepA;
;             const unsigned k2 = last ? 0u : (unsigned)(t + 2) * kstepA, k3 = k2 + kstepA;
;             const unsigned kb2 = last ? 0u : (unsigned)(t + 2) * kstepB, kb3 = kb2 + kstepB;
;             const unsigned x0 = last ? n0 : cur.a0, x1 = last ? n1 : cur.a1, x2 = last ? n2 : cur.a2, x3 = last ? n3 : cur.a3;
;             const unsigned xb = last ? nB : cur.b;
;     ...
;             G_LDB(B0, 0, 0); G_LDB(B1, 0, 1); G_SCHED; G_LDA(At, 0, 0); G_STAGE_A(G_SA(1, 1), cur.a2, cur.a3, k1);
;             G_WAIT_V(8); G_WAIT_L(0); G_BAR; G_MMA(0, 0, At, B0); G_MMA(0, 1, At, B1); G_BAR; G_SCHED;
;             G_LDA(At, 0, 1); G_STAGE_B(G_SB(0, 0), xb, kb2); G_STAGE_B(G_SB(0, 1), xb + hstepB, kb2); G_STAGE_A(G_SA(0, 0), x0, x1, k2);
;             G_WAIT_V(8); G_WAIT_L(0); G_BAR; G_MMA(1, 0, At, B0); G_MMA(1, 1, At, B1); G_BAR; G_SCHED;
.LBB0_511:
	s_add_i32 s27, s26, 0x100
	s_cmp_eq_u32 s10, 28
	s_cselect_b32 s48, 0, s27
	s_cselect_b32 s72, s20, s45
	s_cselect_b32 s73, s24, s41
	s_cselect_b32 s75, s21, s44
	s_cselect_b32 s78, s11, s46
	s_cselect_b32 s37, s25, s40
	s_add_i32 s79, 0, 0x10000
	v_add_u32_e32 v130, s79, v148
	s_add_i32 s80, 0, 0x14000
	ds_read_b128 v[138:141], v130
	ds_read_b128 v[154:157], v130 offset:1024
	ds_read_b128 v[158:161], v130 offset:2048
	ds_read_b128 v[162:165], v130 offset:3072
	v_add_u32_e32 v130, s80, v148
	ds_read_b128 v[166:169], v130
	ds_read_b128 v[170:173], v130 offset:1024
	ds_read_b128 v[174:177], v130 offset:2048
	ds_read_b128 v[178:181], v130 offset:3072
	s_or_b32 s36, s48, 0x80
	v_add_u32_e32 v130, s26, v129
	s_add_i32 m0, s50, 0xc000
	ds_read_b128 v[194:197], v152
	ds_read_b128 v[198:201], v152 offset:1024
	ds_read_b128 v[202:205], v152 offset:2048
	ds_read_b128 v[206:209], v152 offset:3072
	ds_read_b128 v[210:213], v152 offset:4096
	ds_read_b128 v[214:217], v152 offset:5120
	ds_read_b128 v[218:221], v152 offset:6144
	ds_read_b128 v[222:225], v152 offset:7168
	global_load_lds_dwordx4 v130, s[82:83]
	v_add_u32_e32 v130, s26, v128
	s_add_i32 m0, s50, 0xe000
	s_nop 0
	global_load_lds_dwordx4 v130, s[82:83]
	s_waitcnt vmcnt(8)
	s_waitcnt lgkmcnt(0)
	s_barrier
	s_setprio 0
	s_waitcnt lgkmcnt(0)
	v_mfma_f32_16x16x32_bf16 v[124:127], v[138:141], v[194:197], v[124:127]
	v_mfma_f32_16x16x32_bf16 v[120:123], v[158:161], v[194:197], v[120:123]
	v_mfma_f32_16x16x32_bf16 v[116:119], v[138:141], v[202:205], v[116:119]
	v_mfma_f32_16x16x32_bf16 v[112:115], v[158:161], v[202:205], v[112:115]
	v_mfma_f32_16x16x32_bf16 v[108:111], v[138:141], v[210:213], v[108:111]
	v_mfma_f32_16x16x32_bf16 v[104:107], v[158:161], v[210:213], v[104:107]
	v_mfma_f32_16x16x32_bf16 v[100:103], v[138:141], v[218:221], v[100:103]
	v_mfma_f32_16x16x32_bf16 v[96:99], v[158:161], v[218:221], v[96:99]
	v_mfma_f32_16x16x32_bf16 v[124:127], v[154:157], v[198:201], v[124:127]
	v_mfma_f32_16x16x32_bf16 v[120:123], v[162:165], v[198:201], v[120:123]
	v_mfma_f32_16x16x32_bf16 v[116:119], v[154:157], v[206:209], v[116:119]
	v_mfma_f32_16x16x32_bf16 v[112:115], v[162:165], v[206:209], v[112:115]
	v_mfma_f32_16x16x32_bf16 v[108:111], v[154:157], v[214:217], v[108:111]
	v_mfma_f32_16x16x32_bf16 v[104:107], v[162:165], v[214:217], v[104:107]
	v_mfma_f32_16x16x32_bf16 v[100:103], v[154:157], v[222:225], v[100:103]
	v_mfma_f32_16x16x32_bf16 v[96:99], v[162:165], v[222:225], v[96:99]
	v_mfma_f32_16x16x32_bf16 v[92:95], v[166:169], v[194:197], v[92:95]
	v_mfma_f32_16x16x32_bf16 v[88:91], v[174:177], v[194:197], v[88:91]
	v_mfma_f32_16x16x32_bf16 v[84:87], v[166:169], v[202:205], v[84:87]
	v_mfma_f32_16x16x32_bf16 v[80:83], v[174:177], v[202:205], v[80:83]
	v_mfma_f32_16x16x32_bf16 v[76:79], v[166:169], v[210:213], v[76:79]
	v_mfma_f32_16x16x32_bf16 v[72:75], v[174:177], v[210:213], v[72:75]
	v_mfma_f32_16x16x32_bf16 v[68:71], v[166:169], v[218:221], v[68:71]
	v_mfma_f32_16x16x32_bf16 v[64:67], v[174:177], v[218:221], v[64:67]
	v_mfma_f32_16x16x32_bf16 v[92:95], v[170:173], v[198:201], v[92:95]
	v_mfma_f32_16x16x32_bf16 v[88:91], v[178:181], v[198:201], v[88:91]
	v_mfma_f32_16x16x32_bf16 v[84:87], v[170:173], v[206:209], v[84:87]
	v_mfma_f32_16x16x32_bf16 v[80:83], v[178:181], v[206:209], v[80:83]
	v_mfma_f32_16x16x32_bf16 v[76:79], v[170:173], v[214:217], v[76:79]
	v_mfma_f32_16x16x32_bf16 v[72:75], v[178:181], v[214:217], v[72:75]
	v_mfma_f32_16x16x32_bf16 v[68:71], v[170:173], v[222:225], v[68:71]
	v_mfma_f32_16x16x32_bf16 v[64:67], v[178:181], v[222:225], v[64:67]
	s_setprio 1
	s_barrier
	s_add_i32 s26, s48, s37
	s_add_i32 s79, s79, s47
	v_add_u32_e32 v130, s26, v144
	s_mov_b32 m0, s79
	ds_read_b128 v[194:197], v152 offset:16384
	ds_read_b128 v[198:201], v152 offset:17408
	ds_read_b128 v[202:205], v152 offset:18432
	ds_read_b128 v[206:209], v152 offset:19456
	ds_read_b128 v[210:213], v152 offset:20480
	ds_read_b128 v[214:217], v152 offset:21504
	ds_read_b128 v[218:221], v152 offset:22528
	ds_read_b128 v[222:225], v152 offset:23552
	global_load_lds_dwordx4 v130, s[82:83]
	v_add_u32_e32 v130, s26, v146
	s_add_i32 s26, s37, 0x80000
	s_add_i32 m0, s79, 0x2000
	s_add_i32 s79, s26, s48
	s_add_i32 s80, s80, s47
	global_load_lds_dwordx4 v130, s[82:83]
	v_add_u32_e32 v130, s79, v144
	s_mov_b32 m0, s80
	s_nop 0
	global_load_lds_dwordx4 v130, s[82:83]
	v_add_u32_e32 v130, s79, v146
	s_add_i32 m0, s80, 0x2000
	s_nop 0
	global_load_lds_dwordx4 v130, s[82:83]
	v_add_u32_e32 v130, s78, v133
	v_add_u32_e32 v131, s48, v130
	s_mov_b32 m0, s50
	s_nop 0
	global_load_lds_dwordx4 v131, s[82:83]
	v_add_u32_e32 v131, s72, v145
	v_add_u32_e32 v142, s48, v131
	s_mov_b32 m0, s54
	s_nop 0
	global_load_lds_dwordx4 v142, s[82:83]
	s_waitcnt vmcnt(8)
	s_waitcnt lgkmcnt(0)
	s_barrier
; #define G_STAGE_A(bufoff, p0, p1, koff) do { \
;         __builtin_amdgcn_global_load_lds((const unsigned*)(gbase + (size_t)(unsigned)((p0) + (koff) + voffA[0])), (LAS unsigned*)(lds + (bufoff) + ldsw), 16, 0, 0); \
;         __builtin_amdgcn_global_load_lds((const unsigned*)(gbase + (size_t)(unsigned)((p1) + (koff) + voffA[1])), (LAS unsigned*)(lds + (bufoff) + ldsw + 8192), 16, 0, 0); } while (0)
; #define G_LDA(dst, b, h) do { _Pragma("unroll") for (int m = 0; m < 4; ++m) _Pragma("unroll") for (int k = 0; k < 2; ++k) dst[m][k] = *(const LAS bf16x8*)(lds + G_SA(b, h) + aoff + m * 2048 + k * 1024); } while (0)
; #define G_LDB(dst, b, h) do { _Pragma("unroll") for (int n = 0; n < 2; ++n) _Pragma("unroll") for (int k = 0; k < 2; ++k) dst[n][k] = *(const LAS bf16x8*)(lds + G_SB(b, h) + boff + n * 2048 + k * 1024); } while (0)
; #define G_MMA(ai, bj, At, Bt) do { __builtin_amdgcn_s_setprio(1); _Pragma("unroll") for (int m = 0; m < 4; ++m) _Pragma("unroll") for (int n = 0; n < 2; ++n) _Pragma("unroll") for (int k = 0; k < 2; ++k) \
;         acc[ai][bj][m][n] = __builtin_amdgcn_mfma_f32_16x16x32_bf16(Bt[n][k], At[m][k], acc[ai][bj][m][n], 0, 0, 0); __builtin_amdgcn_s_setprio(0); } while (0)
; #define G_WAIT_V(n) asm volatile("s_waitcnt vmcnt(" #n ")" ::: "memory")
; #define G_WAIT_L(n) asm volatile("s_waitcnt lgkmcnt(" #n ")" ::: "memory")
; #define G_BAR __builtin_amdgcn_s_barrier()
; #define G_SCHED __builtin_amdgcn_sched_barrier(0)
; template <class Epi>
; DI void gemm_phase(LAS unsigned char* lds, const Sched& S, const Epi& E, const int K) {
;     ...
;             G_WAIT_V(8); G_WAIT_L(0); G_BAR; G_MMA(1, 0, At, B0); G_MMA(1, 1, At, B1); G_BAR; G_SCHED;
;             G_LDB(B0, 1, 0); G_LDB(B1, 1, 1); G_SCHED; G_LDA(At, 1, 0); G_STAGE_A(G_SA(0, 1), x2, x3, k2);
;             G_WAIT_V(8); G_WAIT_L(0); G_BAR; G_MMA(0, 0, At, B0); G_MMA(0, 1, At, B1); G_BAR; G_SCHED;
	s_setprio 0
	s_waitcnt lgkmcnt(0)
	v_mfma_f32_16x16x32_bf16 v[60:63], v[138:141], v[194:197], v[60:63]
	v_mfma_f32_16x16x32_bf16 v[56:59], v[158:161], v[194:197], v[56:59]
	v_mfma_f32_16x16x32_bf16 v[52:55], v[138:141], v[202:205], v[52:55]
	v_mfma_f32_16x16x32_bf16 v[48:51], v[158:161], v[202:205], v[48:51]
	v_mfma_f32_16x16x32_bf16 v[44:47], v[138:141], v[210:213], v[44:47]
	v_mfma_f32_16x16x32_bf16 v[40:43], v[158:161], v[210:213], v[40:43]
	v_mfma_f32_16x16x32_bf16 v[36:39], v[138:141], v[218:221], v[36:39]
	v_mfma_f32_16x16x32_bf16 v[32:35], v[158:161], v[218:221], v[32:35]
	v_mfma_f32_16x16x32_bf16 v[60:63], v[154:157], v[198:201], v[60:63]
	v_mfma_f32_16x16x32_bf16 v[56:59], v[162:165], v[198:201], v[56:59]
	v_mfma_f32_16x16x32_bf16 v[52:55], v[154:157], v[206:209], v[52:55]
	v_mfma_f32_16x16x32_bf16 v[48:51], v[162:165], v[206:209], v[48:51]
	v_mfma_f32_16x16x32_bf16 v[44:47], v[154:157], v[214:217], v[44:47]
	v_mfma_f32_16x16x32_bf16 v[40:43], v[162:165], v[214:217], v[40:43]
	v_mfma_f32_16x16x32_bf16 v[36:39], v[154:157], v[222:225], v[36:39]
	v_mfma_f32_16x16x32_bf16 v[32:35], v[162:165], v[222:225], v[32:35]
	v_mfma_f32_16x16x32_bf16 v[28:31], v[166:169], v[194:197], v[28:31]
	v_mfma_f32_16x16x32_bf16 v[24:27], v[174:177], v[194:197], v[24:27]
	v_mfma_f32_16x16x32_bf16 v[20:23], v[166:169], v[202:205], v[20:23]
	v_mfma_f32_16x16x32_bf16 v[16:19], v[174:177], v[202:205], v[16:19]
	v_mfma_f32_16x16x32_bf16 v[12:15], v[166:169], v[210:213], v[12:15]
	v_mfma_f32_16x16x32_bf16 v[8:11], v[174:177], v[210:213], v[8:11]
	v_mfma_f32_16x16x32_bf16 v[4:7], v[166:169], v[218:221], v[4:7]
	v_mfma_f32_16x16x32_bf16 v[0:3], v[174:177], v[218:221], v[0:3]
	v_mfma_f32_16x16x32_bf16 v[28:31], v[170:173], v[198:201], v[28:31]
	v_mfma_f32_16x16x32_bf16 v[24:27], v[178:181], v[198:201], v[24:27]
	v_mfma_f32_16x16x32_bf16 v[20:23], v[170:173], v[206:209], v[20:23]
	v_mfma_f32_16x16x32_bf16 v[16:19], v[178:181], v[206:209], v[16:19]
	v_mfma_f32_16x16x32_bf16 v[12:15], v[170:173], v[214:217], v[12:15]
	v_mfma_f32_16x16x32_bf16 v[8:11], v[178:181], v[214:217], v[8:11]
	v_mfma_f32_16x16x32_bf16 v[4:7], v[170:173], v[222:225], v[4:7]
	v_mfma_f32_16x16x32_bf16 v[0:3], v[178:181], v[222:225], v[0:3]
	s_setprio 1
	s_barrier
	s_add_i32 s72, 0, 0x18000
	v_add_u32_e32 v142, s72, v148
	s_add_i32 s78, 0, 0x1c000
	ds_read_b128 v[138:141], v142
	ds_read_b128 v[154:157], v142 offset:1024
	ds_read_b128 v[158:161], v142 offset:2048
	ds_read_b128 v[162:165], v142 offset:3072
	v_add_u32_e32 v142, s78, v148
	ds_read_b128 v[166:169], v142
	ds_read_b128 v[170:173], v142 offset:1024
	ds_read_b128 v[174:177], v142 offset:2048
	ds_read_b128 v[178:181], v142 offset:3072
	s_add_i32 s75, s75, s48
	s_mov_b32 m0, s55
	v_add_u32_e32 v142, s75, v133
	s_add_i32 s73, s73, s48
	ds_read_b128 v[194:197], v152 offset:32768
	ds_read_b128 v[198:201], v152 offset:33792
	ds_read_b128 v[202:205], v152 offset:34816
	ds_read_b128 v[206:209], v152 offset:35840
	ds_read_b128 v[210:213], v152 offset:36864
	ds_read_b128 v[214:217], v152 offset:37888
	ds_read_b128 v[218:221], v152 offset:38912
	ds_read_b128 v[222:225], v152 offset:39936
	global_load_lds_dwordx4 v142, s[82:83]
	v_add_u32_e32 v142, s73, v145
	s_mov_b32 m0, s56
	s_nop 0
	global_load_lds_dwordx4 v142, s[82:83]
	s_waitcnt vmcnt(8)
	s_waitcnt lgkmcnt(0)
	s_barrier
	s_setprio 0
	s_waitcnt lgkmcnt(0)
	v_mfma_f32_16x16x32_bf16 v[124:127], v[138:141], v[194:197], v[124:127]
	v_mfma_f32_16x16x32_bf16 v[120:123], v[158:161], v[194:197], v[120:123]
	v_mfma_f32_16x16x32_bf16 v[116:119], v[138:141], v[202:205], v[116:119]
	v_mfma_f32_16x16x32_bf16 v[112:115], v[158:161], v[202:205], v[112:115]
	v_mfma_f32_16x16x32_bf16 v[108:111], v[138:141], v[210:213], v[108:111]
	v_mfma_f32_16x16x32_bf16 v[104:107], v[158:161], v[210:213], v[104:107]
	v_mfma_f32_16x16x32_bf16 v[100:103], v[138:141], v[218:221], v[100:103]
	v_mfma_f32_16x16x32_bf16 v[96:99], v[158:161], v[218:221], v[96:99]
	v_mfma_f32_16x16x32_bf16 v[124:127], v[154:157], v[198:201], v[124:127]
	v_mfma_f32_16x16x32_bf16 v[120:123], v[162:165], v[198:201], v[120:123]
	v_mfma_f32_16x16x32_bf16 v[116:119], v[154:157], v[206:209], v[116:119]
	v_mfma_f32_16x16x32_bf16 v[112:115], v[162:165], v[206:209], v[112:115]
	v_mfma_f32_16x16x32_bf16 v[108:111], v[154:157], v[214:217], v[108:111]
	v_mfma_f32_16x16x32_bf16 v[104:107], v[162:165], v[214:217], v[104:107]
	v_mfma_f32_16x16x32_bf16 v[100:103], v[154:157], v[222:225], v[100:103]
	v_mfma_f32_16x16x32_bf16 v[96:99], v[162:165], v[222:225], v[96:99]
	v_mfma_f32_16x16x32_bf16 v[92:95], v[166:169], v[194:197], v[92:95]
	v_mfma_f32_16x16x32_bf16 v[88:91], v[174:177], v[194:197], v[88:91]
	v_mfma_f32_16x16x32_bf16 v[84:87], v[166:169], v[202:205], v[84:87]
	v_mfma_f32_16x16x32_bf16 v[80:83], v[174:177], v[202:205], v[80:83]
	v_mfma_f32_16x16x32_bf16 v[76:79], v[166:169], v[210:213], v[76:79]
	v_mfma_f32_16x16x32_bf16 v[72:75], v[174:177], v[210:213], v[72:75]
	v_mfma_f32_16x16x32_bf16 v[68:71], v[166:169], v[218:221], v[68:71]
	v_mfma_f32_16x16x32_bf16 v[64:67], v[174:177], v[218:221], v[64:67]
	v_mfma_f32_16x16x32_bf16 v[92:95], v[170:173], v[198:201], v[92:95]
	v_mfma_f32_16x16x32_bf16 v[88:91], v[178:181], v[198:201], v[88:91]
	v_mfma_f32_16x16x32_bf16 v[84:87], v[170:173], v[206:209], v[84:87]
	v_mfma_f32_16x16x32_bf16 v[80:83], v[178:181], v[206:209], v[80:83]
	v_mfma_f32_16x16x32_bf16 v[76:79], v[170:173], v[214:217], v[76:79]
	v_mfma_f32_16x16x32_bf16 v[72:75], v[178:181], v[214:217], v[72:75]
	v_mfma_f32_16x16x32_bf16 v[68:71], v[170:173], v[222:225], v[68:71]
	v_mfma_f32_16x16x32_bf16 v[64:67], v[178:181], v[222:225], v[64:67]
	s_setprio 1
	s_barrier
; #define G_STAGE_A(bufoff, p0, p1, koff) do { \
;         __builtin_amdgcn_global_load_lds((const unsigned*)(gbase + (size_t)(unsigned)((p0) + (koff) + voffA[0])), (LAS unsigned*)(lds + (bufoff) + ldsw), 16, 0, 0); \
;         __builtin_amdgcn_global_load_lds((const unsigned*)(gbase + (size_t)(unsigned)((p1) + (koff) + voffA[1])), (LAS unsigned*)(lds + (bufoff) + ldsw + 8192), 16, 0, 0); } while (0)
; #define G_STAGE_B(bufoff, p, koff) do { \
;         __builtin_amdgcn_global_load_lds((const unsigned*)(gbase + (size_t)(unsigned)((p) + (koff) + voffB[0])), (LAS unsigned*)(lds + (bufoff) + ldsw), 16, 0, 0); \
;         __builtin_amdgcn_global_load_lds((const unsigned*)(gbase + (size_t)(unsigned)((p) + (koff) + voffB[1])), (LAS unsigned*)(lds + (bufoff) + ldsw + 8192), 16, 0, 0); } while (0)
; #define G_LDA(dst, b, h) do { _Pragma("unroll") for (int m = 0; m < 4; ++m) _Pragma("unroll") for (int k = 0; k < 2; ++k) dst[m][k] = *(const LAS bf16x8*)(lds + G_SA(b, h) + aoff + m * 2048 + k * 1024); } while (0)
; #define G_MMA(ai, bj, At, Bt) do { __builtin_amdgcn_s_setprio(1); _Pragma("unroll") for (int m = 0; m < 4; ++m) _Pragma("unroll") for (int n = 0; n < 2; ++n) _Pragma("unroll") for (int k = 0; k < 2; ++k) \
;         acc[ai][bj][m][n] = __builtin_amdgcn_mfma_f32_16x16x32_bf16(Bt[n][k], At[m][k], acc[ai][bj][m][n], 0, 0, 0); __builtin_amdgcn_s_setprio(0); } while (0)
; #define G_WAIT_V(n) asm volatile("s_waitcnt vmcnt(" #n ")" ::: "memory")
; #define G_WAIT_L(n) asm volatile("s_waitcnt lgkmcnt(" #n ")" ::: "memory")
; #define G_BAR __builtin_amdgcn_s_barrier()
; #define G_SCHED __builtin_amdgcn_sched_barrier(0)
; template <class Epi>
; DI void gemm_phase(LAS unsigned char* lds, const Sched& S, const Epi& E, const int K) {
;     ...
;             G_WAIT_V(8); G_WAIT_L(0); G_BAR; G_MMA(0, 0, At, B0); G_MMA(0, 1, At, B1); G_BAR; G_SCHED;
;             G_LDA(At, 1, 1); G_STAGE_B(G_SB(1, 0), xb, kb3); G_STAGE_B(G_SB(1, 1), xb + hstepB, kb3); G_STAGE_A(G_SA(1, 0), x0, x1, k3);
;             G_WAIT_V(8); G_WAIT_L(0); G_BAR; G_MMA(1, 0, At, B0); G_MMA(1, 1, At, B1); G_BAR; G_SCHED;
;     ...
;         }
;     ...
;         if (wr == 0) G_BAR;
	s_add_i32 s37, s36, s37
	s_add_i32 s48, s72, s47
	v_add_u32_e32 v142, s37, v144
	s_mov_b32 m0, s48
	ds_read_b128 v[194:197], v152 offset:49152
	ds_read_b128 v[198:201], v152 offset:50176
	ds_read_b128 v[202:205], v152 offset:51200
	ds_read_b128 v[206:209], v152 offset:52224
	ds_read_b128 v[210:213], v152 offset:53248
	ds_read_b128 v[214:217], v152 offset:54272
	ds_read_b128 v[218:221], v152 offset:55296
	ds_read_b128 v[222:225], v152 offset:56320
	global_load_lds_dwordx4 v142, s[82:83]
	v_add_u32_e32 v142, s37, v146
	s_add_i32 m0, s48, 0x2000
	s_add_i32 s26, s36, s26
	s_add_i32 s37, s78, s47
	global_load_lds_dwordx4 v142, s[82:83]
	v_add_u32_e32 v142, s26, v144
	s_mov_b32 m0, s37
	v_add_u32_e32 v130, s36, v130
	global_load_lds_dwordx4 v142, s[82:83]
	v_add_u32_e32 v142, s26, v146
	s_add_i32 m0, s37, 0x2000
	s_nop 0
	global_load_lds_dwordx4 v142, s[82:83]
	s_mov_b32 m0, s57
	s_nop 0
	global_load_lds_dwordx4 v130, s[82:83]
	v_add_u32_e32 v130, s36, v131
	s_mov_b32 m0, s58
	s_nop 0
	global_load_lds_dwordx4 v130, s[82:83]
	s_waitcnt vmcnt(8)
	s_waitcnt lgkmcnt(0)
	s_barrier
	s_setprio 0
	s_waitcnt lgkmcnt(0)
	v_mfma_f32_16x16x32_bf16 v[60:63], v[138:141], v[194:197], v[60:63]
	v_mfma_f32_16x16x32_bf16 v[56:59], v[158:161], v[194:197], v[56:59]
	v_mfma_f32_16x16x32_bf16 v[52:55], v[138:141], v[202:205], v[52:55]
	v_mfma_f32_16x16x32_bf16 v[48:51], v[158:161], v[202:205], v[48:51]
	v_mfma_f32_16x16x32_bf16 v[44:47], v[138:141], v[210:213], v[44:47]
	v_mfma_f32_16x16x32_bf16 v[40:43], v[158:161], v[210:213], v[40:43]
	v_mfma_f32_16x16x32_bf16 v[36:39], v[138:141], v[218:221], v[36:39]
	v_mfma_f32_16x16x32_bf16 v[32:35], v[158:161], v[218:221], v[32:35]
	v_mfma_f32_16x16x32_bf16 v[60:63], v[154:157], v[198:201], v[60:63]
	v_mfma_f32_16x16x32_bf16 v[56:59], v[162:165], v[198:201], v[56:59]
	v_mfma_f32_16x16x32_bf16 v[52:55], v[154:157], v[206:209], v[52:55]
	v_mfma_f32_16x16x32_bf16 v[48:51], v[162:165], v[206:209], v[48:51]
	v_mfma_f32_16x16x32_bf16 v[44:47], v[154:157], v[214:217], v[44:47]
	v_mfma_f32_16x16x32_bf16 v[40:43], v[162:165], v[214:217], v[40:43]
	v_mfma_f32_16x16x32_bf16 v[36:39], v[154:157], v[222:225], v[36:39]
	v_mfma_f32_16x16x32_bf16 v[32:35], v[162:165], v[222:225], v[32:35]
	v_mfma_f32_16x16x32_bf16 v[28:31], v[166:169], v[194:197], v[28:31]
	v_mfma_f32_16x16x32_bf16 v[24:27], v[174:177], v[194:197], v[24:27]
	v_mfma_f32_16x16x32_bf16 v[20:23], v[166:169], v[202:205], v[20:23]
	v_mfma_f32_16x16x32_bf16 v[16:19], v[174:177], v[202:205], v[16:19]
	v_mfma_f32_16x16x32_bf16 v[12:15], v[166:169], v[210:213], v[12:15]
	v_mfma_f32_16x16x32_bf16 v[8:11], v[174:177], v[210:213], v[8:11]
	v_mfma_f32_16x16x32_bf16 v[4:7], v[166:169], v[218:221], v[4:7]
	v_mfma_f32_16x16x32_bf16 v[0:3], v[174:177], v[218:221], v[0:3]
	v_mfma_f32_16x16x32_bf16 v[28:31], v[170:173], v[198:201], v[28:31]
	v_mfma_f32_16x16x32_bf16 v[24:27], v[178:181], v[198:201], v[24:27]
	v_mfma_f32_16x16x32_bf16 v[20:23], v[170:173], v[206:209], v[20:23]
	v_mfma_f32_16x16x32_bf16 v[16:19], v[178:181], v[206:209], v[16:19]
	v_mfma_f32_16x16x32_bf16 v[12:15], v[170:173], v[214:217], v[12:15]
	v_mfma_f32_16x16x32_bf16 v[8:11], v[178:181], v[214:217], v[8:11]
	v_mfma_f32_16x16x32_bf16 v[4:7], v[170:173], v[222:225], v[4:7]
	v_mfma_f32_16x16x32_bf16 v[0:3], v[178:181], v[222:225], v[0:3]
	s_setprio 1
	s_barrier
	s_add_i32 s10, s10, 2
	s_cmp_gt_u32 s10, 29
	s_mov_b32 s26, s27
	s_cbranch_scc0 .LBB0_511
	s_and_b64 vcc, exec, s[14:15]
	s_cbranch_vccz .LBB0_514
	s_barrier
